# in-proj GEMM K-loop hand-scheduled (early prefetch issue, dedicated fragment regs); NSA per-element T5-bias lookups made branch-free and batched 8-wide
# speedup vs baseline: 1.0385x; 1.0163x over previous
; DI int otid() { int z; asm volatile("s_mov_b32 %0, 0" : "=s"(z)); return (int)threadIdx.x + z; }
; #define GLOAD2(K0) { const int tl = otid(); LDA2(0, K0) LDA2(1, K0) LDA2(2, K0) LDA2(3, K0) LDB2(0, K0) LDB2(1, K0) LDB2(2, K0) LDB2(3, K0) LDB2(4, K0) LDB2(5, K0) LDB2(6, K0) LDB2(7, K0) }
; template <class AF, class Epi>
; DI void gemm_tile2(AF af, const bf16* __restrict__ Bt, int ldb, int K, char* smem, int& n0ref, int nhalf, Epi epi) {
;   const int tid = otid(), lane = tid & 63, w = tid >> 6, r = lane & 31, h = lane >> 5;
;   const int wm = w >> 1, wn = w & 1;
;   bf16* As = (bf16*)smem;
;   bf16* Bs = As + 128 * 72;
;   f32x16 acc[2][4];
; #pragma unroll
;   for (int a = 0; a < 2; ++a)
; #pragma unroll
;     for (int b = 0; b < 4; ++b)
; #pragma unroll
;       for (int i = 0; i < 16; ++i) acc[a][b][i] = 0.f;
;   uint4 pa_0, pa_1, pa_2, pa_3, pb_0, pb_1, pb_2, pb_3, pb_4, pb_5, pb_6, pb_7;
;     ...
;   const int nk = K >> 6;
;   GLOAD2(0);
;   const bf16* a_ = As + (wm * 64 + r) * 72 + h * 8;
;   const bf16* b_ = Bs + (wn * 128 + r) * 72 + h * 8;
; __global__ void __launch_bounds__(256, LB2) mega(Params p, int ph_lo, int ph_hi) {
;     ...
;       for (int u = own ? (bid >> 3) : vb; u < u_end; u += own ? nloc : nb) {
;         const int t = own ? (u < per_g ? (bid & 7) * per_g + u : n_in + (bid & 7) * 2 + (u - per_g)) : u;
;         if (t < n_in) {
;           int tm, tn;
;           tile_map(t, ntn, tm, tn);
;           const int m0 = tm * 128;
;           int n0 = tn * 256;
;           const int nhalf = (n0 + 128 < NP) ? 2 : 1;
;           ALin af{XN + (size_t)m0 * LDX, LDX};
;           if (even) {
;             gemm_tile2(af, Win + (size_t)n0 * LDX, LDX, DM, smem, n0, nhalf, [&](const float* Cs) {
.LBB0_137:
	s_abs_i32 s1, s10
	s_mul_hi_u32 s11, s1, s12
	s_mul_i32 s18, s11, s63
	s_sub_i32 s1, s1, s18
	s_ashr_i32 s0, s10, 31
	s_add_i32 s18, s11, 1
	s_sub_i32 s19, s1, s63
	s_cmp_ge_u32 s1, s63
	s_cselect_b32 s11, s18, s11
	s_cselect_b32 s1, s19, s1
	s_add_i32 s18, s11, 1
	s_cmp_ge_u32 s1, s63
	s_cselect_b32 s1, s18, s11
	s_xor_b32 s1, s1, s0
	s_sub_i32 s0, s1, s0
	s_mul_i32 s1, s0, s63
	s_sub_i32 s11, s10, s1
	s_lshl_b32 s1, s10, 7
	s_lshl_b32 s64, s11, 5
	s_lshl_b32 s0, s0, 10
	s_and_b32 s1, s1, 0x380
	s_and_b32 s48, s64, 0xffffff00
	s_or_b32 s42, s0, s1
	s_or_b32 s84, s48, 0x80
	s_cmp_lt_i32 s84, s62
	s_cselect_b64 s[50:51], -1, 0
	s_ashr_i32 s43, s42, 31
	s_mul_i32 s0, s42, 0x1080
	s_mul_hi_i32 s1, s42, 0x1080
	s_add_u32 s0, s4, s0
	s_addc_u32 s1, s5, s1
	s_ashr_i32 s49, s48, 31
	s_mul_i32 s10, s48, 0x1080
	s_mul_hi_i32 s85, s48, 0x1080
	s_add_u32 s26, s30, s10
	s_addc_u32 s27, s31, s85
	s_mov_b64 s[18:19], -1
	s_and_b64 vcc, exec, s[20:21]
	s_cbranch_vccz .LBB0_145
	s_mov_b32 s18, 0
	v_mov_b64_e32 v[2:3], s[0:1]
	v_add_u32_e32 v8, s18, v189
	s_mov_b32 s18, 0
	v_bfe_u32 v242, v8, 5, 1
	v_add_u32_e32 v9, s18, v189
	v_add_u32_e32 v6, 0x100, v9
	v_ashrrev_i32_e32 v10, 3, v9
	v_lshlrev_b32_e32 v0, 4, v9
	v_ashrrev_i32_e32 v11, 3, v6
	v_mad_i64_i32 v[4:5], s[18:19], v10, s75, v[2:3]
	v_and_b32_e32 v0, 0x70, v0
	v_mad_i64_i32 v[6:7], s[18:19], v11, s75, v[2:3]
	v_lshl_add_u64 v[4:5], v[4:5], 0, v[0:1]
	v_lshl_add_u64 v[6:7], v[6:7], 0, v[0:1]
	s_waitcnt lgkmcnt(0)
	global_load_dwordx4 v[130:133], v[4:5], off
	global_load_dwordx4 v[134:137], v[6:7], off
	v_add_u32_e32 v4, 0x200, v9
	v_add_u32_e32 v6, 0x300, v9
	v_ashrrev_i32_e32 v12, 3, v4
	v_ashrrev_i32_e32 v13, 3, v6
	v_mad_i64_i32 v[4:5], s[18:19], v12, s75, v[2:3]
	v_mad_i64_i32 v[2:3], s[18:19], v13, s75, v[2:3]
	v_lshl_add_u64 v[4:5], v[4:5], 0, v[0:1]
	v_lshl_add_u64 v[2:3], v[2:3], 0, v[0:1]
	global_load_dwordx4 v[138:141], v[4:5], off
	global_load_dwordx4 v[142:145], v[2:3], off
	v_mov_b64_e32 v[2:3], s[26:27]
	v_mad_i64_i32 v[4:5], s[18:19], v10, s75, v[2:3]
	v_lshl_add_u64 v[4:5], v[4:5], 0, v[0:1]
	v_mad_i64_i32 v[6:7], s[18:19], v11, s75, v[2:3]
	v_lshl_add_u64 v[6:7], v[6:7], 0, v[0:1]
	global_load_dwordx4 v[146:149], v[4:5], off
	global_load_dwordx4 v[150:153], v[6:7], off
	v_mad_i64_i32 v[4:5], s[18:19], v12, s75, v[2:3]
	v_lshl_add_u64 v[4:5], v[4:5], 0, v[0:1]
	v_mad_i64_i32 v[6:7], s[18:19], v13, s75, v[2:3]
	v_lshl_add_u64 v[6:7], v[6:7], 0, v[0:1]
	global_load_dwordx4 v[154:157], v[4:5], off
	global_load_dwordx4 v[158:161], v[6:7], off
	v_add_u32_e32 v4, 0x400, v9
	v_ashrrev_i32_e32 v4, 3, v4
	v_add_u32_e32 v6, 0x500, v9
	v_mad_i64_i32 v[4:5], s[18:19], v4, s75, v[2:3]
	v_ashrrev_i32_e32 v6, 3, v6
	v_lshl_add_u64 v[4:5], v[4:5], 0, v[0:1]
	v_mad_i64_i32 v[6:7], s[18:19], v6, s75, v[2:3]
	v_lshl_add_u64 v[6:7], v[6:7], 0, v[0:1]
	global_load_dwordx4 v[162:165], v[4:5], off
	global_load_dwordx4 v[166:169], v[6:7], off
	v_add_u32_e32 v4, 0x600, v9
	v_ashrrev_i32_e32 v4, 3, v4
	v_add_u32_e32 v6, 0x700, v9
	v_mad_i64_i32 v[4:5], s[18:19], v4, s75, v[2:3]
	v_ashrrev_i32_e32 v6, 3, v6
	v_lshl_add_u64 v[4:5], v[4:5], 0, v[0:1]
	v_mad_i64_i32 v[2:3], s[18:19], v6, s75, v[2:3]
	v_lshl_add_u64 v[2:3], v[2:3], 0, v[0:1]
	global_load_dwordx4 v[170:173], v[4:5], off
	global_load_dwordx4 v[174:177], v[2:3], off
	v_ashrrev_i32_e32 v0, 1, v8
	v_and_b32_e32 v243, 31, v8
	v_and_b32_e32 v244, 0xffffffc0, v0
	v_bfe_u32 v241, v8, 6, 1
	v_or_b32_e32 v2, v244, v243
	v_lshlrev_b32_e32 v0, 4, v242
	s_movk_i32 s36, 0x90
	v_mad_u64_u32 v[182:183], s[18:19], v2, s36, v[0:1]
	v_lshl_or_b32 v2, v241, 7, v243
	v_mad_u32_u24 v183, v2, s36, v0
	v_lshlrev_b32_e32 v0, 4, v8
	v_lshrrev_b32_e32 v2, 3, v8
	v_and_b32_e32 v0, 0x70, v0
	v_mad_u64_u32 v[184:185], s[18:19], v2, s36, v[0:1]
	v_add_u32_e32 v2, 0x100, v8
	v_lshrrev_b32_e32 v2, 3, v2
	v_mad_u64_u32 v[194:195], s[18:19], v2, s36, v[0:1]
	v_add_u32_e32 v2, 0x200, v8
	v_lshrrev_b32_e32 v2, 3, v2
	v_mad_u64_u32 v[196:197], s[18:19], v2, s36, v[0:1]
	v_add_u32_e32 v2, 0x300, v8
	v_lshrrev_b32_e32 v2, 3, v2
	v_mad_u64_u32 v[198:199], s[18:19], v2, s36, v[0:1]
	v_add_u32_e32 v2, 0x400, v8
	v_lshrrev_b32_e32 v2, 3, v2
	v_mad_u64_u32 v[200:201], s[18:19], v2, s36, v[0:1]
	v_add_u32_e32 v2, 0x500, v8
	v_lshrrev_b32_e32 v2, 3, v2
	v_mad_u64_u32 v[202:203], s[18:19], v2, s36, v[0:1]
	v_add_u32_e32 v2, 0x600, v8
	v_lshrrev_b32_e32 v2, 3, v2
	v_mad_u64_u32 v[204:205], s[18:19], v2, s36, v[0:1]
	v_add_u32_e32 v2, 0x700, v8
	v_lshrrev_b32_e32 v2, 3, v2
	v_mad_u64_u32 v[206:207], s[18:19], v2, s36, v[0:1]
	s_add_u32 s36, s15, s10
	v_mov_b32_e32 v2, 0
	s_addc_u32 s37, s8, s85
	s_mov_b64 s[18:19], 0
	s_mov_b32 s44, 64
	v_mov_b32_e32 v3, v2
	v_mov_b32_e32 v4, v2
	v_mov_b32_e32 v5, v2
	v_mov_b32_e32 v6, v2
	v_mov_b32_e32 v7, v2
	v_mov_b32_e32 v8, v2
	v_mov_b32_e32 v9, v2
	v_mov_b32_e32 v10, v2
	v_mov_b32_e32 v11, v2
	v_mov_b32_e32 v12, v2
	v_mov_b32_e32 v13, v2
	v_mov_b32_e32 v14, v2
	v_mov_b32_e32 v15, v2
	v_mov_b32_e32 v16, v2
	v_mov_b32_e32 v17, v2
	v_mov_b32_e32 v18, v2
	v_mov_b32_e32 v19, v2
	v_mov_b32_e32 v20, v2
	v_mov_b32_e32 v21, v2
	v_mov_b32_e32 v22, v2
	v_mov_b32_e32 v23, v2
	v_mov_b32_e32 v24, v2
	v_mov_b32_e32 v25, v2
	v_mov_b32_e32 v26, v2
	v_mov_b32_e32 v27, v2
	v_mov_b32_e32 v28, v2
	v_mov_b32_e32 v29, v2
	v_mov_b32_e32 v30, v2
	v_mov_b32_e32 v31, v2
	v_mov_b32_e32 v32, v2
	v_mov_b32_e32 v33, v2
	v_mov_b32_e32 v34, v2
	v_mov_b32_e32 v35, v2
	v_mov_b32_e32 v36, v2
	v_mov_b32_e32 v37, v2
	v_mov_b32_e32 v38, v2
	v_mov_b32_e32 v39, v2
	v_mov_b32_e32 v40, v2
	v_mov_b32_e32 v41, v2
	v_mov_b32_e32 v42, v2
	v_mov_b32_e32 v43, v2
	v_mov_b32_e32 v44, v2
	v_mov_b32_e32 v45, v2
	v_mov_b32_e32 v46, v2
	v_mov_b32_e32 v47, v2
	v_mov_b32_e32 v48, v2
	v_mov_b32_e32 v49, v2
	v_mov_b32_e32 v50, v2
	v_mov_b32_e32 v51, v2
	v_mov_b32_e32 v52, v2
	v_mov_b32_e32 v53, v2
	v_mov_b32_e32 v54, v2
	v_mov_b32_e32 v55, v2
	v_mov_b32_e32 v56, v2
	v_mov_b32_e32 v57, v2
	v_mov_b32_e32 v58, v2
	v_mov_b32_e32 v59, v2
	v_mov_b32_e32 v60, v2
	v_mov_b32_e32 v61, v2
	v_mov_b32_e32 v62, v2
	v_mov_b32_e32 v63, v2
	v_mov_b32_e32 v64, v2
	v_mov_b32_e32 v65, v2
	v_mov_b32_e32 v66, v2
	v_mov_b32_e32 v67, v2
	v_mov_b32_e32 v68, v2
	v_mov_b32_e32 v69, v2
	s_waitcnt vmcnt(18)
; #define MFMA32(a, b, c) __builtin_amdgcn_mfma_f32_32x32x16_bf16((a), (b), (c), 0, 0, 0)
; #define GLOAD2(K0) { const int tl = otid(); LDA2(0, K0) LDA2(1, K0) LDA2(2, K0) LDA2(3, K0) LDB2(0, K0) LDB2(1, K0) LDB2(2, K0) LDB2(3, K0) LDB2(4, K0) LDB2(5, K0) LDB2(6, K0) LDB2(7, K0) }
; #define SSTORE2() { STA2(0) STA2(1) STA2(2) STA2(3) STB2(0) STB2(1) STB2(2) STB2(3) STB2(4) STB2(5) STB2(6) STB2(7) }
; template <class AF, class Epi>
; DI void gemm_tile2(AF af, const bf16* __restrict__ Bt, int ldb, int K, char* smem, int& n0ref, int nhalf, Epi epi) {
;     ...
;   for (int kt = 0; kt < nk; ++kt) {
;     __syncthreads();
;     SSTORE2();
;     __syncthreads();
;     if (kt + 1 < nk) GLOAD2((kt + 1) * 64);
; #pragma unroll
;     for (int ks = 0; ks < 4; ++ks) {
;       bf16x8 fa[2], fb[4];
; #pragma unroll
;       for (int mb = 0; mb < 2; ++mb) fa[mb] = *(const bf16x8*)(a_ + mb * 32 * 72 + ks * 16);
; #pragma unroll
;       for (int nb = 0; nb < 4; ++nb) fb[nb] = *(const bf16x8*)(b_ + nb * 32 * 72 + ks * 16);
; #pragma unroll
;       for (int mb = 0; mb < 2; ++mb)
; #pragma unroll
;         for (int nb = 0; nb < 4; ++nb) acc[mb][nb] = MFMA32(fa[mb], fb[nb], acc[mb][nb]);
;     }
	v_mov_b32_e32 v70, v2
	v_mov_b32_e32 v71, v2
	v_mov_b32_e32 v72, v2
	v_mov_b32_e32 v73, v2
	s_waitcnt vmcnt(17)
	v_mov_b32_e32 v74, v2
	v_mov_b32_e32 v75, v2
	v_mov_b32_e32 v76, v2
	v_mov_b32_e32 v77, v2
	s_waitcnt vmcnt(16)
	v_mov_b32_e32 v78, v2
	v_mov_b32_e32 v79, v2
	v_mov_b32_e32 v80, v2
	v_mov_b32_e32 v81, v2
	s_waitcnt vmcnt(15)
	v_mov_b32_e32 v82, v2
	v_mov_b32_e32 v83, v2
	v_mov_b32_e32 v84, v2
	v_mov_b32_e32 v85, v2
	s_waitcnt vmcnt(14)
	v_mov_b32_e32 v86, v2
	v_mov_b32_e32 v87, v2
	v_mov_b32_e32 v88, v2
	v_mov_b32_e32 v89, v2
	v_mov_b32_e32 v90, v2
	v_mov_b32_e32 v91, v2
	v_mov_b32_e32 v92, v2
	v_mov_b32_e32 v93, v2
	s_waitcnt vmcnt(13)
	v_mov_b32_e32 v94, v2
	v_mov_b32_e32 v95, v2
	v_mov_b32_e32 v96, v2
	v_mov_b32_e32 v97, v2
	v_mov_b32_e32 v98, v2
	v_mov_b32_e32 v99, v2
	v_mov_b32_e32 v100, v2
	v_mov_b32_e32 v101, v2
	s_waitcnt vmcnt(12)
	v_mov_b32_e32 v102, v2
	v_mov_b32_e32 v103, v2
	v_mov_b32_e32 v104, v2
	v_mov_b32_e32 v105, v2
	v_mov_b32_e32 v106, v2
	v_mov_b32_e32 v107, v2
	v_mov_b32_e32 v108, v2
	v_mov_b32_e32 v109, v2
	v_mov_b32_e32 v110, v2
	v_mov_b32_e32 v111, v2
	v_mov_b32_e32 v112, v2
	v_mov_b32_e32 v113, v2
	v_mov_b32_e32 v114, v2
	v_mov_b32_e32 v115, v2
	v_mov_b32_e32 v116, v2
	v_mov_b32_e32 v117, v2
	v_mov_b32_e32 v118, v2
	v_mov_b32_e32 v119, v2
	v_mov_b32_e32 v120, v2
	v_mov_b32_e32 v121, v2
	v_mov_b32_e32 v122, v2
	v_mov_b32_e32 v123, v2
	v_mov_b32_e32 v124, v2
	v_mov_b32_e32 v125, v2
	v_mov_b32_e32 v126, v2
	v_mov_b32_e32 v127, v2
	v_mov_b32_e32 v128, v2
	v_mov_b32_e32 v129, v2
	v_lshrrev_b32_e32 v236, 3, v189
	v_mul_u32_u24_e32 v236, 0x1080, v236
	v_and_b32_e32 v208, 7, v189
	v_lshl_add_u32 v236, v208, 4, v236
.LBB0_139:
	s_barrier
	s_waitcnt vmcnt(11)
	ds_write_b128 v184, v[130:133]
	s_waitcnt vmcnt(10)
	ds_write_b128 v194, v[134:137]
	s_waitcnt vmcnt(9)
	ds_write_b128 v196, v[138:141]
	s_waitcnt vmcnt(8)
	ds_write_b128 v198, v[142:145]
	s_waitcnt vmcnt(7)
	ds_write_b128 v184, v[146:149] offset:18432
	s_waitcnt vmcnt(6)
	ds_write_b128 v194, v[150:153] offset:18432
	s_waitcnt vmcnt(5)
	ds_write_b128 v196, v[154:157] offset:18432
	s_waitcnt vmcnt(4)
	ds_write_b128 v198, v[158:161] offset:18432
	s_waitcnt vmcnt(3)
	ds_write_b128 v200, v[162:165] offset:18432
	s_waitcnt vmcnt(2)
	ds_write_b128 v202, v[166:169] offset:18432
	s_waitcnt vmcnt(1)
	ds_write_b128 v204, v[170:173] offset:18432
	s_waitcnt vmcnt(0)
	ds_write_b128 v206, v[174:177] offset:18432
	s_waitcnt lgkmcnt(0)
	s_barrier
	ds_read_b128 v[246:249], v182
	ds_read_b128 v[208:211], v183 offset:18432
	ds_read_b128 v[212:215], v183 offset:23040
	ds_read_b128 v[224:227], v183 offset:27648
	ds_read_b128 v[228:231], v183 offset:32256
	ds_read_b128 v[250:253], v182 offset:4608
	s_lshl_b32 s46, s44, 1
	s_add_u32 s46, s0, s46
	s_addc_u32 s47, s1, 0
	global_load_dwordx4 v[130:133], v236, s[46:47]
	s_add_u32 s46, s46, 0x21000
	s_addc_u32 s47, s47, 0
	global_load_dwordx4 v[134:137], v236, s[46:47]
	s_add_u32 s46, s46, 0x21000
	s_addc_u32 s47, s47, 0
	global_load_dwordx4 v[138:141], v236, s[46:47]
	s_add_u32 s46, s46, 0x21000
	s_addc_u32 s47, s47, 0
	global_load_dwordx4 v[142:145], v236, s[46:47]
	s_add_u32 s46, s36, s18
	s_addc_u32 s47, s37, s19
	global_load_dwordx4 v[146:149], v236, s[46:47]
	s_add_u32 s46, s46, 0x21000
	s_addc_u32 s47, s47, 0
	global_load_dwordx4 v[150:153], v236, s[46:47]
	s_add_u32 s46, s46, 0x21000
	s_addc_u32 s47, s47, 0
	global_load_dwordx4 v[154:157], v236, s[46:47]
	s_add_u32 s46, s46, 0x21000
	s_addc_u32 s47, s47, 0
	global_load_dwordx4 v[158:161], v236, s[46:47]
	s_add_u32 s46, s46, 0x21000
	s_addc_u32 s47, s47, 0
	global_load_dwordx4 v[162:165], v236, s[46:47]
	s_add_u32 s46, s46, 0x21000
	s_addc_u32 s47, s47, 0
	global_load_dwordx4 v[166:169], v236, s[46:47]
	s_add_u32 s46, s46, 0x21000
	s_addc_u32 s47, s47, 0
	global_load_dwordx4 v[170:173], v236, s[46:47]
	s_add_u32 s46, s46, 0x21000
	s_addc_u32 s47, s47, 0
	global_load_dwordx4 v[174:177], v236, s[46:47]
	s_add_u32 s18, s18, 0x80
	s_addc_u32 s19, s19, 0
	s_add_i32 s44, s44, 64
	s_waitcnt lgkmcnt(4)
	v_mfma_f32_32x32x16_bf16 v[114:129], v[246:249], v[208:211], v[114:129]
	s_waitcnt lgkmcnt(3)
	v_mfma_f32_32x32x16_bf16 v[98:113], v[246:249], v[212:215], v[98:113]
	s_waitcnt lgkmcnt(2)
	v_mfma_f32_32x32x16_bf16 v[82:97], v[246:249], v[224:227], v[82:97]
	s_waitcnt lgkmcnt(1)
	v_mfma_f32_32x32x16_bf16 v[66:81], v[246:249], v[228:231], v[66:81]
	ds_read_b128 v[246:249], v182 offset:32
	s_waitcnt lgkmcnt(1)
	v_mfma_f32_32x32x16_bf16 v[50:65], v[250:253], v[208:211], v[50:65]
	ds_read_b128 v[208:211], v183 offset:18464
	v_mfma_f32_32x32x16_bf16 v[34:49], v[250:253], v[212:215], v[34:49]
	ds_read_b128 v[212:215], v183 offset:23072
	v_mfma_f32_32x32x16_bf16 v[18:33], v[250:253], v[224:227], v[18:33]
	ds_read_b128 v[224:227], v183 offset:27680
	v_mfma_f32_32x32x16_bf16 v[2:17], v[250:253], v[228:231], v[2:17]
	ds_read_b128 v[228:231], v183 offset:32288
	ds_read_b128 v[250:253], v182 offset:4640
	s_waitcnt lgkmcnt(4)
	v_mfma_f32_32x32x16_bf16 v[114:129], v[246:249], v[208:211], v[114:129]
	s_waitcnt lgkmcnt(3)
	v_mfma_f32_32x32x16_bf16 v[98:113], v[246:249], v[212:215], v[98:113]
	s_waitcnt lgkmcnt(2)
	v_mfma_f32_32x32x16_bf16 v[82:97], v[246:249], v[224:227], v[82:97]
	s_waitcnt lgkmcnt(1)
	v_mfma_f32_32x32x16_bf16 v[66:81], v[246:249], v[228:231], v[66:81]
	ds_read_b128 v[246:249], v182 offset:64
	s_waitcnt lgkmcnt(1)
	v_mfma_f32_32x32x16_bf16 v[50:65], v[250:253], v[208:211], v[50:65]
	ds_read_b128 v[208:211], v183 offset:18496
	v_mfma_f32_32x32x16_bf16 v[34:49], v[250:253], v[212:215], v[34:49]
	ds_read_b128 v[212:215], v183 offset:23104
	v_mfma_f32_32x32x16_bf16 v[18:33], v[250:253], v[224:227], v[18:33]
	ds_read_b128 v[224:227], v183 offset:27712
	v_mfma_f32_32x32x16_bf16 v[2:17], v[250:253], v[228:231], v[2:17]
	ds_read_b128 v[228:231], v183 offset:32320
	ds_read_b128 v[250:253], v182 offset:4672
	s_waitcnt lgkmcnt(4)
; #define MFMA32(a, b, c) __builtin_amdgcn_mfma_f32_32x32x16_bf16((a), (b), (c), 0, 0, 0)
; #define GLOAD2(K0) { const int tl = otid(); LDA2(0, K0) LDA2(1, K0) LDA2(2, K0) LDA2(3, K0) LDB2(0, K0) LDB2(1, K0) LDB2(2, K0) LDB2(3, K0) LDB2(4, K0) LDB2(5, K0) LDB2(6, K0) LDB2(7, K0) }
; #define SSTORE2() { STA2(0) STA2(1) STA2(2) STA2(3) STB2(0) STB2(1) STB2(2) STB2(3) STB2(4) STB2(5) STB2(6) STB2(7) }
; template <class AF, class Epi>
; DI void gemm_tile2(AF af, const bf16* __restrict__ Bt, int ldb, int K, char* smem, int& n0ref, int nhalf, Epi epi) {
;     ...
;   for (int kt = 0; kt < nk; ++kt) {
;     __syncthreads();
;     SSTORE2();
;     __syncthreads();
;     if (kt + 1 < nk) GLOAD2((kt + 1) * 64);
; #pragma unroll
;     for (int ks = 0; ks < 4; ++ks) {
;       bf16x8 fa[2], fb[4];
; #pragma unroll
;       for (int mb = 0; mb < 2; ++mb) fa[mb] = *(const bf16x8*)(a_ + mb * 32 * 72 + ks * 16);
; #pragma unroll
;       for (int nb = 0; nb < 4; ++nb) fb[nb] = *(const bf16x8*)(b_ + nb * 32 * 72 + ks * 16);
; #pragma unroll
;       for (int mb = 0; mb < 2; ++mb)
; #pragma unroll
;         for (int nb = 0; nb < 4; ++nb) acc[mb][nb] = MFMA32(fa[mb], fb[nb], acc[mb][nb]);
;     }
;   }
	v_mfma_f32_32x32x16_bf16 v[114:129], v[246:249], v[208:211], v[114:129]
	s_waitcnt lgkmcnt(3)
	v_mfma_f32_32x32x16_bf16 v[98:113], v[246:249], v[212:215], v[98:113]
	s_waitcnt lgkmcnt(2)
	v_mfma_f32_32x32x16_bf16 v[82:97], v[246:249], v[224:227], v[82:97]
	s_waitcnt lgkmcnt(1)
	v_mfma_f32_32x32x16_bf16 v[66:81], v[246:249], v[228:231], v[66:81]
	ds_read_b128 v[246:249], v182 offset:96
	s_waitcnt lgkmcnt(1)
	v_mfma_f32_32x32x16_bf16 v[50:65], v[250:253], v[208:211], v[50:65]
	ds_read_b128 v[208:211], v183 offset:18528
	v_mfma_f32_32x32x16_bf16 v[34:49], v[250:253], v[212:215], v[34:49]
	ds_read_b128 v[212:215], v183 offset:23136
	v_mfma_f32_32x32x16_bf16 v[18:33], v[250:253], v[224:227], v[18:33]
	ds_read_b128 v[224:227], v183 offset:27744
	v_mfma_f32_32x32x16_bf16 v[2:17], v[250:253], v[228:231], v[2:17]
	ds_read_b128 v[228:231], v183 offset:32352
	ds_read_b128 v[250:253], v182 offset:4704
	s_waitcnt lgkmcnt(4)
	v_mfma_f32_32x32x16_bf16 v[114:129], v[246:249], v[208:211], v[114:129]
	s_waitcnt lgkmcnt(3)
	v_mfma_f32_32x32x16_bf16 v[98:113], v[246:249], v[212:215], v[98:113]
	s_waitcnt lgkmcnt(2)
	v_mfma_f32_32x32x16_bf16 v[82:97], v[246:249], v[224:227], v[82:97]
	s_waitcnt lgkmcnt(1)
	v_mfma_f32_32x32x16_bf16 v[66:81], v[246:249], v[228:231], v[66:81]
	s_waitcnt lgkmcnt(0)
	v_mfma_f32_32x32x16_bf16 v[50:65], v[250:253], v[208:211], v[50:65]
	v_mfma_f32_32x32x16_bf16 v[34:49], v[250:253], v[212:215], v[34:49]
	v_mfma_f32_32x32x16_bf16 v[18:33], v[250:253], v[224:227], v[18:33]
	v_mfma_f32_32x32x16_bf16 v[2:17], v[250:253], v[228:231], v[2:17]
	s_cmpk_eq_i32 s18, 0xf80
	s_cbranch_scc0 .LBB0_139
	v_add_u32_e32 v208, 0x100, v189
	v_add_u32_e32 v209, 0x200, v189
	v_add_u32_e32 v210, 0x300, v189
	v_or_b32_e32 v211, 0x400, v189
	v_add_u32_e32 v212, 0x500, v189
	v_mov_b32_e32 v213, 0x12400
	v_mov_b32_e32 v214, 0x12404
	v_mov_b32_e32 v215, 0x461c4000
	v_mov_b32_e32 v224, 0x7f800000
	v_mov_b32_e32 v225, 0xffffffc0
	v_mov_b32_e32 v226, 0xffffffe0
	v_mov_b32_e32 v227, 0x7fc00000
	v_mbcnt_lo_u32_b32 v228, -1, 0
	v_mbcnt_hi_u32_b32 v228, -1, v228
	v_mov_b32_e32 v229, 0x3ecc95a3
	v_mov_b32_e32 v230, 0xf149f2ca
	v_mov_b32_e32 v231, 0x12000
	v_mov_b32_e32 v236, 0x31f
	s_barrier
	s_waitcnt vmcnt(11)
	ds_write_b128 v184, v[130:133]
	s_waitcnt vmcnt(10)
	ds_write_b128 v194, v[134:137]
	s_waitcnt vmcnt(9)
	ds_write_b128 v196, v[138:141]
	s_waitcnt vmcnt(8)
	ds_write_b128 v198, v[142:145]
	s_waitcnt vmcnt(7)
	ds_write_b128 v184, v[146:149] offset:18432
	s_waitcnt vmcnt(6)
	ds_write_b128 v194, v[150:153] offset:18432
	s_waitcnt vmcnt(5)
	ds_write_b128 v196, v[154:157] offset:18432
	s_waitcnt vmcnt(4)
	ds_write_b128 v198, v[158:161] offset:18432
	s_waitcnt vmcnt(3)
	ds_write_b128 v200, v[162:165] offset:18432
	s_waitcnt vmcnt(2)
	ds_write_b128 v202, v[166:169] offset:18432
	s_waitcnt vmcnt(1)
	ds_write_b128 v204, v[170:173] offset:18432
	s_waitcnt vmcnt(0)
	ds_write_b128 v206, v[174:177] offset:18432
	s_waitcnt lgkmcnt(0)
	s_barrier
	ds_read_b128 v[130:133], v182
	ds_read_b128 v[134:137], v183 offset:18432
	ds_read_b128 v[138:141], v183 offset:18464
	ds_read_b128 v[142:145], v182 offset:32
	ds_read_b128 v[146:149], v183 offset:23040
	ds_read_b128 v[150:153], v183 offset:23072
	ds_read_b128 v[154:157], v183 offset:27648
	ds_read_b128 v[158:161], v183 offset:27680
	ds_read_b128 v[162:165], v183 offset:32256
	ds_read_b128 v[166:169], v183 offset:32288
	s_waitcnt lgkmcnt(8)
	v_mfma_f32_32x32x16_bf16 v[114:129], v[130:133], v[134:137], v[114:129]
	v_cmp_ne_u32_e64 s[18:19], 0, v241
	v_cmp_eq_u32_e32 vcc, 0, v241
	s_waitcnt lgkmcnt(5)
	v_mfma_f32_32x32x16_bf16 v[98:113], v[130:133], v[146:149], v[98:113]
	s_waitcnt lgkmcnt(3)
	v_mfma_f32_32x32x16_bf16 v[82:97], v[130:133], v[154:157], v[82:97]
	s_waitcnt lgkmcnt(1)
	v_mfma_f32_32x32x16_bf16 v[66:81], v[130:133], v[162:165], v[66:81]
	ds_read_b128 v[130:133], v182 offset:4608
	ds_read_b128 v[170:173], v182 offset:4640
	s_waitcnt lgkmcnt(1)
	v_mfma_f32_32x32x16_bf16 v[50:65], v[130:133], v[134:137], v[50:65]
	v_mfma_f32_32x32x16_bf16 v[34:49], v[130:133], v[146:149], v[34:49]
	v_mfma_f32_32x32x16_bf16 v[18:33], v[130:133], v[154:157], v[18:33]
	v_mfma_f32_32x32x16_bf16 v[2:17], v[130:133], v[162:165], v[2:17]
	v_mfma_f32_32x32x16_bf16 v[114:129], v[142:145], v[138:141], v[114:129]
	v_mfma_f32_32x32x16_bf16 v[98:113], v[142:145], v[150:153], v[98:113]
	v_mfma_f32_32x32x16_bf16 v[82:97], v[142:145], v[158:161], v[82:97]
	v_mfma_f32_32x32x16_bf16 v[66:81], v[142:145], v[166:169], v[66:81]
	s_waitcnt lgkmcnt(0)
	v_mfma_f32_32x32x16_bf16 v[50:65], v[170:173], v[138:141], v[50:65]
	ds_read_b128 v[130:133], v182 offset:64
	ds_read_b128 v[134:137], v183 offset:18496
	ds_read_b128 v[138:141], v182 offset:96
	ds_read_b128 v[142:145], v183 offset:18528
	v_mfma_f32_32x32x16_bf16 v[34:49], v[170:173], v[150:153], v[34:49]
	ds_read_b128 v[146:149], v183 offset:23104
	ds_read_b128 v[150:153], v183 offset:23136
	v_mfma_f32_32x32x16_bf16 v[18:33], v[170:173], v[158:161], v[18:33]
	ds_read_b128 v[154:157], v183 offset:27712
	ds_read_b128 v[158:161], v183 offset:27744
	v_mfma_f32_32x32x16_bf16 v[2:17], v[170:173], v[166:169], v[2:17]
	ds_read_b128 v[162:165], v183 offset:32320
	ds_read_b128 v[166:169], v183 offset:32352
	s_waitcnt lgkmcnt(8)
	v_mfma_f32_32x32x16_bf16 v[114:129], v[130:133], v[134:137], v[114:129]
	s_waitcnt lgkmcnt(5)
	v_mfma_f32_32x32x16_bf16 v[98:113], v[130:133], v[146:149], v[98:113]
	s_waitcnt lgkmcnt(3)
	v_mfma_f32_32x32x16_bf16 v[82:97], v[130:133], v[154:157], v[82:97]
	s_waitcnt lgkmcnt(1)
	v_mfma_f32_32x32x16_bf16 v[66:81], v[130:133], v[162:165], v[66:81]
	ds_read_b128 v[130:133], v182 offset:4672
	ds_read_b128 v[170:173], v182 offset:4704
	s_waitcnt lgkmcnt(0)
	s_barrier
; DI int crow(int i, int h) { return (i & 3) + 8 * (i >> 2) + 4 * h; }
; template <class AF, class Epi>
; DI void gemm_tile2(AF af, const bf16* __restrict__ Bt, int ldb, int K, char* smem, int& n0ref, int nhalf, Epi epi) {
;     ...
;   float* Cs = (float*)smem;
; #pragma unroll
;   for (int hf = 0; hf < 2; ++hf) {
;     if (hf < nhalf) {
;       __syncthreads();
;       if (wn == hf) {
; #pragma unroll
;         for (int mb = 0; mb < 2; ++mb)
; #pragma unroll
;           for (int nb = 0; nb < 4; ++nb)
; #pragma unroll
;             for (int i = 0; i < 16; ++i) Cs[(wm * 64 + mb * 32 + crow(i, h)) * 132 + nb * 32 + r] = acc[mb][nb][i];
;       }
;       __syncthreads();
	v_mfma_f32_32x32x16_bf16 v[50:65], v[130:133], v[134:137], v[50:65]
	v_mfma_f32_32x32x16_bf16 v[34:49], v[130:133], v[146:149], v[34:49]
	v_mfma_f32_32x32x16_bf16 v[18:33], v[130:133], v[154:157], v[18:33]
	v_mfma_f32_32x32x16_bf16 v[2:17], v[130:133], v[162:165], v[2:17]
	v_mfma_f32_32x32x16_bf16 v[114:129], v[138:141], v[142:145], v[114:129]
	v_mfma_f32_32x32x16_bf16 v[98:113], v[138:141], v[150:153], v[98:113]
	v_mfma_f32_32x32x16_bf16 v[82:97], v[138:141], v[158:161], v[82:97]
	v_mfma_f32_32x32x16_bf16 v[66:81], v[138:141], v[166:169], v[66:81]
	v_lshl_or_b32 v139, v242, 2, v244
	v_lshlrev_b32_e32 v138, 2, v243
	v_mfma_f32_32x32x16_bf16 v[50:65], v[170:173], v[142:145], v[50:65]
	v_mfma_f32_32x32x16_bf16 v[34:49], v[170:173], v[150:153], v[34:49]
	v_mfma_f32_32x32x16_bf16 v[18:33], v[170:173], v[158:161], v[18:33]
	v_mfma_f32_32x32x16_bf16 v[2:17], v[170:173], v[166:169], v[2:17]
	s_and_saveexec_b64 s[36:37], vcc
	s_cbranch_execz .LBB0_142
	v_mad_u64_u32 v[130:131], s[44:45], v139, s54, v[138:139]
	v_add_u32_e32 v0, 0x400, v130
	v_add_u32_e32 v131, 0x1000, v130
	v_add_u32_e32 v132, 0x1400, v130
	v_add_u32_e32 v133, 0x2000, v130
	v_add_u32_e32 v134, 0x2400, v130
	v_add_u32_e32 v136, 0x3200, v130
	ds_write2_b32 v130, v114, v98 offset1:32
	ds_write2_b32 v130, v115, v99 offset0:132 offset1:164
	ds_write2_b32 v0, v116, v100 offset0:8 offset1:40
	ds_write2_b32 v0, v117, v101 offset0:140 offset1:172
	ds_write2_b32 v131, v118, v102 offset0:32 offset1:64
	ds_write2_b32 v131, v119, v103 offset0:164 offset1:196
	ds_write2_b32 v132, v120, v104 offset0:40 offset1:72
	ds_write2_b32 v132, v121, v105 offset0:172 offset1:204
	ds_write2_b32 v133, v122, v106 offset0:64 offset1:96
	ds_write2_b32 v133, v123, v107 offset0:196 offset1:228
	ds_write2_b32 v134, v124, v108 offset0:72 offset1:104
	ds_write2_b32 v134, v125, v109 offset0:204 offset1:236
	v_add_u32_e32 v135, 0x3000, v130
	ds_write2_b32 v136, v127, v111 offset0:100 offset1:132
	v_add_u32_e32 v136, 0x3400, v130
	v_add_u32_e32 v137, 0x3600, v130
	ds_write2_b32 v135, v126, v110 offset0:96 offset1:128
	ds_write2_b32 v136, v128, v112 offset0:104 offset1:136
	ds_write2_b32 v137, v129, v113 offset0:108 offset1:140
	ds_write2_b32 v130, v82, v66 offset0:64 offset1:96
	ds_write2_b32 v130, v83, v67 offset0:196 offset1:228
	ds_write2_b32 v0, v84, v68 offset0:72 offset1:104
	ds_write2_b32 v0, v85, v69 offset0:204 offset1:236
	ds_write2_b32 v131, v86, v70 offset0:96 offset1:128
	v_add_u32_e32 v0, 0x1200, v130
	ds_write2_b32 v0, v87, v71 offset0:100 offset1:132
	ds_write2_b32 v132, v88, v72 offset0:104 offset1:136
	v_add_u32_e32 v0, 0x1600, v130
	ds_write2_b32 v0, v89, v73 offset0:108 offset1:140
	ds_write2_b32 v133, v90, v74 offset0:128 offset1:160
	ds_write2_b32 v134, v91, v75 offset0:4 offset1:36
	ds_write2_b32 v134, v92, v76 offset0:136 offset1:168
	v_add_u32_e32 v0, 0x2800, v130
	ds_write2_b32 v0, v93, v77 offset0:12 offset1:44
	ds_write2_b32 v135, v94, v78 offset0:160 offset1:192
	ds_write2_b32 v136, v95, v79 offset0:36 offset1:68
	ds_write2_b32 v136, v96, v80 offset0:168 offset1:200
	v_add_u32_e32 v0, 0x3800, v130
	ds_write2_b32 v0, v97, v81 offset0:44 offset1:76
	v_add_u32_e32 v0, 0x4000, v130
	v_add_u32_e32 v131, 0x4400, v130
	v_add_u32_e32 v133, 0x5000, v130
	ds_write2_b32 v0, v50, v34 offset0:128 offset1:160
	ds_write2_b32 v131, v51, v35 offset0:4 offset1:36
	ds_write2_b32 v131, v52, v36 offset0:136 offset1:168
	v_add_u32_e32 v132, 0x4800, v130
	ds_write2_b32 v133, v54, v38 offset0:160 offset1:192
	v_add_u32_e32 v133, 0x5400, v130
	v_add_u32_e32 v135, 0x6000, v130
	ds_write2_b32 v132, v53, v37 offset0:12 offset1:44
	ds_write2_b32 v133, v55, v39 offset0:36 offset1:68
	ds_write2_b32 v133, v56, v40 offset0:168 offset1:200
	v_add_u32_e32 v134, 0x5800, v130
	ds_write2_b32 v135, v58, v42 offset0:192 offset1:224
	v_add_u32_e32 v135, 0x6400, v130
	v_add_u32_e32 v137, 0x7200, v130
	v_add_u32_e32 v140, 0x7600, v130
	ds_write2_b32 v134, v57, v41 offset0:44 offset1:76
	ds_write2_b32 v135, v59, v43 offset0:68 offset1:100
	ds_write2_b32 v135, v60, v44 offset0:200 offset1:232
	v_add_u32_e32 v136, 0x6800, v130
	ds_write2_b32 v137, v62, v46 offset0:96 offset1:128
	v_add_u32_e32 v137, 0x7400, v130
	ds_write2_b32 v140, v64, v48 offset0:104 offset1:136
	v_add_u32_e32 v140, 0x7800, v130
	ds_write2_b32 v136, v61, v45 offset0:76 offset1:108
	ds_write2_b32 v137, v63, v47 offset0:100 offset1:132
	ds_write2_b32 v140, v65, v49 offset0:108 offset1:140
	ds_write2_b32 v0, v18, v2 offset0:192 offset1:224
	ds_write2_b32 v131, v19, v3 offset0:68 offset1:100
	ds_write2_b32 v131, v20, v4 offset0:200 offset1:232
	ds_write2_b32 v132, v21, v5 offset0:76 offset1:108
	v_add_u32_e32 v0, 0x5200, v130
	ds_write2_b32 v0, v22, v6 offset0:96 offset1:128
	ds_write2_b32 v133, v23, v7 offset0:100 offset1:132
	v_add_u32_e32 v0, 0x5600, v130
	ds_write2_b32 v0, v24, v8 offset0:104 offset1:136
	ds_write2_b32 v134, v25, v9 offset0:108 offset1:140
	ds_write2_b32 v135, v26, v10 offset1:32
	ds_write2_b32 v135, v27, v11 offset0:132 offset1:164
	ds_write2_b32 v136, v28, v12 offset0:8 offset1:40
	ds_write2_b32 v136, v29, v13 offset0:140 offset1:172
	ds_write2_b32 v137, v30, v14 offset0:32 offset1:64
	ds_write2_b32 v137, v31, v15 offset0:164 offset1:196
	ds_write2_b32 v140, v32, v16 offset0:40 offset1:72
	ds_write2_b32 v140, v33, v17 offset0:172 offset1:204

; DI int otid() { int z; asm volatile("s_mov_b32 %0, 0" : "=s"(z)); return (int)threadIdx.x + z; }
; #define GLOAD2(K0) { const int tl = otid(); LDA2(0, K0) LDA2(1, K0) LDA2(2, K0) LDA2(3, K0) LDB2(0, K0) LDB2(1, K0) LDB2(2, K0) LDB2(3, K0) LDB2(4, K0) LDB2(5, K0) LDB2(6, K0) LDB2(7, K0) }
; template <class AF, class Epi>
; DI void gemm_tile2(AF af, const bf16* __restrict__ Bt, int ldb, int K, char* smem, int& n0ref, int nhalf, Epi epi) {
;   const int tid = otid(), lane = tid & 63, w = tid >> 6, r = lane & 31, h = lane >> 5;
;   const int wm = w >> 1, wn = w & 1;
;   bf16* As = (bf16*)smem;
;   bf16* Bs = As + 128 * 72;
;   f32x16 acc[2][4];
; #pragma unroll
;   for (int a = 0; a < 2; ++a)
; #pragma unroll
;     for (int b = 0; b < 4; ++b)
; #pragma unroll
;       for (int i = 0; i < 16; ++i) acc[a][b][i] = 0.f;
;   uint4 pa_0, pa_1, pa_2, pa_3, pb_0, pb_1, pb_2, pb_3, pb_4, pb_5, pb_6, pb_7;
;     ...
;   const int nk = K >> 6;
;   GLOAD2(0);
;   const bf16* a_ = As + (wm * 64 + r) * 72 + h * 8;
;   const bf16* b_ = Bs + (wn * 128 + r) * 72 + h * 8;
; __global__ void __launch_bounds__(256, LB2) mega(Params p, int ph_lo, int ph_hi) {
;     ...
;           } else {
;             gemm_tile2(af, Win + (size_t)n0 * LDX, LDX, DM, smem, n0, nhalf, [&](const float* Cs) {
.LBB0_171:
	s_mov_b32 s11, 0
	v_mov_b64_e32 v[2:3], s[0:1]
	v_add_u32_e32 v8, s11, v189
	s_mov_b32 s11, 0
	v_bfe_u32 v242, v8, 5, 1
	v_add_u32_e32 v9, s11, v189
	v_add_u32_e32 v6, 0x100, v9
	v_ashrrev_i32_e32 v10, 3, v9
	v_lshlrev_b32_e32 v0, 4, v9
	v_ashrrev_i32_e32 v11, 3, v6
	v_mad_i64_i32 v[4:5], s[18:19], v10, s75, v[2:3]
	v_and_b32_e32 v0, 0x70, v0
	v_mad_i64_i32 v[6:7], s[18:19], v11, s75, v[2:3]
	v_lshl_add_u64 v[4:5], v[4:5], 0, v[0:1]
	v_lshl_add_u64 v[6:7], v[6:7], 0, v[0:1]
	s_waitcnt lgkmcnt(0)
	global_load_dwordx4 v[130:133], v[4:5], off
	global_load_dwordx4 v[134:137], v[6:7], off
	v_add_u32_e32 v4, 0x200, v9
	v_add_u32_e32 v6, 0x300, v9
	v_ashrrev_i32_e32 v12, 3, v4
	v_ashrrev_i32_e32 v13, 3, v6
	v_mad_i64_i32 v[4:5], s[18:19], v12, s75, v[2:3]
	v_mad_i64_i32 v[2:3], s[18:19], v13, s75, v[2:3]
	v_lshl_add_u64 v[4:5], v[4:5], 0, v[0:1]
	v_lshl_add_u64 v[2:3], v[2:3], 0, v[0:1]
	global_load_dwordx4 v[138:141], v[4:5], off
	global_load_dwordx4 v[142:145], v[2:3], off
	v_mov_b64_e32 v[2:3], s[26:27]
	v_mad_i64_i32 v[4:5], s[18:19], v10, s75, v[2:3]
	v_lshl_add_u64 v[4:5], v[4:5], 0, v[0:1]
	v_mad_i64_i32 v[6:7], s[18:19], v11, s75, v[2:3]
	v_lshl_add_u64 v[6:7], v[6:7], 0, v[0:1]
	global_load_dwordx4 v[146:149], v[4:5], off
	global_load_dwordx4 v[150:153], v[6:7], off
	v_mad_i64_i32 v[4:5], s[18:19], v12, s75, v[2:3]
	v_lshl_add_u64 v[4:5], v[4:5], 0, v[0:1]
	v_mad_i64_i32 v[6:7], s[18:19], v13, s75, v[2:3]
	v_lshl_add_u64 v[6:7], v[6:7], 0, v[0:1]
	global_load_dwordx4 v[154:157], v[4:5], off
	global_load_dwordx4 v[158:161], v[6:7], off
	v_add_u32_e32 v4, 0x400, v9
	v_ashrrev_i32_e32 v4, 3, v4
	v_add_u32_e32 v6, 0x500, v9
	v_mad_i64_i32 v[4:5], s[18:19], v4, s75, v[2:3]
	v_ashrrev_i32_e32 v6, 3, v6
	v_lshl_add_u64 v[4:5], v[4:5], 0, v[0:1]
	v_mad_i64_i32 v[6:7], s[18:19], v6, s75, v[2:3]
	v_lshl_add_u64 v[6:7], v[6:7], 0, v[0:1]
	global_load_dwordx4 v[162:165], v[4:5], off
	global_load_dwordx4 v[166:169], v[6:7], off
	v_add_u32_e32 v4, 0x600, v9
	v_ashrrev_i32_e32 v4, 3, v4
	v_add_u32_e32 v6, 0x700, v9
	v_mad_i64_i32 v[4:5], s[18:19], v4, s75, v[2:3]
	v_ashrrev_i32_e32 v6, 3, v6
	v_lshl_add_u64 v[4:5], v[4:5], 0, v[0:1]
	v_mad_i64_i32 v[2:3], s[18:19], v6, s75, v[2:3]
	v_lshl_add_u64 v[2:3], v[2:3], 0, v[0:1]
	global_load_dwordx4 v[170:173], v[4:5], off
	global_load_dwordx4 v[174:177], v[2:3], off
	v_ashrrev_i32_e32 v0, 1, v8
	v_and_b32_e32 v243, 31, v8
	v_and_b32_e32 v244, 0xffffffc0, v0
	v_bfe_u32 v241, v8, 6, 1
	v_or_b32_e32 v2, v244, v243
	v_lshlrev_b32_e32 v0, 4, v242
	s_movk_i32 s11, 0x90
	v_mad_u64_u32 v[182:183], s[18:19], v2, s11, v[0:1]
	v_lshl_or_b32 v2, v241, 7, v243
	v_mad_u32_u24 v183, v2, s11, v0
	v_lshlrev_b32_e32 v0, 4, v8
	v_lshrrev_b32_e32 v2, 3, v8
	v_and_b32_e32 v0, 0x70, v0
	v_mad_u64_u32 v[184:185], s[18:19], v2, s11, v[0:1]
	v_add_u32_e32 v2, 0x100, v8
	v_lshrrev_b32_e32 v2, 3, v2
	v_mad_u64_u32 v[194:195], s[18:19], v2, s11, v[0:1]
	v_add_u32_e32 v2, 0x200, v8
	v_lshrrev_b32_e32 v2, 3, v2
	v_mad_u64_u32 v[196:197], s[18:19], v2, s11, v[0:1]
	v_add_u32_e32 v2, 0x300, v8
	v_lshrrev_b32_e32 v2, 3, v2
	v_mad_u64_u32 v[198:199], s[18:19], v2, s11, v[0:1]
	v_add_u32_e32 v2, 0x400, v8
	v_lshrrev_b32_e32 v2, 3, v2
	v_mad_u64_u32 v[200:201], s[18:19], v2, s11, v[0:1]
	v_add_u32_e32 v2, 0x500, v8
	v_lshrrev_b32_e32 v2, 3, v2
	v_mad_u64_u32 v[202:203], s[18:19], v2, s11, v[0:1]
	v_add_u32_e32 v2, 0x600, v8
	v_lshrrev_b32_e32 v2, 3, v2
	v_mad_u64_u32 v[204:205], s[18:19], v2, s11, v[0:1]
	v_add_u32_e32 v2, 0x700, v8
	v_lshrrev_b32_e32 v2, 3, v2
	v_mad_u64_u32 v[206:207], s[18:19], v2, s11, v[0:1]
	s_add_u32 s10, s15, s10
	v_mov_b32_e32 v2, 0
	s_addc_u32 s11, s8, s85
	s_mov_b64 s[18:19], 0
	s_mov_b32 s26, 64
	v_mov_b32_e32 v3, v2
	v_mov_b32_e32 v4, v2
	v_mov_b32_e32 v5, v2
	v_mov_b32_e32 v6, v2
	v_mov_b32_e32 v7, v2
	v_mov_b32_e32 v8, v2
	v_mov_b32_e32 v9, v2
	v_mov_b32_e32 v10, v2
	v_mov_b32_e32 v11, v2
	v_mov_b32_e32 v12, v2
	v_mov_b32_e32 v13, v2
	v_mov_b32_e32 v14, v2
	v_mov_b32_e32 v15, v2
	v_mov_b32_e32 v16, v2
	v_mov_b32_e32 v17, v2
	v_mov_b32_e32 v18, v2
	v_mov_b32_e32 v19, v2
	v_mov_b32_e32 v20, v2
	v_mov_b32_e32 v21, v2
	v_mov_b32_e32 v22, v2
	v_mov_b32_e32 v23, v2
	v_mov_b32_e32 v24, v2
	v_mov_b32_e32 v25, v2
	v_mov_b32_e32 v26, v2
	v_mov_b32_e32 v27, v2
	v_mov_b32_e32 v28, v2
	v_mov_b32_e32 v29, v2
	v_mov_b32_e32 v30, v2
	v_mov_b32_e32 v31, v2
	v_mov_b32_e32 v32, v2
	v_mov_b32_e32 v33, v2
	v_mov_b32_e32 v34, v2
	v_mov_b32_e32 v35, v2
	v_mov_b32_e32 v36, v2
	v_mov_b32_e32 v37, v2
	v_mov_b32_e32 v38, v2
	v_mov_b32_e32 v39, v2
	v_mov_b32_e32 v40, v2
	v_mov_b32_e32 v41, v2
	v_mov_b32_e32 v42, v2
	v_mov_b32_e32 v43, v2
	v_mov_b32_e32 v44, v2
	v_mov_b32_e32 v45, v2
	v_mov_b32_e32 v46, v2
	v_mov_b32_e32 v47, v2
	v_mov_b32_e32 v48, v2
	v_mov_b32_e32 v49, v2
	v_mov_b32_e32 v50, v2
	v_mov_b32_e32 v51, v2
	v_mov_b32_e32 v52, v2
	v_mov_b32_e32 v53, v2
	v_mov_b32_e32 v54, v2
	v_mov_b32_e32 v55, v2
	v_mov_b32_e32 v56, v2
	v_mov_b32_e32 v57, v2
	v_mov_b32_e32 v58, v2
	v_mov_b32_e32 v59, v2
	v_mov_b32_e32 v60, v2
	v_mov_b32_e32 v61, v2
	v_mov_b32_e32 v62, v2
	v_mov_b32_e32 v63, v2
	v_mov_b32_e32 v64, v2
	v_mov_b32_e32 v65, v2
	v_mov_b32_e32 v66, v2
	v_mov_b32_e32 v67, v2
	v_mov_b32_e32 v68, v2
	v_mov_b32_e32 v69, v2
	s_waitcnt vmcnt(18)
	v_mov_b32_e32 v70, v2
	v_mov_b32_e32 v71, v2
	v_mov_b32_e32 v72, v2
	v_mov_b32_e32 v73, v2
	s_waitcnt vmcnt(17)
	v_mov_b32_e32 v74, v2
	v_mov_b32_e32 v75, v2
	v_mov_b32_e32 v76, v2
	v_mov_b32_e32 v77, v2
	s_waitcnt vmcnt(16)
	v_mov_b32_e32 v78, v2
	v_mov_b32_e32 v79, v2
	v_mov_b32_e32 v80, v2
	v_mov_b32_e32 v81, v2
	s_waitcnt vmcnt(15)
	v_mov_b32_e32 v82, v2
	v_mov_b32_e32 v83, v2
	v_mov_b32_e32 v84, v2
	v_mov_b32_e32 v85, v2
	s_waitcnt vmcnt(14)
	v_mov_b32_e32 v86, v2
	v_mov_b32_e32 v87, v2
	v_mov_b32_e32 v88, v2
	v_mov_b32_e32 v89, v2
	v_mov_b32_e32 v90, v2
	v_mov_b32_e32 v91, v2
	v_mov_b32_e32 v92, v2
	v_mov_b32_e32 v93, v2
	s_waitcnt vmcnt(13)
	v_mov_b32_e32 v94, v2
	v_mov_b32_e32 v95, v2
	v_mov_b32_e32 v96, v2
	v_mov_b32_e32 v97, v2
	v_mov_b32_e32 v98, v2
	v_mov_b32_e32 v99, v2
	v_mov_b32_e32 v100, v2
	v_mov_b32_e32 v101, v2
	s_waitcnt vmcnt(12)
	v_mov_b32_e32 v102, v2
	v_mov_b32_e32 v103, v2
	v_mov_b32_e32 v104, v2
	v_mov_b32_e32 v105, v2
	v_mov_b32_e32 v106, v2
	v_mov_b32_e32 v107, v2
	v_mov_b32_e32 v108, v2
	v_mov_b32_e32 v109, v2
	v_mov_b32_e32 v110, v2
	v_mov_b32_e32 v111, v2
	v_mov_b32_e32 v112, v2
	v_mov_b32_e32 v113, v2
	v_mov_b32_e32 v114, v2
	v_mov_b32_e32 v115, v2
	v_mov_b32_e32 v116, v2
	v_mov_b32_e32 v117, v2
	v_mov_b32_e32 v118, v2
	v_mov_b32_e32 v119, v2
	v_mov_b32_e32 v120, v2
	v_mov_b32_e32 v121, v2
	v_mov_b32_e32 v122, v2
	v_mov_b32_e32 v123, v2
	v_mov_b32_e32 v124, v2
	v_mov_b32_e32 v125, v2
	v_mov_b32_e32 v126, v2
	v_mov_b32_e32 v127, v2
	v_mov_b32_e32 v128, v2
	v_mov_b32_e32 v129, v2
	v_lshrrev_b32_e32 v236, 3, v189
	v_mul_u32_u24_e32 v236, 0x1080, v236
	v_and_b32_e32 v208, 7, v189
	v_lshl_add_u32 v236, v208, 4, v236
; #define MFMA32(a, b, c) __builtin_amdgcn_mfma_f32_32x32x16_bf16((a), (b), (c), 0, 0, 0)
; #define GLOAD2(K0) { const int tl = otid(); LDA2(0, K0) LDA2(1, K0) LDA2(2, K0) LDA2(3, K0) LDB2(0, K0) LDB2(1, K0) LDB2(2, K0) LDB2(3, K0) LDB2(4, K0) LDB2(5, K0) LDB2(6, K0) LDB2(7, K0) }
; #define SSTORE2() { STA2(0) STA2(1) STA2(2) STA2(3) STB2(0) STB2(1) STB2(2) STB2(3) STB2(4) STB2(5) STB2(6) STB2(7) }
; template <class AF, class Epi>
; DI void gemm_tile2(AF af, const bf16* __restrict__ Bt, int ldb, int K, char* smem, int& n0ref, int nhalf, Epi epi) {
;     ...
;   for (int kt = 0; kt < nk; ++kt) {
;     __syncthreads();
;     SSTORE2();
;     __syncthreads();
;     if (kt + 1 < nk) GLOAD2((kt + 1) * 64);
; #pragma unroll
;     for (int ks = 0; ks < 4; ++ks) {
;       bf16x8 fa[2], fb[4];
; #pragma unroll
;       for (int mb = 0; mb < 2; ++mb) fa[mb] = *(const bf16x8*)(a_ + mb * 32 * 72 + ks * 16);
; #pragma unroll
;       for (int nb = 0; nb < 4; ++nb) fb[nb] = *(const bf16x8*)(b_ + nb * 32 * 72 + ks * 16);
; #pragma unroll
;       for (int mb = 0; mb < 2; ++mb)
; #pragma unroll
;         for (int nb = 0; nb < 4; ++nb) acc[mb][nb] = MFMA32(fa[mb], fb[nb], acc[mb][nb]);
;     }
.LBB0_172:
	s_barrier
	s_waitcnt vmcnt(11)
	ds_write_b128 v184, v[130:133]
	s_waitcnt vmcnt(10)
	ds_write_b128 v194, v[134:137]
	s_waitcnt vmcnt(9)
	ds_write_b128 v196, v[138:141]
	s_waitcnt vmcnt(8)
	ds_write_b128 v198, v[142:145]
	s_waitcnt vmcnt(7)
	ds_write_b128 v184, v[146:149] offset:18432
	s_waitcnt vmcnt(6)
	ds_write_b128 v194, v[150:153] offset:18432
	s_waitcnt vmcnt(5)
	ds_write_b128 v196, v[154:157] offset:18432
	s_waitcnt vmcnt(4)
	ds_write_b128 v198, v[158:161] offset:18432
	s_waitcnt vmcnt(3)
	ds_write_b128 v200, v[162:165] offset:18432
	s_waitcnt vmcnt(2)
	ds_write_b128 v202, v[166:169] offset:18432
	s_waitcnt vmcnt(1)
	ds_write_b128 v204, v[170:173] offset:18432
	s_waitcnt vmcnt(0)
	ds_write_b128 v206, v[174:177] offset:18432
	s_waitcnt lgkmcnt(0)
	s_barrier
	ds_read_b128 v[246:249], v182
	ds_read_b128 v[208:211], v183 offset:18432
	ds_read_b128 v[212:215], v183 offset:23040
	ds_read_b128 v[224:227], v183 offset:27648
	ds_read_b128 v[228:231], v183 offset:32256
	ds_read_b128 v[250:253], v182 offset:4608
	s_lshl_b32 s36, s26, 1
	s_add_u32 s36, s0, s36
	s_addc_u32 s37, s1, 0
	global_load_dwordx4 v[130:133], v236, s[36:37]
	s_add_u32 s36, s36, 0x21000
	s_addc_u32 s37, s37, 0
	global_load_dwordx4 v[134:137], v236, s[36:37]
	s_add_u32 s36, s36, 0x21000
	s_addc_u32 s37, s37, 0
	global_load_dwordx4 v[138:141], v236, s[36:37]
	s_add_u32 s36, s36, 0x21000
	s_addc_u32 s37, s37, 0
	global_load_dwordx4 v[142:145], v236, s[36:37]
	s_add_u32 s36, s10, s18
	s_addc_u32 s37, s11, s19
	global_load_dwordx4 v[146:149], v236, s[36:37]
	s_add_u32 s36, s36, 0x21000
	s_addc_u32 s37, s37, 0
	global_load_dwordx4 v[150:153], v236, s[36:37]
	s_add_u32 s36, s36, 0x21000
	s_addc_u32 s37, s37, 0
	global_load_dwordx4 v[154:157], v236, s[36:37]
	s_add_u32 s36, s36, 0x21000
	s_addc_u32 s37, s37, 0
	global_load_dwordx4 v[158:161], v236, s[36:37]
	s_add_u32 s36, s36, 0x21000
	s_addc_u32 s37, s37, 0
	global_load_dwordx4 v[162:165], v236, s[36:37]
	s_add_u32 s36, s36, 0x21000
	s_addc_u32 s37, s37, 0
	global_load_dwordx4 v[166:169], v236, s[36:37]
	s_add_u32 s36, s36, 0x21000
	s_addc_u32 s37, s37, 0
	global_load_dwordx4 v[170:173], v236, s[36:37]
	s_add_u32 s36, s36, 0x21000
	s_addc_u32 s37, s37, 0
	global_load_dwordx4 v[174:177], v236, s[36:37]
	s_add_u32 s18, s18, 0x80
	s_addc_u32 s19, s19, 0
	s_add_i32 s26, s26, 64
	s_waitcnt lgkmcnt(4)
	v_mfma_f32_32x32x16_bf16 v[114:129], v[246:249], v[208:211], v[114:129]
	s_waitcnt lgkmcnt(3)
	v_mfma_f32_32x32x16_bf16 v[98:113], v[246:249], v[212:215], v[98:113]
	s_waitcnt lgkmcnt(2)
	v_mfma_f32_32x32x16_bf16 v[82:97], v[246:249], v[224:227], v[82:97]
	s_waitcnt lgkmcnt(1)
	v_mfma_f32_32x32x16_bf16 v[66:81], v[246:249], v[228:231], v[66:81]
	ds_read_b128 v[246:249], v182 offset:32
	s_waitcnt lgkmcnt(1)
	v_mfma_f32_32x32x16_bf16 v[50:65], v[250:253], v[208:211], v[50:65]
	ds_read_b128 v[208:211], v183 offset:18464
	v_mfma_f32_32x32x16_bf16 v[34:49], v[250:253], v[212:215], v[34:49]
	ds_read_b128 v[212:215], v183 offset:23072
	v_mfma_f32_32x32x16_bf16 v[18:33], v[250:253], v[224:227], v[18:33]
	ds_read_b128 v[224:227], v183 offset:27680
	v_mfma_f32_32x32x16_bf16 v[2:17], v[250:253], v[228:231], v[2:17]
	ds_read_b128 v[228:231], v183 offset:32288
	ds_read_b128 v[250:253], v182 offset:4640
	s_waitcnt lgkmcnt(4)
	v_mfma_f32_32x32x16_bf16 v[114:129], v[246:249], v[208:211], v[114:129]
	s_waitcnt lgkmcnt(3)
	v_mfma_f32_32x32x16_bf16 v[98:113], v[246:249], v[212:215], v[98:113]
	s_waitcnt lgkmcnt(2)
	v_mfma_f32_32x32x16_bf16 v[82:97], v[246:249], v[224:227], v[82:97]
	s_waitcnt lgkmcnt(1)
	v_mfma_f32_32x32x16_bf16 v[66:81], v[246:249], v[228:231], v[66:81]
	ds_read_b128 v[246:249], v182 offset:64
	s_waitcnt lgkmcnt(1)
	v_mfma_f32_32x32x16_bf16 v[50:65], v[250:253], v[208:211], v[50:65]
	ds_read_b128 v[208:211], v183 offset:18496
	v_mfma_f32_32x32x16_bf16 v[34:49], v[250:253], v[212:215], v[34:49]
	ds_read_b128 v[212:215], v183 offset:23104
	v_mfma_f32_32x32x16_bf16 v[18:33], v[250:253], v[224:227], v[18:33]
	ds_read_b128 v[224:227], v183 offset:27712
	v_mfma_f32_32x32x16_bf16 v[2:17], v[250:253], v[228:231], v[2:17]
	ds_read_b128 v[228:231], v183 offset:32320
	ds_read_b128 v[250:253], v182 offset:4672
	s_waitcnt lgkmcnt(4)
	v_mfma_f32_32x32x16_bf16 v[114:129], v[246:249], v[208:211], v[114:129]
	s_waitcnt lgkmcnt(3)
	v_mfma_f32_32x32x16_bf16 v[98:113], v[246:249], v[212:215], v[98:113]
	s_waitcnt lgkmcnt(2)
	v_mfma_f32_32x32x16_bf16 v[82:97], v[246:249], v[224:227], v[82:97]
	s_waitcnt lgkmcnt(1)
	v_mfma_f32_32x32x16_bf16 v[66:81], v[246:249], v[228:231], v[66:81]
	ds_read_b128 v[246:249], v182 offset:96
	s_waitcnt lgkmcnt(1)
	v_mfma_f32_32x32x16_bf16 v[50:65], v[250:253], v[208:211], v[50:65]
	ds_read_b128 v[208:211], v183 offset:18528
	v_mfma_f32_32x32x16_bf16 v[34:49], v[250:253], v[212:215], v[34:49]
	ds_read_b128 v[212:215], v183 offset:23136
	v_mfma_f32_32x32x16_bf16 v[18:33], v[250:253], v[224:227], v[18:33]
	ds_read_b128 v[224:227], v183 offset:27744
	v_mfma_f32_32x32x16_bf16 v[2:17], v[250:253], v[228:231], v[2:17]
	ds_read_b128 v[228:231], v183 offset:32352
	ds_read_b128 v[250:253], v182 offset:4704
	s_waitcnt lgkmcnt(4)
	v_mfma_f32_32x32x16_bf16 v[114:129], v[246:249], v[208:211], v[114:129]
	s_waitcnt lgkmcnt(3)
	v_mfma_f32_32x32x16_bf16 v[98:113], v[246:249], v[212:215], v[98:113]
	s_waitcnt lgkmcnt(2)
	v_mfma_f32_32x32x16_bf16 v[82:97], v[246:249], v[224:227], v[82:97]
	s_waitcnt lgkmcnt(1)
	v_mfma_f32_32x32x16_bf16 v[66:81], v[246:249], v[228:231], v[66:81]
	s_waitcnt lgkmcnt(0)
	v_mfma_f32_32x32x16_bf16 v[50:65], v[250:253], v[208:211], v[50:65]
	v_mfma_f32_32x32x16_bf16 v[34:49], v[250:253], v[212:215], v[34:49]
	v_mfma_f32_32x32x16_bf16 v[18:33], v[250:253], v[224:227], v[18:33]
	v_mfma_f32_32x32x16_bf16 v[2:17], v[250:253], v[228:231], v[2:17]
	s_cmpk_eq_i32 s18, 0xf80
	s_cbranch_scc0 .LBB0_172
; #define MFMA32(a, b, c) __builtin_amdgcn_mfma_f32_32x32x16_bf16((a), (b), (c), 0, 0, 0)
; #define GLOAD2(K0) { const int tl = otid(); LDA2(0, K0) LDA2(1, K0) LDA2(2, K0) LDA2(3, K0) LDB2(0, K0) LDB2(1, K0) LDB2(2, K0) LDB2(3, K0) LDB2(4, K0) LDB2(5, K0) LDB2(6, K0) LDB2(7, K0) }
; #define SSTORE2() { STA2(0) STA2(1) STA2(2) STA2(3) STB2(0) STB2(1) STB2(2) STB2(3) STB2(4) STB2(5) STB2(6) STB2(7) }
; template <class AF, class Epi>
; DI void gemm_tile2(AF af, const bf16* __restrict__ Bt, int ldb, int K, char* smem, int& n0ref, int nhalf, Epi epi) {
;     ...
;   for (int kt = 0; kt < nk; ++kt) {
;     __syncthreads();
;     SSTORE2();
;     __syncthreads();
;     if (kt + 1 < nk) GLOAD2((kt + 1) * 64);
; #pragma unroll
;     for (int ks = 0; ks < 4; ++ks) {
;       bf16x8 fa[2], fb[4];
; #pragma unroll
;       for (int mb = 0; mb < 2; ++mb) fa[mb] = *(const bf16x8*)(a_ + mb * 32 * 72 + ks * 16);
; #pragma unroll
;       for (int nb = 0; nb < 4; ++nb) fb[nb] = *(const bf16x8*)(b_ + nb * 32 * 72 + ks * 16);
; #pragma unroll
;       for (int mb = 0; mb < 2; ++mb)
; #pragma unroll
;         for (int nb = 0; nb < 4; ++nb) acc[mb][nb] = MFMA32(fa[mb], fb[nb], acc[mb][nb]);
;     }
;   }
;     ...
;   float* Cs = (float*)smem;
; #pragma unroll
;   for (int hf = 0; hf < 2; ++hf) {
;     if (hf < nhalf) {
;       __syncthreads();
;       if (wn == hf) {
	v_add_u32_e32 v208, 0x100, v189
	v_add_u32_e32 v209, 0x200, v189
	v_add_u32_e32 v210, 0x300, v189
	v_or_b32_e32 v211, 0x400, v189
	v_add_u32_e32 v212, 0x500, v189
	v_mov_b32_e32 v213, 0x12400
	v_mov_b32_e32 v214, 0x12404
	v_mov_b32_e32 v215, 0x461c4000
	v_mov_b32_e32 v224, 0x7f800000
	v_mov_b32_e32 v225, 0xffffffc0
	v_mov_b32_e32 v226, 0xffffffe0
	v_mov_b32_e32 v227, 0x7fc00000
	v_mbcnt_lo_u32_b32 v228, -1, 0
	v_mbcnt_hi_u32_b32 v228, -1, v228
	v_mov_b32_e32 v229, 0x3ecc95a3
	v_mov_b32_e32 v230, 0xf149f2ca
	v_mov_b32_e32 v231, 0x12000
	v_mov_b32_e32 v236, 0x31f
	s_barrier
	s_waitcnt vmcnt(11)
	ds_write_b128 v184, v[130:133]
	s_waitcnt vmcnt(10)
	ds_write_b128 v194, v[134:137]
	s_waitcnt vmcnt(9)
	ds_write_b128 v196, v[138:141]
	s_waitcnt vmcnt(8)
	ds_write_b128 v198, v[142:145]
	s_waitcnt vmcnt(7)
	ds_write_b128 v184, v[146:149] offset:18432
	s_waitcnt vmcnt(6)
	ds_write_b128 v194, v[150:153] offset:18432
	s_waitcnt vmcnt(5)
	ds_write_b128 v196, v[154:157] offset:18432
	s_waitcnt vmcnt(4)
	ds_write_b128 v198, v[158:161] offset:18432
	s_waitcnt vmcnt(3)
	ds_write_b128 v200, v[162:165] offset:18432
	s_waitcnt vmcnt(2)
	ds_write_b128 v202, v[166:169] offset:18432
	s_waitcnt vmcnt(1)
	ds_write_b128 v204, v[170:173] offset:18432
	s_waitcnt vmcnt(0)
	ds_write_b128 v206, v[174:177] offset:18432
	s_waitcnt lgkmcnt(0)
	s_barrier
	ds_read_b128 v[130:133], v182
	ds_read_b128 v[134:137], v183 offset:18432
	ds_read_b128 v[138:141], v183 offset:18464
	ds_read_b128 v[142:145], v182 offset:32
	ds_read_b128 v[146:149], v183 offset:23040
	ds_read_b128 v[150:153], v183 offset:23072
	ds_read_b128 v[154:157], v183 offset:27648
	ds_read_b128 v[158:161], v183 offset:27680
	ds_read_b128 v[162:165], v183 offset:32256
	ds_read_b128 v[166:169], v183 offset:32288
	s_waitcnt lgkmcnt(8)
	v_mfma_f32_32x32x16_bf16 v[114:129], v[130:133], v[134:137], v[114:129]
	v_cmp_ne_u32_e64 s[18:19], 0, v241
	v_cmp_eq_u32_e32 vcc, 0, v241
	s_waitcnt lgkmcnt(5)
	v_mfma_f32_32x32x16_bf16 v[98:113], v[130:133], v[146:149], v[98:113]
	s_waitcnt lgkmcnt(3)
	v_mfma_f32_32x32x16_bf16 v[82:97], v[130:133], v[154:157], v[82:97]
	s_waitcnt lgkmcnt(1)
	v_mfma_f32_32x32x16_bf16 v[66:81], v[130:133], v[162:165], v[66:81]
	ds_read_b128 v[130:133], v182 offset:4608
	ds_read_b128 v[170:173], v182 offset:4640
	s_waitcnt lgkmcnt(1)
	v_mfma_f32_32x32x16_bf16 v[50:65], v[130:133], v[134:137], v[50:65]
	v_mfma_f32_32x32x16_bf16 v[34:49], v[130:133], v[146:149], v[34:49]
	v_mfma_f32_32x32x16_bf16 v[18:33], v[130:133], v[154:157], v[18:33]
	v_mfma_f32_32x32x16_bf16 v[2:17], v[130:133], v[162:165], v[2:17]
	v_mfma_f32_32x32x16_bf16 v[114:129], v[142:145], v[138:141], v[114:129]
	v_mfma_f32_32x32x16_bf16 v[98:113], v[142:145], v[150:153], v[98:113]
	v_mfma_f32_32x32x16_bf16 v[82:97], v[142:145], v[158:161], v[82:97]
	v_mfma_f32_32x32x16_bf16 v[66:81], v[142:145], v[166:169], v[66:81]
	s_waitcnt lgkmcnt(0)
	v_mfma_f32_32x32x16_bf16 v[50:65], v[170:173], v[138:141], v[50:65]
	ds_read_b128 v[130:133], v182 offset:64
	ds_read_b128 v[134:137], v183 offset:18496
	ds_read_b128 v[138:141], v182 offset:96
	ds_read_b128 v[142:145], v183 offset:18528
	v_mfma_f32_32x32x16_bf16 v[34:49], v[170:173], v[150:153], v[34:49]
	ds_read_b128 v[146:149], v183 offset:23104
	ds_read_b128 v[150:153], v183 offset:23136
	v_mfma_f32_32x32x16_bf16 v[18:33], v[170:173], v[158:161], v[18:33]
	ds_read_b128 v[154:157], v183 offset:27712
	ds_read_b128 v[158:161], v183 offset:27744
	v_mfma_f32_32x32x16_bf16 v[2:17], v[170:173], v[166:169], v[2:17]
	ds_read_b128 v[162:165], v183 offset:32320
	ds_read_b128 v[166:169], v183 offset:32352
	s_waitcnt lgkmcnt(8)
	v_mfma_f32_32x32x16_bf16 v[114:129], v[130:133], v[134:137], v[114:129]
	s_waitcnt lgkmcnt(5)
	v_mfma_f32_32x32x16_bf16 v[98:113], v[130:133], v[146:149], v[98:113]
	s_waitcnt lgkmcnt(3)
	v_mfma_f32_32x32x16_bf16 v[82:97], v[130:133], v[154:157], v[82:97]
	s_waitcnt lgkmcnt(1)
	v_mfma_f32_32x32x16_bf16 v[66:81], v[130:133], v[162:165], v[66:81]
	ds_read_b128 v[130:133], v182 offset:4672
	ds_read_b128 v[170:173], v182 offset:4704
	s_waitcnt lgkmcnt(0)
	s_barrier
	v_mfma_f32_32x32x16_bf16 v[50:65], v[130:133], v[134:137], v[50:65]
	v_mfma_f32_32x32x16_bf16 v[34:49], v[130:133], v[146:149], v[34:49]
	v_mfma_f32_32x32x16_bf16 v[18:33], v[130:133], v[154:157], v[18:33]
	v_mfma_f32_32x32x16_bf16 v[2:17], v[130:133], v[162:165], v[2:17]
	v_mfma_f32_32x32x16_bf16 v[114:129], v[138:141], v[142:145], v[114:129]
	v_mfma_f32_32x32x16_bf16 v[98:113], v[138:141], v[150:153], v[98:113]
	v_mfma_f32_32x32x16_bf16 v[82:97], v[138:141], v[158:161], v[82:97]
	v_mfma_f32_32x32x16_bf16 v[66:81], v[138:141], v[166:169], v[66:81]
	v_lshl_or_b32 v139, v242, 2, v244
	v_lshlrev_b32_e32 v138, 2, v243
	v_mfma_f32_32x32x16_bf16 v[50:65], v[170:173], v[142:145], v[50:65]
	v_mfma_f32_32x32x16_bf16 v[34:49], v[170:173], v[150:153], v[34:49]
	v_mfma_f32_32x32x16_bf16 v[18:33], v[170:173], v[158:161], v[18:33]
	v_mfma_f32_32x32x16_bf16 v[2:17], v[170:173], v[166:169], v[2:17]
	s_and_saveexec_b64 s[0:1], vcc
	s_cbranch_execz .LBB0_175
; DI int crow(int i, int h) { return (i & 3) + 8 * (i >> 2) + 4 * h; }
; template <class AF, class Epi>
; DI void gemm_tile2(AF af, const bf16* __restrict__ Bt, int ldb, int K, char* smem, int& n0ref, int nhalf, Epi epi) {
;     ...
;   float* Cs = (float*)smem;
; #pragma unroll
;   for (int hf = 0; hf < 2; ++hf) {
;     if (hf < nhalf) {
;       __syncthreads();
;       if (wn == hf) {
; #pragma unroll
;         for (int mb = 0; mb < 2; ++mb)
; #pragma unroll
;           for (int nb = 0; nb < 4; ++nb)
; #pragma unroll
;             for (int i = 0; i < 16; ++i) Cs[(wm * 64 + mb * 32 + crow(i, h)) * 132 + nb * 32 + r] = acc[mb][nb][i];
;       }
;       __syncthreads();
	v_mad_u64_u32 v[130:131], s[10:11], v139, s54, v[138:139]
	v_add_u32_e32 v0, 0x400, v130
	v_add_u32_e32 v131, 0x1000, v130
	v_add_u32_e32 v132, 0x1400, v130
	v_add_u32_e32 v133, 0x2000, v130
	v_add_u32_e32 v134, 0x2400, v130
	v_add_u32_e32 v136, 0x3200, v130
	ds_write2_b32 v130, v114, v98 offset1:32
	ds_write2_b32 v130, v115, v99 offset0:132 offset1:164
	ds_write2_b32 v0, v116, v100 offset0:8 offset1:40
	ds_write2_b32 v0, v117, v101 offset0:140 offset1:172
	ds_write2_b32 v131, v118, v102 offset0:32 offset1:64
	ds_write2_b32 v131, v119, v103 offset0:164 offset1:196
	ds_write2_b32 v132, v120, v104 offset0:40 offset1:72
	ds_write2_b32 v132, v121, v105 offset0:172 offset1:204
	ds_write2_b32 v133, v122, v106 offset0:64 offset1:96
	ds_write2_b32 v133, v123, v107 offset0:196 offset1:228
	ds_write2_b32 v134, v124, v108 offset0:72 offset1:104
	ds_write2_b32 v134, v125, v109 offset0:204 offset1:236
	v_add_u32_e32 v135, 0x3000, v130
	ds_write2_b32 v136, v127, v111 offset0:100 offset1:132
	v_add_u32_e32 v136, 0x3400, v130
	v_add_u32_e32 v137, 0x3600, v130
	ds_write2_b32 v135, v126, v110 offset0:96 offset1:128
	ds_write2_b32 v136, v128, v112 offset0:104 offset1:136
	ds_write2_b32 v137, v129, v113 offset0:108 offset1:140
	ds_write2_b32 v130, v82, v66 offset0:64 offset1:96
	ds_write2_b32 v130, v83, v67 offset0:196 offset1:228
	ds_write2_b32 v0, v84, v68 offset0:72 offset1:104
	ds_write2_b32 v0, v85, v69 offset0:204 offset1:236
	ds_write2_b32 v131, v86, v70 offset0:96 offset1:128
	v_add_u32_e32 v0, 0x1200, v130
	ds_write2_b32 v0, v87, v71 offset0:100 offset1:132
	ds_write2_b32 v132, v88, v72 offset0:104 offset1:136
	v_add_u32_e32 v0, 0x1600, v130
	ds_write2_b32 v0, v89, v73 offset0:108 offset1:140
	ds_write2_b32 v133, v90, v74 offset0:128 offset1:160
	ds_write2_b32 v134, v91, v75 offset0:4 offset1:36
	ds_write2_b32 v134, v92, v76 offset0:136 offset1:168
	v_add_u32_e32 v0, 0x2800, v130
	ds_write2_b32 v0, v93, v77 offset0:12 offset1:44
	ds_write2_b32 v135, v94, v78 offset0:160 offset1:192
	ds_write2_b32 v136, v95, v79 offset0:36 offset1:68
	ds_write2_b32 v136, v96, v80 offset0:168 offset1:200
	v_add_u32_e32 v0, 0x3800, v130
	ds_write2_b32 v0, v97, v81 offset0:44 offset1:76
	v_add_u32_e32 v0, 0x4000, v130
	v_add_u32_e32 v131, 0x4400, v130
	v_add_u32_e32 v133, 0x5000, v130
	ds_write2_b32 v0, v50, v34 offset0:128 offset1:160
	ds_write2_b32 v131, v51, v35 offset0:4 offset1:36
	ds_write2_b32 v131, v52, v36 offset0:136 offset1:168
	v_add_u32_e32 v132, 0x4800, v130
	ds_write2_b32 v133, v54, v38 offset0:160 offset1:192
	v_add_u32_e32 v133, 0x5400, v130
	v_add_u32_e32 v135, 0x6000, v130
	ds_write2_b32 v132, v53, v37 offset0:12 offset1:44
	ds_write2_b32 v133, v55, v39 offset0:36 offset1:68
	ds_write2_b32 v133, v56, v40 offset0:168 offset1:200
	v_add_u32_e32 v134, 0x5800, v130
	ds_write2_b32 v135, v58, v42 offset0:192 offset1:224
	v_add_u32_e32 v135, 0x6400, v130
	v_add_u32_e32 v137, 0x7200, v130
	v_add_u32_e32 v140, 0x7600, v130
	ds_write2_b32 v134, v57, v41 offset0:44 offset1:76
	ds_write2_b32 v135, v59, v43 offset0:68 offset1:100
	ds_write2_b32 v135, v60, v44 offset0:200 offset1:232
	v_add_u32_e32 v136, 0x6800, v130
	ds_write2_b32 v137, v62, v46 offset0:96 offset1:128
	v_add_u32_e32 v137, 0x7400, v130
	ds_write2_b32 v140, v64, v48 offset0:104 offset1:136
	v_add_u32_e32 v140, 0x7800, v130
	ds_write2_b32 v136, v61, v45 offset0:76 offset1:108
	ds_write2_b32 v137, v63, v47 offset0:100 offset1:132
	ds_write2_b32 v140, v65, v49 offset0:108 offset1:140
	ds_write2_b32 v0, v18, v2 offset0:192 offset1:224
	ds_write2_b32 v131, v19, v3 offset0:68 offset1:100
	ds_write2_b32 v131, v20, v4 offset0:200 offset1:232
	ds_write2_b32 v132, v21, v5 offset0:76 offset1:108
	v_add_u32_e32 v0, 0x5200, v130
	ds_write2_b32 v0, v22, v6 offset0:96 offset1:128
	ds_write2_b32 v133, v23, v7 offset0:100 offset1:132
	v_add_u32_e32 v0, 0x5600, v130
	ds_write2_b32 v0, v24, v8 offset0:104 offset1:136
	ds_write2_b32 v134, v25, v9 offset0:108 offset1:140
	ds_write2_b32 v135, v26, v10 offset1:32
	ds_write2_b32 v135, v27, v11 offset0:132 offset1:164
	ds_write2_b32 v136, v28, v12 offset0:8 offset1:40
	ds_write2_b32 v136, v29, v13 offset0:140 offset1:172
	ds_write2_b32 v137, v30, v14 offset0:32 offset1:64
	ds_write2_b32 v137, v31, v15 offset0:164 offset1:196
	ds_write2_b32 v140, v32, v16 offset0:40 offset1:72
	ds_write2_b32 v140, v33, v17 offset0:172 offset1:204

; #define MFMA32(a, b, c) __builtin_amdgcn_mfma_f32_32x32x16_bf16((a), (b), (c), 0, 0, 0)
; DI int crow(int i, int h) { return (i & 3) + 8 * (i >> 2) + 4 * h; }
;   DI float aux(int key) const { return (cuml[key] + cpre[key >> 7]) * LOG2E; }
;   DI float aux(int key) const { return __int_as_float(pos[key]); }
;   DI float score(float s, int, float, int t) const { return mine(t) ? s * sc + bfar : NEG; }
;   DI float aux(int key) const { return __int_as_float(pos[key]); }
; template <int DK, bool PV, class SF, class PH>
; DI void attn_tile(const bf16x8 (&qf)[DK / 16], f32x16 (&o)[4], float& m, float& l, const char* smem, SF sf, PH ph) {
;     ...
;   for (int kb = 0; kb < 2; ++kb) {
; #pragma unroll
;     for (int i = 0; i < 16; ++i) s[kb][i] = 0.f;
; #pragma unroll
;     for (int ks = 0; ks < DK / 16; ++ks) {
;       bf16x8 a = *(const bf16x8*)(Ks + (kb * 32 + r) * (DK + 8) + ks * 16 + h * 8);
;       s[kb] = MFMA32(a, qf[ks], s[kb]);
;     }
;   }
;   float mx = m;
; #pragma unroll
;   for (int kb = 0; kb < 2; ++kb)
; #pragma unroll
;     for (int i = 0; i < 16; ++i) {
;       int kl = kb * 32 + crow(i, h);
;       float v = sf(s[kb][i], kl, auxs[kl]);
;       s[kb][i] = v;
;       mx = fmaxf(mx, v);
;     }
;           DI float aux(int key) const { int n = key < 511 ? key : 510; return __int_as_float(pos[16 * n + 31]); }
;           DI float score(float s, int key, float ax, int) const {
;             bool valid = (16 * key + 31 <= tq) && key < 511;
;             int d = posq - __float_as_int(ax);
;             d = d < 0 ? 0 : (d > 799 ? 799 : d);
;             return valid ? s * sc + lutr[d] : NEG;
;           }
.LBB0_485:
	s_or_b64 exec, exec, s[10:11]
	s_waitcnt vmcnt(7)
	ds_write_b128 v38, v[2:5]
	s_waitcnt vmcnt(6)
	ds_write_b128 v39, v[6:9]
	s_waitcnt vmcnt(5)
	ds_write_b128 v40, v[10:13]
	s_waitcnt vmcnt(4)
	ds_write_b128 v41, v[14:17]
	s_waitcnt vmcnt(3)
	ds_write2_b64 v43, v[18:19], v[20:21] offset1:1
	s_waitcnt vmcnt(2)
	ds_write2_b64 v44, v[22:23], v[24:25] offset1:1
	s_waitcnt vmcnt(1)
	ds_write2_b64 v45, v[26:27], v[28:29] offset1:1
	s_waitcnt vmcnt(0)
	ds_write2_b64 v46, v[30:31], v[32:33] offset1:1
	s_and_saveexec_b64 s[10:11], vcc
	ds_write_b32 v35, v0 offset:43008
	s_or_b64 exec, exec, s[10:11]
	s_waitcnt lgkmcnt(0)
	s_barrier
	s_mov_b32 s10, 0
	s_nop 0
	v_add_u32_e32 v0, s10, v189
	v_bfe_u32 v48, v0, 5, 1
	v_and_b32_e32 v2, 31, v0
	v_lshlrev_b32_e32 v50, 4, v48
	v_mad_u32_u24 v0, v2, s73, v50
	ds_read_b128 v[2:5], v0
	ds_read_b128 v[6:9], v0 offset:32
	s_waitcnt lgkmcnt(1)
	v_mfma_f32_32x32x16_bf16 v[18:33], v[2:5], v[136:139], 0
	ds_read_b128 v[2:5], v0 offset:64
	ds_read_b128 v[52:55], v0 offset:8736
	v_lshl_add_u32 v49, v48, 6, s37
	s_waitcnt lgkmcnt(2)
	v_mfma_f32_32x32x16_bf16 v[18:33], v[6:9], v[112:115], v[18:33]
	s_waitcnt lgkmcnt(1)
	v_mfma_f32_32x32x16_bf16 v[18:33], v[2:5], v[116:119], v[18:33]
	ds_read_b128 v[2:5], v0 offset:96
	s_waitcnt lgkmcnt(0)
	v_mfma_f32_32x32x16_bf16 v[18:33], v[2:5], v[120:123], v[18:33]
	ds_read_b128 v[2:5], v0 offset:128
	s_waitcnt lgkmcnt(0)
	v_mfma_f32_32x32x16_bf16 v[18:33], v[2:5], v[124:127], v[18:33]
	ds_read_b128 v[2:5], v0 offset:160
	s_waitcnt lgkmcnt(0)
	v_mfma_f32_32x32x16_bf16 v[18:33], v[2:5], v[128:131], v[18:33]
	ds_read_b128 v[2:5], v0 offset:192
	s_waitcnt lgkmcnt(0)
	v_mfma_f32_32x32x16_bf16 v[18:33], v[2:5], v[132:135], v[18:33]
	ds_read_b128 v[2:5], v0 offset:224
	s_waitcnt lgkmcnt(0)
	v_mfma_f32_32x32x16_bf16 v[18:33], v[2:5], v[140:143], v[18:33]
	ds_read_b128 v[2:5], v0 offset:8704
	s_waitcnt lgkmcnt(0)
	v_mfma_f32_32x32x16_bf16 v[2:17], v[2:5], v[136:139], 0
	v_mfma_f32_32x32x16_bf16 v[2:17], v[52:55], v[112:115], v[2:17]
	ds_read_b128 v[52:55], v0 offset:8768
	s_waitcnt lgkmcnt(0)
	v_mfma_f32_32x32x16_bf16 v[2:17], v[52:55], v[116:119], v[2:17]
	ds_read_b128 v[52:55], v0 offset:8800
	s_waitcnt lgkmcnt(0)
	v_mfma_f32_32x32x16_bf16 v[2:17], v[52:55], v[120:123], v[2:17]
	ds_read_b128 v[52:55], v0 offset:8832
	s_waitcnt lgkmcnt(0)
	v_mfma_f32_32x32x16_bf16 v[2:17], v[52:55], v[124:127], v[2:17]
	ds_read_b128 v[52:55], v0 offset:8864
	s_waitcnt lgkmcnt(0)
	v_mfma_f32_32x32x16_bf16 v[2:17], v[52:55], v[128:131], v[2:17]
	ds_read_b128 v[52:55], v0 offset:8896
	s_waitcnt lgkmcnt(0)
	v_mfma_f32_32x32x16_bf16 v[2:17], v[52:55], v[132:135], v[2:17]
	ds_read_b128 v[52:55], v0 offset:8928
	v_lshlrev_b32_e32 v0, 2, v48
	v_lshl_add_u64 v[36:37], s[14:15], 0, v[0:1]
	v_add_u32_e32 v37, 0xfffffc50, v49
	v_cmp_le_i32_e64 s[10:11], v37, v150
	v_cmp_gt_u32_e64 s[12:13], s78, v36
	s_and_b64 s[12:13], s[12:13], s[10:11]
	s_waitcnt lgkmcnt(0)
	v_mfma_f32_32x32x16_bf16 v[2:17], v[52:55], v[140:143], v[2:17]
	v_mov_b32_e32 v37, 0xf149f2ca
	v_mov_b32_e32 v48, 0xf149f2ca
	v_and_b32_e32 v226, 32, v189
	v_lshrrev_b32_e32 v226, 1, v226
	ds_read_b32 v213, v226 offset:43008
	ds_read_b32 v214, v226 offset:43012
	ds_read_b32 v215, v226 offset:43016
	ds_read_b32 v216, v226 offset:43020
	ds_read_b32 v217, v226 offset:43040
	ds_read_b32 v218, v226 offset:43044
	ds_read_b32 v224, v226 offset:43048
	ds_read_b32 v225, v226 offset:43052
	s_waitcnt lgkmcnt(0)
	v_sub_u32_e32 v213, v162, v213
	v_med3_i32 v213, v213, 0, v236
	v_lshl_add_u32 v213, v213, 2, v163
	ds_read_b32 v213, v213 offset:43264
	v_sub_u32_e32 v214, v162, v214
	v_med3_i32 v214, v214, 0, v236
	v_lshl_add_u32 v214, v214, 2, v163
	ds_read_b32 v214, v214 offset:43264
	v_sub_u32_e32 v215, v162, v215
	v_med3_i32 v215, v215, 0, v236
	v_lshl_add_u32 v215, v215, 2, v163
	ds_read_b32 v215, v215 offset:43264
	v_sub_u32_e32 v216, v162, v216
	v_med3_i32 v216, v216, 0, v236
	v_lshl_add_u32 v216, v216, 2, v163
	ds_read_b32 v216, v216 offset:43264
	v_sub_u32_e32 v217, v162, v217
	v_med3_i32 v217, v217, 0, v236
	v_lshl_add_u32 v217, v217, 2, v163
	ds_read_b32 v217, v217 offset:43264
	v_sub_u32_e32 v218, v162, v218
	v_med3_i32 v218, v218, 0, v236
	v_lshl_add_u32 v218, v218, 2, v163
	ds_read_b32 v218, v218 offset:43264
	v_sub_u32_e32 v224, v162, v224
	v_med3_i32 v224, v224, 0, v236
	v_lshl_add_u32 v224, v224, 2, v163
	ds_read_b32 v224, v224 offset:43264
	v_sub_u32_e32 v225, v162, v225
	v_med3_i32 v225, v225, 0, v236
	v_lshl_add_u32 v225, v225, 2, v163
	ds_read_b32 v225, v225 offset:43264
	s_waitcnt lgkmcnt(0)
	v_fmac_f32_e32 v213, 0x3e0293ee, v18
	v_cndmask_b32_e64 v48, v48, v213, s[12:13]
.LBB0_489:
	v_add_u32_e32 v18, 1, v36
	v_add_u32_e32 v51, 0xfffffc60, v49
	v_cmp_le_i32_e64 s[10:11], v51, v150
	v_cmp_gt_u32_e64 s[12:13], s78, v18
	s_and_b64 s[12:13], s[12:13], s[10:11]
	v_fmac_f32_e32 v214, 0x3e0293ee, v19
	v_cndmask_b32_e64 v37, v37, v214, s[12:13]
.LBB0_491:
	v_add_u32_e32 v18, 2, v36
	v_add_u32_e32 v19, 0xfffffc70, v49
	v_cmp_le_i32_e64 s[10:11], v19, v150
	v_cmp_gt_u32_e64 s[12:13], s78, v18
	s_and_b64 s[12:13], s[12:13], s[10:11]
	v_mov_b32_e32 v18, 0xf149f2ca
	v_mov_b32_e32 v19, 0xf149f2ca
	v_fmac_f32_e32 v215, 0x3e0293ee, v20
	v_cndmask_b32_e64 v19, v19, v215, s[12:13]
.LBB0_493:
	v_add_u32_e32 v20, 3, v36
	v_add_u32_e32 v51, 0xfffffc80, v49
	v_cmp_le_i32_e64 s[10:11], v51, v150
	v_cmp_gt_u32_e64 s[12:13], s78, v20
	s_and_b64 s[12:13], s[12:13], s[10:11]
	v_fmac_f32_e32 v216, 0x3e0293ee, v21
	v_cndmask_b32_e64 v18, v18, v216, s[12:13]
; DI int crow(int i, int h) { return (i & 3) + 8 * (i >> 2) + 4 * h; }
;   DI float aux(int key) const { return (cuml[key] + cpre[key >> 7]) * LOG2E; }
;   DI float aux(int key) const { return __int_as_float(pos[key]); }
;   DI float score(float s, int, float, int t) const { return mine(t) ? s * sc + bfar : NEG; }
;   DI float aux(int key) const { return __int_as_float(pos[key]); }
; template <int DK, bool PV, class SF, class PH>
; DI void attn_tile(const bf16x8 (&qf)[DK / 16], f32x16 (&o)[4], float& m, float& l, const char* smem, SF sf, PH ph) {
;     ...
;   for (int kb = 0; kb < 2; ++kb)
; #pragma unroll
;     for (int i = 0; i < 16; ++i) {
;       int kl = kb * 32 + crow(i, h);
;       float v = sf(s[kb][i], kl, auxs[kl]);
;       s[kb][i] = v;
;       mx = fmaxf(mx, v);
;     }
;           DI float aux(int key) const { int n = key < 511 ? key : 510; return __int_as_float(pos[16 * n + 31]); }
;           DI float score(float s, int key, float ax, int) const {
;             bool valid = (16 * key + 31 <= tq) && key < 511;
;             int d = posq - __float_as_int(ax);
;             d = d < 0 ? 0 : (d > 799 ? 799 : d);
;             return valid ? s * sc + lutr[d] : NEG;
;           }
.LBB0_495:
	v_add_u32_e32 v20, 8, v36
	v_add_u32_e32 v21, 0xfffffcd0, v49
	v_cmp_le_i32_e64 s[10:11], v21, v150
	v_cmp_gt_u32_e64 s[12:13], s78, v20
	s_and_b64 s[12:13], s[12:13], s[10:11]
	v_mov_b32_e32 v20, 0xf149f2ca
	v_mov_b32_e32 v21, 0xf149f2ca
	v_fmac_f32_e32 v217, 0x3e0293ee, v22
	v_cndmask_b32_e64 v21, v21, v217, s[12:13]
.LBB0_497:
	v_add_u32_e32 v22, 9, v36
	v_add_u32_e32 v50, 0xfffffce0, v49
	v_cmp_le_i32_e64 s[10:11], v50, v150
	v_cmp_gt_u32_e64 s[12:13], s78, v22
	s_and_b64 s[12:13], s[12:13], s[10:11]
	v_lshlrev_b32_e32 v50, 2, v0
	v_fmac_f32_e32 v218, 0x3e0293ee, v23
	v_cndmask_b32_e64 v20, v20, v218, s[12:13]
.LBB0_499:
	v_add_u32_e32 v0, 10, v36
	v_add_u32_e32 v22, 0xfffffcf0, v49
	v_cmp_le_i32_e64 s[10:11], v22, v150
	v_cmp_gt_u32_e64 s[12:13], s78, v0
	s_and_b64 s[12:13], s[12:13], s[10:11]
	v_mov_b32_e32 v0, 0xf149f2ca
	v_mov_b32_e32 v22, 0xf149f2ca
	v_fmac_f32_e32 v224, 0x3e0293ee, v24
	v_cndmask_b32_e64 v22, v22, v224, s[12:13]
.LBB0_501:
	v_add_u32_e32 v23, 11, v36
	v_add_u32_e32 v24, 0xfffffd00, v49
	v_cmp_le_i32_e64 s[10:11], v24, v150
	v_cmp_gt_u32_e64 s[12:13], s78, v23
	s_and_b64 s[12:13], s[12:13], s[10:11]
	v_fmac_f32_e32 v225, 0x3e0293ee, v25
	v_cndmask_b32_e64 v0, v0, v225, s[12:13]
.LBB0_503:
	v_add_u32_e32 v23, 16, v36
	v_add_u32_e32 v24, 0xfffffd50, v49
	v_cmp_le_i32_e64 s[10:11], v24, v150
	v_cmp_gt_u32_e64 s[12:13], s78, v23
	s_and_b64 s[12:13], s[12:13], s[10:11]
	v_mov_b32_e32 v23, 0xf149f2ca
	v_mov_b32_e32 v24, 0xf149f2ca
	ds_read_b32 v213, v226 offset:43072
	ds_read_b32 v214, v226 offset:43076
	ds_read_b32 v215, v226 offset:43080
	ds_read_b32 v216, v226 offset:43084
	ds_read_b32 v217, v226 offset:43104
	ds_read_b32 v218, v226 offset:43108
	ds_read_b32 v224, v226 offset:43112
	ds_read_b32 v225, v226 offset:43116
	s_waitcnt lgkmcnt(0)
	v_sub_u32_e32 v213, v162, v213
	v_med3_i32 v213, v213, 0, v236
	v_lshl_add_u32 v213, v213, 2, v163
	ds_read_b32 v213, v213 offset:43264
	v_sub_u32_e32 v214, v162, v214
	v_med3_i32 v214, v214, 0, v236
	v_lshl_add_u32 v214, v214, 2, v163
	ds_read_b32 v214, v214 offset:43264
	v_sub_u32_e32 v215, v162, v215
	v_med3_i32 v215, v215, 0, v236
	v_lshl_add_u32 v215, v215, 2, v163
	ds_read_b32 v215, v215 offset:43264
	v_sub_u32_e32 v216, v162, v216
	v_med3_i32 v216, v216, 0, v236
	v_lshl_add_u32 v216, v216, 2, v163
	ds_read_b32 v216, v216 offset:43264
	v_sub_u32_e32 v217, v162, v217
	v_med3_i32 v217, v217, 0, v236
	v_lshl_add_u32 v217, v217, 2, v163
	ds_read_b32 v217, v217 offset:43264
	v_sub_u32_e32 v218, v162, v218
	v_med3_i32 v218, v218, 0, v236
	v_lshl_add_u32 v218, v218, 2, v163
	ds_read_b32 v218, v218 offset:43264
	v_sub_u32_e32 v224, v162, v224
	v_med3_i32 v224, v224, 0, v236
	v_lshl_add_u32 v224, v224, 2, v163
	ds_read_b32 v224, v224 offset:43264
	v_sub_u32_e32 v225, v162, v225
	v_med3_i32 v225, v225, 0, v236
	v_lshl_add_u32 v225, v225, 2, v163
	ds_read_b32 v225, v225 offset:43264
	s_waitcnt lgkmcnt(0)
	v_fmac_f32_e32 v213, 0x3e0293ee, v26
	v_cndmask_b32_e64 v24, v24, v213, s[12:13]
.LBB0_505:
	v_add_u32_e32 v25, 17, v36
	v_add_u32_e32 v26, 0xfffffd60, v49
	v_cmp_le_i32_e64 s[10:11], v26, v150
	v_cmp_gt_u32_e64 s[12:13], s78, v25
	s_and_b64 s[12:13], s[12:13], s[10:11]
	v_fmac_f32_e32 v214, 0x3e0293ee, v27
	v_cndmask_b32_e64 v23, v23, v214, s[12:13]
.LBB0_507:
	v_add_u32_e32 v25, 18, v36
	v_add_u32_e32 v26, 0xfffffd70, v49
	v_cmp_le_i32_e64 s[10:11], v26, v150
	v_cmp_gt_u32_e64 s[12:13], s78, v25
	s_and_b64 s[12:13], s[12:13], s[10:11]
	v_mov_b32_e32 v25, 0xf149f2ca
	v_mov_b32_e32 v26, 0xf149f2ca
	v_fmac_f32_e32 v215, 0x3e0293ee, v28
	v_cndmask_b32_e64 v26, v26, v215, s[12:13]
.LBB0_509:
	v_add_u32_e32 v27, 19, v36
	v_add_u32_e32 v28, 0xfffffd80, v49
	v_cmp_le_i32_e64 s[10:11], v28, v150
	v_cmp_gt_u32_e64 s[12:13], s78, v27
	s_and_b64 s[12:13], s[12:13], s[10:11]
	v_fmac_f32_e32 v216, 0x3e0293ee, v29
	v_cndmask_b32_e64 v25, v25, v216, s[12:13]
.LBB0_511:
	v_add_u32_e32 v27, 24, v36
	v_add_u32_e32 v28, 0xfffffdd0, v49
	v_cmp_le_i32_e64 s[10:11], v28, v150
	v_cmp_gt_u32_e64 s[12:13], s78, v27
	s_and_b64 s[12:13], s[12:13], s[10:11]
	v_mov_b32_e32 v27, 0xf149f2ca
	v_mov_b32_e32 v28, 0xf149f2ca
	v_fmac_f32_e32 v217, 0x3e0293ee, v30
	v_cndmask_b32_e64 v28, v28, v217, s[12:13]
.LBB0_513:
	v_add_u32_e32 v29, 25, v36
	v_add_u32_e32 v30, 0xfffffde0, v49
	v_cmp_le_i32_e64 s[10:11], v30, v150
	v_cmp_gt_u32_e64 s[12:13], s78, v29
	s_and_b64 s[12:13], s[12:13], s[10:11]
	v_fmac_f32_e32 v218, 0x3e0293ee, v31
	v_cndmask_b32_e64 v27, v27, v218, s[12:13]
.LBB0_515:
	v_add_u32_e32 v29, 26, v36
	v_add_u32_e32 v30, 0xfffffdf0, v49
	v_cmp_le_i32_e64 s[10:11], v30, v150
	v_cmp_gt_u32_e64 s[12:13], s78, v29
	s_and_b64 s[12:13], s[12:13], s[10:11]
	v_mov_b32_e32 v29, 0xf149f2ca
	v_mov_b32_e32 v30, 0xf149f2ca
	v_fmac_f32_e32 v224, 0x3e0293ee, v32
	v_cndmask_b32_e64 v30, v30, v224, s[12:13]
.LBB0_517:
	v_add_u32_e32 v31, 27, v36
	v_add_u32_e32 v32, 0xfffffe00, v49
	v_cmp_le_i32_e64 s[10:11], v32, v150
	v_cmp_gt_u32_e64 s[12:13], s78, v31
	s_and_b64 s[12:13], s[12:13], s[10:11]
	v_fmac_f32_e32 v225, 0x3e0293ee, v33
	v_cndmask_b32_e64 v29, v29, v225, s[12:13]
; DI int crow(int i, int h) { return (i & 3) + 8 * (i >> 2) + 4 * h; }
;   DI float aux(int key) const { return (cuml[key] + cpre[key >> 7]) * LOG2E; }
;   DI float aux(int key) const { return __int_as_float(pos[key]); }
;   DI float score(float s, int, float, int t) const { return mine(t) ? s * sc + bfar : NEG; }
;   DI float aux(int key) const { return __int_as_float(pos[key]); }
; template <int DK, bool PV, class SF, class PH>
; DI void attn_tile(const bf16x8 (&qf)[DK / 16], f32x16 (&o)[4], float& m, float& l, const char* smem, SF sf, PH ph) {
;     ...
;   for (int kb = 0; kb < 2; ++kb)
; #pragma unroll
;     for (int i = 0; i < 16; ++i) {
;       int kl = kb * 32 + crow(i, h);
;       float v = sf(s[kb][i], kl, auxs[kl]);
;       s[kb][i] = v;
;       mx = fmaxf(mx, v);
;     }
;           DI float aux(int key) const { int n = key < 511 ? key : 510; return __int_as_float(pos[16 * n + 31]); }
;           DI float score(float s, int key, float ax, int) const {
;             bool valid = (16 * key + 31 <= tq) && key < 511;
;             int d = posq - __float_as_int(ax);
;             d = d < 0 ? 0 : (d > 799 ? 799 : d);
;             return valid ? s * sc + lutr[d] : NEG;
;           }
.LBB0_519:
	v_add_u32_e32 v31, 32, v36
	v_add_u32_e32 v32, 0xfffffe50, v49
	v_cmp_le_i32_e64 s[10:11], v32, v150
	v_cmp_gt_u32_e64 s[12:13], s78, v31
	s_and_b64 s[12:13], s[12:13], s[10:11]
	v_mov_b32_e32 v31, 0xf149f2ca
	v_mov_b32_e32 v32, 0xf149f2ca
	ds_read_b32 v213, v226 offset:43136
	ds_read_b32 v214, v226 offset:43140
	ds_read_b32 v215, v226 offset:43144
	ds_read_b32 v216, v226 offset:43148
	ds_read_b32 v217, v226 offset:43168
	ds_read_b32 v218, v226 offset:43172
	ds_read_b32 v224, v226 offset:43176
	ds_read_b32 v225, v226 offset:43180
	s_waitcnt lgkmcnt(0)
	v_sub_u32_e32 v213, v162, v213
	v_med3_i32 v213, v213, 0, v236
	v_lshl_add_u32 v213, v213, 2, v163
	ds_read_b32 v213, v213 offset:43264
	v_sub_u32_e32 v214, v162, v214
	v_med3_i32 v214, v214, 0, v236
	v_lshl_add_u32 v214, v214, 2, v163
	ds_read_b32 v214, v214 offset:43264
	v_sub_u32_e32 v215, v162, v215
	v_med3_i32 v215, v215, 0, v236
	v_lshl_add_u32 v215, v215, 2, v163
	ds_read_b32 v215, v215 offset:43264
	v_sub_u32_e32 v216, v162, v216
	v_med3_i32 v216, v216, 0, v236
	v_lshl_add_u32 v216, v216, 2, v163
	ds_read_b32 v216, v216 offset:43264
	v_sub_u32_e32 v217, v162, v217
	v_med3_i32 v217, v217, 0, v236
	v_lshl_add_u32 v217, v217, 2, v163
	ds_read_b32 v217, v217 offset:43264
	v_sub_u32_e32 v218, v162, v218
	v_med3_i32 v218, v218, 0, v236
	v_lshl_add_u32 v218, v218, 2, v163
	ds_read_b32 v218, v218 offset:43264
	v_sub_u32_e32 v224, v162, v224
	v_med3_i32 v224, v224, 0, v236
	v_lshl_add_u32 v224, v224, 2, v163
	ds_read_b32 v224, v224 offset:43264
	v_sub_u32_e32 v225, v162, v225
	v_med3_i32 v225, v225, 0, v236
	v_lshl_add_u32 v225, v225, 2, v163
	ds_read_b32 v225, v225 offset:43264
	s_waitcnt lgkmcnt(0)
	v_fmac_f32_e32 v213, 0x3e0293ee, v2
	v_cndmask_b32_e64 v32, v32, v213, s[12:13]
.LBB0_521:
	v_add_u32_e32 v2, 33, v36
	v_add_u32_e32 v33, 0xfffffe60, v49
	v_cmp_le_i32_e64 s[10:11], v33, v150
	v_cmp_gt_u32_e64 s[12:13], s78, v2
	s_and_b64 s[12:13], s[12:13], s[10:11]
	v_fmac_f32_e32 v214, 0x3e0293ee, v3
	v_cndmask_b32_e64 v31, v31, v214, s[12:13]
.LBB0_523:
	v_add_u32_e32 v2, 34, v36
	v_add_u32_e32 v3, 0xfffffe70, v49
	v_cmp_le_i32_e64 s[10:11], v3, v150
	v_cmp_gt_u32_e64 s[12:13], s78, v2
	s_and_b64 s[12:13], s[12:13], s[10:11]
	v_mov_b32_e32 v2, 0xf149f2ca
	v_mov_b32_e32 v3, 0xf149f2ca
	v_fmac_f32_e32 v215, 0x3e0293ee, v4
	v_cndmask_b32_e64 v3, v3, v215, s[12:13]
.LBB0_525:
	v_add_u32_e32 v4, 35, v36
	v_add_u32_e32 v33, 0xfffffe80, v49
	v_cmp_le_i32_e64 s[10:11], v33, v150
	v_cmp_gt_u32_e64 s[12:13], s78, v4
	s_and_b64 s[12:13], s[12:13], s[10:11]
	v_fmac_f32_e32 v216, 0x3e0293ee, v5
	v_cndmask_b32_e64 v2, v2, v216, s[12:13]
.LBB0_527:
	v_add_u32_e32 v4, 40, v36
	v_add_u32_e32 v5, 0xfffffed0, v49
	v_cmp_le_i32_e64 s[10:11], v5, v150
	v_cmp_gt_u32_e64 s[12:13], s78, v4
	s_and_b64 s[12:13], s[12:13], s[10:11]
	v_mov_b32_e32 v4, 0xf149f2ca
	v_mov_b32_e32 v5, 0xf149f2ca
	v_fmac_f32_e32 v217, 0x3e0293ee, v6
	v_cndmask_b32_e64 v5, v5, v217, s[12:13]
.LBB0_529:
	v_add_u32_e32 v6, 41, v36
	v_add_u32_e32 v33, 0xfffffee0, v49
	v_cmp_le_i32_e64 s[10:11], v33, v150
	v_cmp_gt_u32_e64 s[12:13], s78, v6
	s_and_b64 s[12:13], s[12:13], s[10:11]
	v_fmac_f32_e32 v218, 0x3e0293ee, v7
	v_cndmask_b32_e64 v4, v4, v218, s[12:13]
.LBB0_531:
	v_add_u32_e32 v6, 42, v36
	v_add_u32_e32 v7, 0xfffffef0, v49
	v_cmp_le_i32_e64 s[10:11], v7, v150
	v_cmp_gt_u32_e64 s[12:13], s78, v6
	s_and_b64 s[12:13], s[12:13], s[10:11]
	v_mov_b32_e32 v6, 0xf149f2ca
	v_mov_b32_e32 v7, 0xf149f2ca
	v_fmac_f32_e32 v224, 0x3e0293ee, v8
	v_cndmask_b32_e64 v7, v7, v224, s[12:13]
.LBB0_533:
	v_add_u32_e32 v8, 43, v36
	v_add_u32_e32 v33, 0xffffff00, v49
	v_cmp_le_i32_e64 s[10:11], v33, v150
	v_cmp_gt_u32_e64 s[12:13], s78, v8
	s_and_b64 s[12:13], s[12:13], s[10:11]
	v_fmac_f32_e32 v225, 0x3e0293ee, v9
	v_cndmask_b32_e64 v6, v6, v225, s[12:13]
.LBB0_535:
	v_add_u32_e32 v8, 48, v36
	v_add_u32_e32 v9, 0xffffff50, v49
	v_cmp_le_i32_e64 s[10:11], v9, v150
	v_cmp_gt_u32_e64 s[12:13], s78, v8
	s_and_b64 s[12:13], s[12:13], s[10:11]
	v_mov_b32_e32 v8, 0xf149f2ca
	v_mov_b32_e32 v9, 0xf149f2ca
	ds_read_b32 v213, v226 offset:43200
	ds_read_b32 v214, v226 offset:43204
	ds_read_b32 v215, v226 offset:43208
	ds_read_b32 v216, v226 offset:43212
	ds_read_b32 v217, v226 offset:43232
	ds_read_b32 v218, v226 offset:43236
	ds_read_b32 v224, v226 offset:43240
	ds_read_b32 v225, v226 offset:43244
	s_waitcnt lgkmcnt(0)
	v_sub_u32_e32 v213, v162, v213
	v_med3_i32 v213, v213, 0, v236
	v_lshl_add_u32 v213, v213, 2, v163
	ds_read_b32 v213, v213 offset:43264
	v_sub_u32_e32 v214, v162, v214
	v_med3_i32 v214, v214, 0, v236
	v_lshl_add_u32 v214, v214, 2, v163
	ds_read_b32 v214, v214 offset:43264
	v_sub_u32_e32 v215, v162, v215
	v_med3_i32 v215, v215, 0, v236
	v_lshl_add_u32 v215, v215, 2, v163
	ds_read_b32 v215, v215 offset:43264
	v_sub_u32_e32 v216, v162, v216
	v_med3_i32 v216, v216, 0, v236
	v_lshl_add_u32 v216, v216, 2, v163
	ds_read_b32 v216, v216 offset:43264
	v_sub_u32_e32 v217, v162, v217
	v_med3_i32 v217, v217, 0, v236
	v_lshl_add_u32 v217, v217, 2, v163
	ds_read_b32 v217, v217 offset:43264
	v_sub_u32_e32 v218, v162, v218
	v_med3_i32 v218, v218, 0, v236
	v_lshl_add_u32 v218, v218, 2, v163
	ds_read_b32 v218, v218 offset:43264
	v_sub_u32_e32 v224, v162, v224
	v_med3_i32 v224, v224, 0, v236
	v_lshl_add_u32 v224, v224, 2, v163
	ds_read_b32 v224, v224 offset:43264
	v_sub_u32_e32 v225, v162, v225
	v_med3_i32 v225, v225, 0, v236
	v_lshl_add_u32 v225, v225, 2, v163
	ds_read_b32 v225, v225 offset:43264
	s_waitcnt lgkmcnt(0)
	v_fmac_f32_e32 v213, 0x3e0293ee, v10
	v_cndmask_b32_e64 v9, v9, v213, s[12:13]
; DI int crow(int i, int h) { return (i & 3) + 8 * (i >> 2) + 4 * h; }
; DI float ex2(float x) { return __builtin_amdgcn_exp2f(x); }
; template <int DK, bool PV, class SF, class PH>
; DI void attn_tile(const bf16x8 (&qf)[DK / 16], f32x16 (&o)[4], float& m, float& l, const char* smem, SF sf, PH ph) {
;     ...
;   for (int kb = 0; kb < 2; ++kb)
; #pragma unroll
;     for (int i = 0; i < 16; ++i) {
;       int kl = kb * 32 + crow(i, h);
;       float v = sf(s[kb][i], kl, auxs[kl]);
;       s[kb][i] = v;
;       mx = fmaxf(mx, v);
;     }
;   mx = fmaxf(mx, __shfl_xor(mx, 32));
;   float alpha = ex2(m - mx);
;   m = mx;
;   float psum = 0.f;
; #pragma unroll
;   for (int kb = 0; kb < 2; ++kb)
; #pragma unroll
;     for (int i = 0; i < 16; ++i) {
;       float pv = ex2(s[kb][i] - mx);
;       s[kb][i] = pv;
;       psum += pv;
;     }
;   l = l * alpha + psum;
.LBB0_537:
	v_add_u32_e32 v10, 49, v36
	v_add_u32_e32 v33, 0xffffff60, v49
	v_cmp_le_i32_e64 s[10:11], v33, v150
	v_cmp_gt_u32_e64 s[12:13], s78, v10
	s_and_b64 s[12:13], s[12:13], s[10:11]
	v_fmac_f32_e32 v214, 0x3e0293ee, v11
	v_cndmask_b32_e64 v8, v8, v214, s[12:13]
.LBB0_539:
	v_add_u32_e32 v10, 50, v36
	v_add_u32_e32 v11, 0xffffff70, v49
	v_cmp_le_i32_e64 s[10:11], v11, v150
	v_cmp_gt_u32_e64 s[12:13], s78, v10
	s_and_b64 s[12:13], s[12:13], s[10:11]
	v_mov_b32_e32 v10, 0xf149f2ca
	v_mov_b32_e32 v11, 0xf149f2ca
	v_fmac_f32_e32 v215, 0x3e0293ee, v12
	v_cndmask_b32_e64 v11, v11, v215, s[12:13]
.LBB0_541:
	v_add_u32_e32 v12, 51, v36
	v_add_u32_e32 v33, 0xffffff80, v49
	v_cmp_le_i32_e64 s[10:11], v33, v150
	v_cmp_gt_u32_e64 s[12:13], s78, v12
	s_and_b64 s[12:13], s[12:13], s[10:11]
	v_fmac_f32_e32 v216, 0x3e0293ee, v13
	v_cndmask_b32_e64 v10, v10, v216, s[12:13]
.LBB0_543:
	v_add_u32_e32 v12, 56, v36
	v_subrev_u32_e32 v13, 48, v49
	v_cmp_le_i32_e64 s[10:11], v13, v150
	v_cmp_gt_u32_e64 s[12:13], s78, v12
	s_and_b64 s[12:13], s[12:13], s[10:11]
	v_mov_b32_e32 v12, 0xf149f2ca
	v_mov_b32_e32 v13, 0xf149f2ca
	v_fmac_f32_e32 v217, 0x3e0293ee, v14
	v_cndmask_b32_e64 v13, v13, v217, s[12:13]
.LBB0_545:
	v_add_u32_e32 v14, 57, v36
	v_subrev_u32_e32 v33, 32, v49
	v_cmp_le_i32_e64 s[10:11], v33, v150
	v_cmp_gt_u32_e64 s[12:13], s78, v14
	s_and_b64 s[12:13], s[12:13], s[10:11]
	v_fmac_f32_e32 v218, 0x3e0293ee, v15
	v_cndmask_b32_e64 v12, v12, v218, s[12:13]
.LBB0_547:
	v_add_u32_e32 v14, 58, v36
	v_add_u32_e32 v15, -16, v49
	v_cmp_le_i32_e64 s[10:11], v15, v150
	v_cmp_gt_u32_e64 s[12:13], s78, v14
	s_and_b64 s[12:13], s[12:13], s[10:11]
	v_mov_b32_e32 v14, 0xf149f2ca
	v_mov_b32_e32 v33, 0xf149f2ca
	v_fmac_f32_e32 v224, 0x3e0293ee, v16
	v_cndmask_b32_e64 v33, v33, v224, s[12:13]
.LBB0_549:
	v_add_u32_e32 v15, 59, v36
	v_cmp_le_i32_e64 s[10:11], v49, v150
	v_cmp_gt_u32_e64 s[12:13], s78, v15
	s_and_b64 s[12:13], s[12:13], s[10:11]
	v_fmac_f32_e32 v225, 0x3e0293ee, v17
	v_cndmask_b32_e64 v14, v14, v225, s[12:13]
.LBB0_551:
	v_max3_f32 v15, v47, v48, v37
	v_max3_f32 v15, v15, v19, v18
	v_max3_f32 v15, v15, v21, v20
	v_max3_f32 v15, v15, v22, v0
	v_max3_f32 v15, v15, v24, v23
	v_max3_f32 v15, v15, v26, v25
	v_max3_f32 v15, v15, v28, v27
	v_max3_f32 v15, v15, v30, v29
	v_max3_f32 v15, v15, v32, v31
	v_max3_f32 v15, v15, v3, v2
	v_max3_f32 v15, v15, v5, v4
	v_max3_f32 v15, v15, v7, v6
	v_and_b32_e32 v17, 64, v228
	v_max3_f32 v15, v15, v9, v8
	v_xor_b32_e32 v16, 32, v228
	v_add_u32_e32 v161, 64, v17
	v_max3_f32 v15, v15, v11, v10
	v_cmp_lt_i32_e64 s[10:11], v16, v161
	v_max3_f32 v15, v15, v13, v12
	v_max3_f32 v15, v15, v33, v14
	v_cndmask_b32_e64 v16, v228, v16, s[10:11]
	v_lshlrev_b32_e32 v164, 2, v16
	ds_bpermute_b32 v16, v164, v15
	s_add_u32 s14, s14, 64
	s_addc_u32 s15, s15, 0
	s_addk_i32 s37, 0x400
	s_add_u32 s26, s26, 0x80
	s_waitcnt lgkmcnt(0)
	v_max_f32_e32 v16, v16, v16
	v_max_f32_e32 v15, v15, v16
	v_sub_f32_e32 v17, v48, v15
	v_exp_f32_e32 v17, v17
	v_sub_f32_e32 v36, v37, v15
	v_exp_f32_e32 v36, v36
	v_sub_f32_e32 v19, v19, v15
	v_exp_f32_e32 v19, v19
	v_sub_f32_e32 v18, v18, v15
	v_exp_f32_e32 v18, v18
	v_add_f32_e32 v17, 0, v17
	v_add_f32_e32 v17, v36, v17
	v_add_f32_e32 v17, v19, v17
	v_add_f32_e32 v17, v18, v17
	v_sub_f32_e32 v18, v21, v15
	v_exp_f32_e32 v18, v18
	v_sub_f32_e32 v19, v20, v15
	v_exp_f32_e32 v19, v19
	v_sub_f32_e32 v20, v22, v15
	v_exp_f32_e32 v20, v20
	v_sub_f32_e32 v0, v0, v15
	v_exp_f32_e32 v0, v0
	v_add_f32_e32 v17, v18, v17
	v_add_f32_e32 v17, v19, v17
	v_add_f32_e32 v17, v20, v17
	v_add_f32_e32 v0, v0, v17
	v_sub_f32_e32 v17, v24, v15
	v_exp_f32_e32 v17, v17
	v_sub_f32_e32 v18, v23, v15
	v_exp_f32_e32 v18, v18
	v_sub_f32_e32 v19, v26, v15
	v_exp_f32_e32 v19, v19
	v_sub_f32_e32 v20, v25, v15
	v_exp_f32_e32 v20, v20
	v_add_f32_e32 v0, v17, v0
	v_sub_f32_e32 v17, v28, v15
	v_add_f32_e32 v0, v18, v0
	v_exp_f32_e32 v17, v17
	v_sub_f32_e32 v18, v27, v15
	v_exp_f32_e32 v18, v18
	v_add_f32_e32 v0, v19, v0
	v_sub_f32_e32 v19, v30, v15
	v_add_f32_e32 v0, v20, v0
	v_exp_f32_e32 v19, v19
	v_sub_f32_e32 v20, v29, v15
	v_exp_f32_e32 v20, v20
	v_add_f32_e32 v0, v17, v0
	v_sub_f32_e32 v17, v32, v15
	v_add_f32_e32 v0, v18, v0
	v_exp_f32_e32 v17, v17
	v_sub_f32_e32 v18, v31, v15
	v_exp_f32_e32 v18, v18
	v_sub_f32_e32 v3, v3, v15
	v_add_f32_e32 v0, v19, v0
	v_exp_f32_e32 v3, v3
	v_sub_f32_e32 v2, v2, v15
	v_add_f32_e32 v0, v20, v0
	v_exp_f32_e32 v2, v2
	v_add_f32_e32 v0, v17, v0
	v_add_f32_e32 v0, v18, v0
	v_add_f32_e32 v0, v3, v0
	v_add_f32_e32 v0, v2, v0
	v_sub_f32_e32 v2, v5, v15
	v_exp_f32_e32 v2, v2
	v_sub_f32_e32 v3, v4, v15
	v_exp_f32_e32 v3, v3
	v_sub_f32_e32 v4, v7, v15
	v_exp_f32_e32 v4, v4
	v_sub_f32_e32 v5, v6, v15
	v_exp_f32_e32 v5, v5
	v_add_f32_e32 v0, v2, v0
	v_sub_f32_e32 v2, v9, v15
	v_add_f32_e32 v0, v3, v0
	v_exp_f32_e32 v2, v2
	v_sub_f32_e32 v3, v8, v15
	v_add_f32_e32 v0, v4, v0
	v_exp_f32_e32 v3, v3
	v_sub_f32_e32 v4, v11, v15
	v_add_f32_e32 v0, v5, v0
	v_exp_f32_e32 v4, v4
	v_sub_f32_e32 v5, v10, v15
	v_exp_f32_e32 v5, v5
	v_add_f32_e32 v0, v2, v0
	v_sub_f32_e32 v2, v13, v15
	v_add_f32_e32 v0, v3, v0
	v_exp_f32_e32 v2, v2
	v_sub_f32_e32 v3, v12, v15
	v_add_f32_e32 v0, v4, v0
	v_exp_f32_e32 v3, v3
	v_sub_f32_e32 v4, v33, v15
	v_add_f32_e32 v0, v5, v0
	v_exp_f32_e32 v4, v4
	v_sub_f32_e32 v5, v14, v15
	v_sub_f32_e32 v16, v47, v15
	v_exp_f32_e32 v5, v5
	v_add_f32_e32 v0, v2, v0
	v_exp_f32_e32 v2, v16
	v_add_f32_e32 v0, v3, v0
	v_add_f32_e32 v0, v4, v0
	v_add_f32_e32 v0, v5, v0
	s_addc_u32 s27, s27, 0
	s_cmp_lg_u32 s36, s14
	v_fmac_f32_e32 v0, v42, v2
	s_cbranch_scc0 .LBB0_553
	v_mov_b32_e32 v42, v0
	v_mov_b32_e32 v47, v15
	s_branch .LBB0_483

; #define MFMA32(a, b, c) __builtin_amdgcn_mfma_f32_32x32x16_bf16((a), (b), (c), 0, 0, 0)
; DI int crow(int i, int h) { return (i & 3) + 8 * (i >> 2) + 4 * h; }
;   DI float aux(int key) const { return (cuml[key] + cpre[key >> 7]) * LOG2E; }
;   DI float aux(int key) const { return __int_as_float(pos[key]); }
;   DI float score(float s, int, float, int t) const { return mine(t) ? s * sc + bfar : NEG; }
;   DI float aux(int key) const { return __int_as_float(pos[key]); }
; template <int DK, bool PV, class SF, class PH>
; DI void attn_tile(const bf16x8 (&qf)[DK / 16], f32x16 (&o)[4], float& m, float& l, const char* smem, SF sf, PH ph) {
;     ...
;   for (int kb = 0; kb < 2; ++kb) {
; #pragma unroll
;     for (int i = 0; i < 16; ++i) s[kb][i] = 0.f;
; #pragma unroll
;     for (int ks = 0; ks < DK / 16; ++ks) {
;       bf16x8 a = *(const bf16x8*)(Ks + (kb * 32 + r) * (DK + 8) + ks * 16 + h * 8);
;       s[kb] = MFMA32(a, qf[ks], s[kb]);
;     }
;   }
;   float mx = m;
; #pragma unroll
;   for (int kb = 0; kb < 2; ++kb)
; #pragma unroll
;     for (int i = 0; i < 16; ++i) {
;       int kl = kb * 32 + crow(i, h);
;       float v = sf(s[kb][i], kl, auxs[kl]);
;       s[kb][i] = v;
;       mx = fmaxf(mx, v);
;     }
;           DI float aux(int key) const { int n = key < 511 ? key : 510; return __int_as_float(pos[16 * n + 31]); }
;           DI float score(float s, int key, float ax, int) const {
;             bool valid = (16 * key + 31 <= tq) && key < 511;
;             int d = posq - __float_as_int(ax);
;             d = d < 0 ? 0 : (d > 799 ? 799 : d);
;             return valid ? s * sc + lutr[d] : NEG;
;           }
.LBB0_558:
	s_or_b64 exec, exec, s[12:13]
	s_waitcnt vmcnt(7)
	ds_write_b128 v158, v[2:5]
	s_waitcnt vmcnt(6)
	ds_write_b128 v159, v[6:9]
	s_waitcnt vmcnt(5)
	ds_write_b128 v169, v[10:13]
	s_waitcnt vmcnt(4)
	ds_write_b128 v170, v[80:83]
	s_waitcnt vmcnt(3)
	ds_write2_b64 v171, v[84:85], v[86:87] offset1:1
	s_waitcnt vmcnt(2)
	ds_write2_b64 v172, v[88:89], v[90:91] offset1:1
	s_waitcnt vmcnt(1)
	ds_write2_b64 v173, v[92:93], v[94:95] offset1:1
	s_waitcnt vmcnt(0)
	ds_write2_b64 v174, v[96:97], v[98:99] offset1:1
	s_and_saveexec_b64 s[12:13], s[10:11]
	ds_write_b32 v149, v0 offset:43008
	s_or_b64 exec, exec, s[12:13]
	s_waitcnt lgkmcnt(0)
	s_barrier
	s_mov_b32 s12, 0
	v_mov_b32_e32 v7, 0xf149f2ca
	v_add_u32_e32 v0, s12, v189
	v_bfe_u32 v5, v0, 5, 1
	v_and_b32_e32 v4, 31, v0
	v_lshlrev_b32_e32 v9, 4, v5
	v_mad_u32_u24 v0, v4, s73, v9
	ds_read_b128 v[10:13], v0
	ds_read_b128 v[80:83], v0 offset:32
	s_waitcnt lgkmcnt(1)
	v_mfma_f32_32x32x16_bf16 v[96:111], v[10:13], v[136:139], 0
	ds_read_b128 v[10:13], v0 offset:64
	v_mov_b32_e32 v8, 0xf149f2ca
	s_waitcnt lgkmcnt(1)
	v_mfma_f32_32x32x16_bf16 v[96:111], v[80:83], v[112:115], v[96:111]
	s_waitcnt lgkmcnt(0)
	v_mfma_f32_32x32x16_bf16 v[96:111], v[10:13], v[116:119], v[96:111]
	ds_read_b128 v[10:13], v0 offset:96
	s_waitcnt lgkmcnt(0)
	v_mfma_f32_32x32x16_bf16 v[96:111], v[10:13], v[120:123], v[96:111]
	ds_read_b128 v[10:13], v0 offset:128
	s_waitcnt lgkmcnt(0)
	v_mfma_f32_32x32x16_bf16 v[96:111], v[10:13], v[124:127], v[96:111]
	ds_read_b128 v[10:13], v0 offset:160
	s_waitcnt lgkmcnt(0)
	v_mfma_f32_32x32x16_bf16 v[96:111], v[10:13], v[128:131], v[96:111]
	ds_read_b128 v[10:13], v0 offset:192
	s_waitcnt lgkmcnt(0)
	v_mfma_f32_32x32x16_bf16 v[96:111], v[10:13], v[132:135], v[96:111]
	ds_read_b128 v[10:13], v0 offset:224
	s_waitcnt lgkmcnt(0)
	v_mfma_f32_32x32x16_bf16 v[96:111], v[10:13], v[140:143], v[96:111]
	ds_read_b128 v[10:13], v0 offset:8704
	s_waitcnt lgkmcnt(0)
	v_mfma_f32_32x32x16_bf16 v[80:95], v[10:13], v[136:139], 0
	ds_read_b128 v[10:13], v0 offset:8736
	s_waitcnt lgkmcnt(0)
	v_mfma_f32_32x32x16_bf16 v[80:95], v[10:13], v[112:115], v[80:95]
	ds_read_b128 v[10:13], v0 offset:8768
	s_waitcnt lgkmcnt(0)
	v_mfma_f32_32x32x16_bf16 v[80:95], v[10:13], v[116:119], v[80:95]
	ds_read_b128 v[10:13], v0 offset:8800
	s_waitcnt lgkmcnt(0)
	v_mfma_f32_32x32x16_bf16 v[80:95], v[10:13], v[120:123], v[80:95]
	ds_read_b128 v[10:13], v0 offset:8832
	s_waitcnt lgkmcnt(0)
	v_mfma_f32_32x32x16_bf16 v[80:95], v[10:13], v[124:127], v[80:95]
	ds_read_b128 v[10:13], v0 offset:8864
	s_waitcnt lgkmcnt(0)
	v_mfma_f32_32x32x16_bf16 v[80:95], v[10:13], v[128:131], v[80:95]
	ds_read_b128 v[10:13], v0 offset:8896
	s_waitcnt lgkmcnt(0)
	v_mfma_f32_32x32x16_bf16 v[80:95], v[10:13], v[132:135], v[80:95]
	ds_read_b128 v[10:13], v0 offset:8928
	v_lshlrev_b32_e32 v0, 2, v5
	v_lshl_add_u64 v[2:3], s[26:27], 0, v[0:1]
	v_lshl_add_u32 v3, v5, 6, s36
	v_add_u32_e32 v5, 0xfffffc50, v3
	v_cmp_le_i32_e32 vcc, v5, v150
	v_cmp_gt_u32_e64 s[12:13], s78, v2
	s_waitcnt lgkmcnt(0)
	v_mfma_f32_32x32x16_bf16 v[80:95], v[10:13], v[140:143], v[80:95]
	s_and_b64 s[44:45], s[12:13], vcc
	v_and_b32_e32 v226, 32, v189
	v_lshrrev_b32_e32 v226, 1, v226
	ds_read_b32 v213, v226 offset:43008
	ds_read_b32 v214, v226 offset:43012
	ds_read_b32 v215, v226 offset:43016
	ds_read_b32 v216, v226 offset:43020
	ds_read_b32 v217, v226 offset:43040
	ds_read_b32 v218, v226 offset:43044
	ds_read_b32 v224, v226 offset:43048
	ds_read_b32 v225, v226 offset:43052
	s_waitcnt lgkmcnt(0)
	v_sub_u32_e32 v213, v162, v213
	v_med3_i32 v213, v213, 0, v236
	v_lshl_add_u32 v213, v213, 2, v163
	ds_read_b32 v213, v213 offset:43264
	v_sub_u32_e32 v214, v162, v214
	v_med3_i32 v214, v214, 0, v236
	v_lshl_add_u32 v214, v214, 2, v163
	ds_read_b32 v214, v214 offset:43264
	v_sub_u32_e32 v215, v162, v215
	v_med3_i32 v215, v215, 0, v236
	v_lshl_add_u32 v215, v215, 2, v163
	ds_read_b32 v215, v215 offset:43264
	v_sub_u32_e32 v216, v162, v216
	v_med3_i32 v216, v216, 0, v236
	v_lshl_add_u32 v216, v216, 2, v163
	ds_read_b32 v216, v216 offset:43264
	v_sub_u32_e32 v217, v162, v217
	v_med3_i32 v217, v217, 0, v236
	v_lshl_add_u32 v217, v217, 2, v163
	ds_read_b32 v217, v217 offset:43264
	v_sub_u32_e32 v218, v162, v218
	v_med3_i32 v218, v218, 0, v236
	v_lshl_add_u32 v218, v218, 2, v163
	ds_read_b32 v218, v218 offset:43264
	v_sub_u32_e32 v224, v162, v224
	v_med3_i32 v224, v224, 0, v236
	v_lshl_add_u32 v224, v224, 2, v163
	ds_read_b32 v224, v224 offset:43264
	v_sub_u32_e32 v225, v162, v225
	v_med3_i32 v225, v225, 0, v236
	v_lshl_add_u32 v225, v225, 2, v163
	ds_read_b32 v225, v225 offset:43264
	s_waitcnt lgkmcnt(0)
	v_fmac_f32_e32 v213, 0x3e0293ee, v96
	v_cndmask_b32_e64 v8, v8, v213, s[44:45]
.LBB0_562:
	v_add_u32_e32 v5, 1, v2
	v_add_u32_e32 v6, 0xfffffc60, v3
	v_cmp_le_i32_e32 vcc, v6, v150
	v_cmp_gt_u32_e64 s[12:13], s78, v5
	s_and_b64 s[44:45], s[12:13], vcc
	v_fmac_f32_e32 v214, 0x3e0293ee, v97
	v_cndmask_b32_e64 v7, v7, v214, s[44:45]
.LBB0_564:
	v_add_u32_e32 v5, 2, v2
	v_add_u32_e32 v6, 0xfffffc70, v3
	v_cmp_le_i32_e32 vcc, v6, v150
	v_cmp_gt_u32_e64 s[12:13], s78, v5
	s_and_b64 s[44:45], s[12:13], vcc
	v_mov_b32_e32 v13, 0xf149f2ca
	v_mov_b32_e32 v14, 0xf149f2ca
	v_fmac_f32_e32 v215, 0x3e0293ee, v98
	v_cndmask_b32_e64 v14, v14, v215, s[44:45]
.LBB0_566:
	v_add_u32_e32 v5, 3, v2
	v_add_u32_e32 v6, 0xfffffc80, v3
	v_cmp_le_i32_e32 vcc, v6, v150
	v_cmp_gt_u32_e64 s[12:13], s78, v5
	s_and_b64 s[44:45], s[12:13], vcc
	v_fmac_f32_e32 v216, 0x3e0293ee, v99
	v_cndmask_b32_e64 v13, v13, v216, s[44:45]
; DI int crow(int i, int h) { return (i & 3) + 8 * (i >> 2) + 4 * h; }
;   DI float score(float s, int, float, int t) const { return mine(t) ? s * sc + bfar : NEG; }
; template <int DK, bool PV, class SF, class PH>
; DI void attn_tile(const bf16x8 (&qf)[DK / 16], f32x16 (&o)[4], float& m, float& l, const char* smem, SF sf, PH ph) {
;     ...
;   for (int kb = 0; kb < 2; ++kb)
; #pragma unroll
;     for (int i = 0; i < 16; ++i) {
;       int kl = kb * 32 + crow(i, h);
;       float v = sf(s[kb][i], kl, auxs[kl]);
;       s[kb][i] = v;
;       mx = fmaxf(mx, v);
;     }
;           DI float score(float s, int key, float ax, int) const {
;             bool valid = (16 * key + 31 <= tq) && key < 511;
;             int d = posq - __float_as_int(ax);
;             d = d < 0 ? 0 : (d > 799 ? 799 : d);
;             return valid ? s * sc + lutr[d] : NEG;
;           }
.LBB0_568:
	v_add_u32_e32 v5, 8, v2
	v_add_u32_e32 v6, 0xfffffcd0, v3
	v_cmp_le_i32_e32 vcc, v6, v150
	v_cmp_gt_u32_e64 s[12:13], s78, v5
	s_and_b64 s[44:45], s[12:13], vcc
	v_mov_b32_e32 v5, 0xf149f2ca
	v_mov_b32_e32 v6, 0xf149f2ca
	v_fmac_f32_e32 v217, 0x3e0293ee, v100
	v_cndmask_b32_e64 v6, v6, v217, s[44:45]
.LBB0_570:
	v_add_u32_e32 v9, 9, v2
	v_add_u32_e32 v10, 0xfffffce0, v3
	v_cmp_le_i32_e32 vcc, v10, v150
	v_cmp_gt_u32_e64 s[12:13], s78, v9
	s_and_b64 s[44:45], s[12:13], vcc
	v_lshlrev_b32_e32 v176, 2, v0
	v_fmac_f32_e32 v218, 0x3e0293ee, v101
	v_cndmask_b32_e64 v5, v5, v218, s[44:45]
.LBB0_572:
	v_add_u32_e32 v9, 10, v2
	v_add_u32_e32 v10, 0xfffffcf0, v3
	v_cmp_le_i32_e32 vcc, v10, v150
	v_cmp_gt_u32_e64 s[12:13], s78, v9
	s_and_b64 s[44:45], s[12:13], vcc
	v_mov_b32_e32 v10, 0xf149f2ca
	v_mov_b32_e32 v9, 0xf149f2ca
	v_fmac_f32_e32 v224, 0x3e0293ee, v102
	v_cndmask_b32_e64 v9, v9, v224, s[44:45]
.LBB0_574:
	v_add_u32_e32 v11, 11, v2
	v_add_u32_e32 v12, 0xfffffd00, v3
	v_cmp_le_i32_e32 vcc, v12, v150
	v_cmp_gt_u32_e64 s[12:13], s78, v11
	s_and_b64 s[44:45], s[12:13], vcc
	v_fmac_f32_e32 v225, 0x3e0293ee, v103
	v_cndmask_b32_e64 v10, v10, v225, s[44:45]
.LBB0_576:
	v_add_u32_e32 v11, 16, v2
	v_add_u32_e32 v12, 0xfffffd50, v3
	v_cmp_le_i32_e32 vcc, v12, v150
	v_cmp_gt_u32_e64 s[12:13], s78, v11
	s_and_b64 s[44:45], s[12:13], vcc
	v_mov_b32_e32 v11, 0xf149f2ca
	v_mov_b32_e32 v12, 0xf149f2ca
	ds_read_b32 v213, v226 offset:43072
	ds_read_b32 v214, v226 offset:43076
	ds_read_b32 v215, v226 offset:43080
	ds_read_b32 v216, v226 offset:43084
	ds_read_b32 v217, v226 offset:43104
	ds_read_b32 v218, v226 offset:43108
	ds_read_b32 v224, v226 offset:43112
	ds_read_b32 v225, v226 offset:43116
	s_waitcnt lgkmcnt(0)
	v_sub_u32_e32 v213, v162, v213
	v_med3_i32 v213, v213, 0, v236
	v_lshl_add_u32 v213, v213, 2, v163
	ds_read_b32 v213, v213 offset:43264
	v_sub_u32_e32 v214, v162, v214
	v_med3_i32 v214, v214, 0, v236
	v_lshl_add_u32 v214, v214, 2, v163
	ds_read_b32 v214, v214 offset:43264
	v_sub_u32_e32 v215, v162, v215
	v_med3_i32 v215, v215, 0, v236
	v_lshl_add_u32 v215, v215, 2, v163
	ds_read_b32 v215, v215 offset:43264
	v_sub_u32_e32 v216, v162, v216
	v_med3_i32 v216, v216, 0, v236
	v_lshl_add_u32 v216, v216, 2, v163
	ds_read_b32 v216, v216 offset:43264
	v_sub_u32_e32 v217, v162, v217
	v_med3_i32 v217, v217, 0, v236
	v_lshl_add_u32 v217, v217, 2, v163
	ds_read_b32 v217, v217 offset:43264
	v_sub_u32_e32 v218, v162, v218
	v_med3_i32 v218, v218, 0, v236
	v_lshl_add_u32 v218, v218, 2, v163
	ds_read_b32 v218, v218 offset:43264
	v_sub_u32_e32 v224, v162, v224
	v_med3_i32 v224, v224, 0, v236
	v_lshl_add_u32 v224, v224, 2, v163
	ds_read_b32 v224, v224 offset:43264
	v_sub_u32_e32 v225, v162, v225
	v_med3_i32 v225, v225, 0, v236
	v_lshl_add_u32 v225, v225, 2, v163
	ds_read_b32 v225, v225 offset:43264
	s_waitcnt lgkmcnt(0)
	v_fmac_f32_e32 v213, 0x3e0293ee, v104
	v_cndmask_b32_e64 v12, v12, v213, s[44:45]
.LBB0_578:
	v_add_u32_e32 v15, 17, v2
	v_add_u32_e32 v96, 0xfffffd60, v3
	v_cmp_le_i32_e32 vcc, v96, v150
	v_cmp_gt_u32_e64 s[12:13], s78, v15
	s_and_b64 s[44:45], s[12:13], vcc
	v_fmac_f32_e32 v214, 0x3e0293ee, v105
	v_cndmask_b32_e64 v11, v11, v214, s[44:45]
.LBB0_580:
	v_add_u32_e32 v15, 18, v2
	v_add_u32_e32 v96, 0xfffffd70, v3
	v_cmp_le_i32_e32 vcc, v96, v150
	v_cmp_gt_u32_e64 s[12:13], s78, v15
	s_and_b64 s[44:45], s[12:13], vcc
	v_mov_b32_e32 v96, 0xf149f2ca
	v_mov_b32_e32 v15, 0xf149f2ca
	v_fmac_f32_e32 v215, 0x3e0293ee, v106
	v_cndmask_b32_e64 v15, v15, v215, s[44:45]
.LBB0_582:
	v_add_u32_e32 v97, 19, v2
	v_add_u32_e32 v98, 0xfffffd80, v3
	v_cmp_le_i32_e32 vcc, v98, v150
	v_cmp_gt_u32_e64 s[12:13], s78, v97
	s_and_b64 s[44:45], s[12:13], vcc
	v_fmac_f32_e32 v216, 0x3e0293ee, v107
	v_cndmask_b32_e64 v96, v96, v216, s[44:45]
.LBB0_584:
	v_add_u32_e32 v97, 24, v2
	v_add_u32_e32 v98, 0xfffffdd0, v3
	v_cmp_le_i32_e32 vcc, v98, v150
	v_cmp_gt_u32_e64 s[12:13], s78, v97
	s_and_b64 s[44:45], s[12:13], vcc
	v_mov_b32_e32 v97, 0xf149f2ca
	v_mov_b32_e32 v98, 0xf149f2ca
	v_fmac_f32_e32 v217, 0x3e0293ee, v108
	v_cndmask_b32_e64 v98, v98, v217, s[44:45]
.LBB0_586:
	v_add_u32_e32 v99, 25, v2
	v_add_u32_e32 v100, 0xfffffde0, v3
	v_cmp_le_i32_e32 vcc, v100, v150
	v_cmp_gt_u32_e64 s[12:13], s78, v99
	s_and_b64 s[44:45], s[12:13], vcc
	v_fmac_f32_e32 v218, 0x3e0293ee, v109
	v_cndmask_b32_e64 v97, v97, v218, s[44:45]
.LBB0_588:
	v_add_u32_e32 v99, 26, v2
	v_add_u32_e32 v100, 0xfffffdf0, v3
	v_cmp_le_i32_e32 vcc, v100, v150
	v_cmp_gt_u32_e64 s[12:13], s78, v99
	s_and_b64 s[44:45], s[12:13], vcc
	v_mov_b32_e32 v100, 0xf149f2ca
	v_mov_b32_e32 v99, 0xf149f2ca
	v_fmac_f32_e32 v224, 0x3e0293ee, v110
	v_cndmask_b32_e64 v99, v99, v224, s[44:45]
.LBB0_590:
	v_add_u32_e32 v101, 27, v2
	v_add_u32_e32 v102, 0xfffffe00, v3
	v_cmp_le_i32_e32 vcc, v102, v150
	v_cmp_gt_u32_e64 s[12:13], s78, v101
	s_and_b64 s[44:45], s[12:13], vcc
	v_fmac_f32_e32 v225, 0x3e0293ee, v111
	v_cndmask_b32_e64 v100, v100, v225, s[44:45]
; DI int crow(int i, int h) { return (i & 3) + 8 * (i >> 2) + 4 * h; }
;   DI float score(float s, int, float, int t) const { return mine(t) ? s * sc + bfar : NEG; }
; template <int DK, bool PV, class SF, class PH>
; DI void attn_tile(const bf16x8 (&qf)[DK / 16], f32x16 (&o)[4], float& m, float& l, const char* smem, SF sf, PH ph) {
;     ...
;   for (int kb = 0; kb < 2; ++kb)
; #pragma unroll
;     for (int i = 0; i < 16; ++i) {
;       int kl = kb * 32 + crow(i, h);
;       float v = sf(s[kb][i], kl, auxs[kl]);
;       s[kb][i] = v;
;       mx = fmaxf(mx, v);
;     }
;           DI float score(float s, int key, float ax, int) const {
;             bool valid = (16 * key + 31 <= tq) && key < 511;
;             int d = posq - __float_as_int(ax);
;             d = d < 0 ? 0 : (d > 799 ? 799 : d);
;             return valid ? s * sc + lutr[d] : NEG;
;           }
.LBB0_592:
	v_add_u32_e32 v101, 32, v2
	v_add_u32_e32 v102, 0xfffffe50, v3
	v_cmp_le_i32_e32 vcc, v102, v150
	v_cmp_gt_u32_e64 s[12:13], s78, v101
	s_and_b64 s[44:45], s[12:13], vcc
	v_mov_b32_e32 v101, 0xf149f2ca
	v_mov_b32_e32 v102, 0xf149f2ca
	ds_read_b32 v213, v226 offset:43136
	ds_read_b32 v214, v226 offset:43140
	ds_read_b32 v215, v226 offset:43144
	ds_read_b32 v216, v226 offset:43148
	ds_read_b32 v217, v226 offset:43168
	ds_read_b32 v218, v226 offset:43172
	ds_read_b32 v224, v226 offset:43176
	ds_read_b32 v225, v226 offset:43180
	s_waitcnt lgkmcnt(0)
	v_sub_u32_e32 v213, v162, v213
	v_med3_i32 v213, v213, 0, v236
	v_lshl_add_u32 v213, v213, 2, v163
	ds_read_b32 v213, v213 offset:43264
	v_sub_u32_e32 v214, v162, v214
	v_med3_i32 v214, v214, 0, v236
	v_lshl_add_u32 v214, v214, 2, v163
	ds_read_b32 v214, v214 offset:43264
	v_sub_u32_e32 v215, v162, v215
	v_med3_i32 v215, v215, 0, v236
	v_lshl_add_u32 v215, v215, 2, v163
	ds_read_b32 v215, v215 offset:43264
	v_sub_u32_e32 v216, v162, v216
	v_med3_i32 v216, v216, 0, v236
	v_lshl_add_u32 v216, v216, 2, v163
	ds_read_b32 v216, v216 offset:43264
	v_sub_u32_e32 v217, v162, v217
	v_med3_i32 v217, v217, 0, v236
	v_lshl_add_u32 v217, v217, 2, v163
	ds_read_b32 v217, v217 offset:43264
	v_sub_u32_e32 v218, v162, v218
	v_med3_i32 v218, v218, 0, v236
	v_lshl_add_u32 v218, v218, 2, v163
	ds_read_b32 v218, v218 offset:43264
	v_sub_u32_e32 v224, v162, v224
	v_med3_i32 v224, v224, 0, v236
	v_lshl_add_u32 v224, v224, 2, v163
	ds_read_b32 v224, v224 offset:43264
	v_sub_u32_e32 v225, v162, v225
	v_med3_i32 v225, v225, 0, v236
	v_lshl_add_u32 v225, v225, 2, v163
	ds_read_b32 v225, v225 offset:43264
	s_waitcnt lgkmcnt(0)
	v_fmac_f32_e32 v213, 0x3e0293ee, v80
	v_cndmask_b32_e64 v102, v102, v213, s[44:45]
.LBB0_594:
	v_add_u32_e32 v80, 33, v2
	v_add_u32_e32 v103, 0xfffffe60, v3
	v_cmp_le_i32_e32 vcc, v103, v150
	v_cmp_gt_u32_e64 s[12:13], s78, v80
	s_and_b64 s[44:45], s[12:13], vcc
	v_fmac_f32_e32 v214, 0x3e0293ee, v81
	v_cndmask_b32_e64 v101, v101, v214, s[44:45]
.LBB0_596:
	v_add_u32_e32 v80, 34, v2
	v_add_u32_e32 v81, 0xfffffe70, v3
	v_cmp_le_i32_e32 vcc, v81, v150
	v_cmp_gt_u32_e64 s[12:13], s78, v80
	s_and_b64 s[44:45], s[12:13], vcc
	v_mov_b32_e32 v103, 0xf149f2ca
	v_mov_b32_e32 v104, 0xf149f2ca
	v_fmac_f32_e32 v215, 0x3e0293ee, v82
	v_cndmask_b32_e64 v104, v104, v215, s[44:45]
.LBB0_598:
	v_add_u32_e32 v80, 35, v2
	v_add_u32_e32 v81, 0xfffffe80, v3
	v_cmp_le_i32_e32 vcc, v81, v150
	v_cmp_gt_u32_e64 s[12:13], s78, v80
	s_and_b64 s[44:45], s[12:13], vcc
	v_fmac_f32_e32 v216, 0x3e0293ee, v83
	v_cndmask_b32_e64 v103, v103, v216, s[44:45]
.LBB0_600:
	v_add_u32_e32 v80, 40, v2
	v_add_u32_e32 v81, 0xfffffed0, v3
	v_cmp_le_i32_e32 vcc, v81, v150
	v_cmp_gt_u32_e64 s[12:13], s78, v80
	s_and_b64 s[44:45], s[12:13], vcc
	v_mov_b32_e32 v80, 0xf149f2ca
	v_mov_b32_e32 v81, 0xf149f2ca
	v_fmac_f32_e32 v217, 0x3e0293ee, v84
	v_cndmask_b32_e64 v81, v81, v217, s[44:45]
.LBB0_602:
	v_add_u32_e32 v82, 41, v2
	v_add_u32_e32 v83, 0xfffffee0, v3
	v_cmp_le_i32_e32 vcc, v83, v150
	v_cmp_gt_u32_e64 s[12:13], s78, v82
	s_and_b64 s[44:45], s[12:13], vcc
	v_fmac_f32_e32 v218, 0x3e0293ee, v85
	v_cndmask_b32_e64 v80, v80, v218, s[44:45]
.LBB0_604:
	v_add_u32_e32 v82, 42, v2
	v_add_u32_e32 v83, 0xfffffef0, v3
	v_cmp_le_i32_e32 vcc, v83, v150
	v_cmp_gt_u32_e64 s[12:13], s78, v82
	s_and_b64 s[44:45], s[12:13], vcc
	v_mov_b32_e32 v83, 0xf149f2ca
	v_mov_b32_e32 v82, 0xf149f2ca
	v_fmac_f32_e32 v224, 0x3e0293ee, v86
	v_cndmask_b32_e64 v82, v82, v224, s[44:45]
.LBB0_606:
	v_add_u32_e32 v84, 43, v2
	v_add_u32_e32 v85, 0xffffff00, v3
	v_cmp_le_i32_e32 vcc, v85, v150
	v_cmp_gt_u32_e64 s[12:13], s78, v84
	s_and_b64 s[44:45], s[12:13], vcc
	v_fmac_f32_e32 v225, 0x3e0293ee, v87
	v_cndmask_b32_e64 v83, v83, v225, s[44:45]
; DI int otid() { int z; asm volatile("s_mov_b32 %0, 0" : "=s"(z)); return (int)threadIdx.x + z; }
; DI int crow(int i, int h) { return (i & 3) + 8 * (i >> 2) + 4 * h; }
; DI float ex2(float x) { return __builtin_amdgcn_exp2f(x); }
; template <int DK, bool PV, class SF, class PH>
; DI void attn_tile(const bf16x8 (&qf)[DK / 16], f32x16 (&o)[4], float& m, float& l, const char* smem, SF sf, PH ph) {
;     ...
;   float mx = m;
; #pragma unroll
;   for (int kb = 0; kb < 2; ++kb)
; #pragma unroll
;     for (int i = 0; i < 16; ++i) {
;       int kl = kb * 32 + crow(i, h);
;       float v = sf(s[kb][i], kl, auxs[kl]);
;       s[kb][i] = v;
;       mx = fmaxf(mx, v);
;     }
;   mx = fmaxf(mx, __shfl_xor(mx, 32));
;   float alpha = ex2(m - mx);
;   m = mx;
;   float psum = 0.f;
; #pragma unroll
;   for (int kb = 0; kb < 2; ++kb)
; #pragma unroll
;     for (int i = 0; i < 16; ++i) {
;       float pv = ex2(s[kb][i] - mx);
;       s[kb][i] = pv;
;       psum += pv;
;     }
;   l = l * alpha + psum;
;           DI void hook(int kb, const f32x16& pt, int tc) const {
;             if (!p2) return;
;             const int lane = otid() & 63, h = lane >> 5, r = lane & 31;
; #pragma unroll
;             for (int gq = 0; gq < 4; ++gq) {
;               float p3 = 0.5f * pt[4 * gq + 3];
;               float vm = (pt[4 * gq] + pt[4 * gq + 1] + pt[4 * gq + 2] + p3) * invl;
;               float vs = p3 * invl;
;               vm += __shfl_xor(vm, 8); vm += __shfl_xor(vm, 16);
;               vs += __shfl_xor(vs, 8); vs += __shfl_xor(vs, 16);
;               int j = tc * 16 + kb * 8 + 2 * gq + h;
;               if (r < 8) { atomicAdd(&imp[ql * 132 + j], vm); atomicAdd(&imp[ql * 132 + j + 1], vs); }
;             }
;           }
.LBB0_608:
	v_add_u32_e32 v84, 48, v2
	v_add_u32_e32 v85, 0xffffff50, v3
	v_cmp_le_i32_e32 vcc, v85, v150
	v_cmp_gt_u32_e64 s[12:13], s78, v84
	s_and_b64 s[44:45], s[12:13], vcc
	v_mov_b32_e32 v84, 0xf149f2ca
	v_mov_b32_e32 v85, 0xf149f2ca
	ds_read_b32 v213, v226 offset:43200
	ds_read_b32 v214, v226 offset:43204
	ds_read_b32 v215, v226 offset:43208
	ds_read_b32 v216, v226 offset:43212
	ds_read_b32 v217, v226 offset:43232
	ds_read_b32 v218, v226 offset:43236
	ds_read_b32 v224, v226 offset:43240
	ds_read_b32 v225, v226 offset:43244
	s_waitcnt lgkmcnt(0)
	v_sub_u32_e32 v213, v162, v213
	v_med3_i32 v213, v213, 0, v236
	v_lshl_add_u32 v213, v213, 2, v163
	ds_read_b32 v213, v213 offset:43264
	v_sub_u32_e32 v214, v162, v214
	v_med3_i32 v214, v214, 0, v236
	v_lshl_add_u32 v214, v214, 2, v163
	ds_read_b32 v214, v214 offset:43264
	v_sub_u32_e32 v215, v162, v215
	v_med3_i32 v215, v215, 0, v236
	v_lshl_add_u32 v215, v215, 2, v163
	ds_read_b32 v215, v215 offset:43264
	v_sub_u32_e32 v216, v162, v216
	v_med3_i32 v216, v216, 0, v236
	v_lshl_add_u32 v216, v216, 2, v163
	ds_read_b32 v216, v216 offset:43264
	v_sub_u32_e32 v217, v162, v217
	v_med3_i32 v217, v217, 0, v236
	v_lshl_add_u32 v217, v217, 2, v163
	ds_read_b32 v217, v217 offset:43264
	v_sub_u32_e32 v218, v162, v218
	v_med3_i32 v218, v218, 0, v236
	v_lshl_add_u32 v218, v218, 2, v163
	ds_read_b32 v218, v218 offset:43264
	v_sub_u32_e32 v224, v162, v224
	v_med3_i32 v224, v224, 0, v236
	v_lshl_add_u32 v224, v224, 2, v163
	ds_read_b32 v224, v224 offset:43264
	v_sub_u32_e32 v225, v162, v225
	v_med3_i32 v225, v225, 0, v236
	v_lshl_add_u32 v225, v225, 2, v163
	ds_read_b32 v225, v225 offset:43264
	s_waitcnt lgkmcnt(0)
	v_fmac_f32_e32 v213, 0x3e0293ee, v88
	v_cndmask_b32_e64 v85, v85, v213, s[44:45]
.LBB0_610:
	v_add_u32_e32 v86, 49, v2
	v_add_u32_e32 v87, 0xffffff60, v3
	v_cmp_le_i32_e32 vcc, v87, v150
	v_cmp_gt_u32_e64 s[12:13], s78, v86
	s_and_b64 s[44:45], s[12:13], vcc
	v_fmac_f32_e32 v214, 0x3e0293ee, v89
	v_cndmask_b32_e64 v84, v84, v214, s[44:45]
.LBB0_612:
	v_add_u32_e32 v86, 50, v2
	v_add_u32_e32 v87, 0xffffff70, v3
	v_cmp_le_i32_e32 vcc, v87, v150
	v_cmp_gt_u32_e64 s[12:13], s78, v86
	s_and_b64 s[44:45], s[12:13], vcc
	v_mov_b32_e32 v87, 0xf149f2ca
	v_mov_b32_e32 v86, 0xf149f2ca
	v_fmac_f32_e32 v215, 0x3e0293ee, v90
	v_cndmask_b32_e64 v86, v86, v215, s[44:45]
.LBB0_614:
	v_add_u32_e32 v88, 51, v2
	v_add_u32_e32 v89, 0xffffff80, v3
	v_cmp_le_i32_e32 vcc, v89, v150
	v_cmp_gt_u32_e64 s[12:13], s78, v88
	s_and_b64 s[44:45], s[12:13], vcc
	v_fmac_f32_e32 v216, 0x3e0293ee, v91
	v_cndmask_b32_e64 v87, v87, v216, s[44:45]
.LBB0_616:
	v_add_u32_e32 v88, 56, v2
	v_subrev_u32_e32 v89, 48, v3
	v_cmp_le_i32_e32 vcc, v89, v150
	v_cmp_gt_u32_e64 s[12:13], s78, v88
	s_and_b64 s[44:45], s[12:13], vcc
	v_mov_b32_e32 v88, 0xf149f2ca
	v_mov_b32_e32 v90, 0xf149f2ca
	v_fmac_f32_e32 v217, 0x3e0293ee, v92
	v_cndmask_b32_e64 v90, v90, v217, s[44:45]
.LBB0_618:
	v_add_u32_e32 v89, 57, v2
	v_subrev_u32_e32 v91, 32, v3
	v_cmp_le_i32_e32 vcc, v91, v150
	v_cmp_gt_u32_e64 s[12:13], s78, v89
	s_and_b64 s[44:45], s[12:13], vcc
	v_fmac_f32_e32 v218, 0x3e0293ee, v93
	v_cndmask_b32_e64 v88, v88, v218, s[44:45]
.LBB0_620:
	v_add_u32_e32 v89, 58, v2
	v_add_u32_e32 v91, -16, v3
	v_cmp_le_i32_e32 vcc, v91, v150
	v_cmp_gt_u32_e64 s[12:13], s78, v89
	s_and_b64 s[44:45], s[12:13], vcc
	v_mov_b32_e32 v106, 0xf149f2ca
	v_mov_b32_e32 v105, 0xf149f2ca
	v_fmac_f32_e32 v224, 0x3e0293ee, v94
	v_cndmask_b32_e64 v105, v105, v224, s[44:45]
.LBB0_622:
	v_add_u32_e32 v2, 59, v2
	v_cmp_le_i32_e32 vcc, v3, v150
	v_cmp_gt_u32_e64 s[12:13], s78, v2
	s_and_b64 s[44:45], s[12:13], vcc
	v_fmac_f32_e32 v225, 0x3e0293ee, v95
	v_cndmask_b32_e64 v106, v106, v225, s[44:45]
.LBB0_624:
	v_max3_f32 v2, v175, v8, v7
	v_max3_f32 v2, v2, v14, v13
	v_max3_f32 v2, v2, v6, v5
	v_max3_f32 v2, v2, v9, v10
	v_max3_f32 v2, v2, v12, v11
	v_max3_f32 v2, v2, v15, v96
	v_max3_f32 v2, v2, v98, v97
	v_max3_f32 v2, v2, v99, v100
	v_max3_f32 v2, v2, v102, v101
	v_max3_f32 v2, v2, v104, v103
	v_max3_f32 v2, v2, v81, v80
	v_max3_f32 v2, v2, v82, v83
	v_max3_f32 v2, v2, v85, v84
	v_max3_f32 v2, v2, v86, v87
	v_max3_f32 v2, v2, v90, v88
	v_max3_f32 v2, v2, v105, v106
	ds_bpermute_b32 v3, v164, v2
	s_mov_b32 s12, 0
	s_waitcnt lgkmcnt(0)
	v_max_f32_e32 v3, v3, v3
	v_max_f32_e32 v3, v2, v3
	v_sub_f32_e32 v2, v8, v3
	v_exp_f32_e32 v8, v2
	v_sub_f32_e32 v2, v7, v3
	v_exp_f32_e32 v7, v2
	v_sub_f32_e32 v2, v14, v3
	v_exp_f32_e32 v14, v2
	v_sub_f32_e32 v2, v13, v3
	v_exp_f32_e32 v13, v2
	v_add_u32_e32 v2, s12, v189
	v_bfe_u32 v89, v2, 5, 1
	v_and_b32_e32 v2, 24, v2
	v_cmp_eq_u32_e32 vcc, 0, v2
	v_add_u32_e32 v2, s15, v89
	v_add_f32_e32 v89, v8, v7
	v_add_f32_e32 v91, v14, v89
	v_mul_f32_e32 v93, 0.5, v13
	v_fmac_f32_e32 v91, 0.5, v13
	v_mul_f32_e32 v89, v145, v91
	v_mul_f32_e32 v92, v145, v93
	ds_bpermute_b32 v89, v168, v89
	ds_bpermute_b32 v92, v168, v92
	v_lshl_add_u32 v2, v2, 2, v156
	s_waitcnt lgkmcnt(1)
	v_fmac_f32_e32 v89, v145, v91
	s_waitcnt lgkmcnt(0)
	v_fmac_f32_e32 v92, v145, v93
	ds_bpermute_b32 v91, v167, v89
	ds_bpermute_b32 v93, v167, v92
	s_and_saveexec_b64 s[12:13], vcc
	s_cbranch_execz .LBB0_626
	s_waitcnt lgkmcnt(1)
	v_add_f32_e32 v89, v89, v91
	s_waitcnt lgkmcnt(0)
	v_add_f32_e32 v92, v92, v93
	ds_add_f32 v2, v89 offset:56064
	ds_add_f32 v2, v92 offset:56068

; #define MFMA32(a, b, c) __builtin_amdgcn_mfma_f32_32x32x16_bf16((a), (b), (c), 0, 0, 0)
; DI int crow(int i, int h) { return (i & 3) + 8 * (i >> 2) + 4 * h; }
;   DI float aux(int key) const { return (cuml[key] + cpre[key >> 7]) * LOG2E; }
;           DI float aux(int key) const { int n = key < 511 ? key : 510; return __int_as_float(pos[16 * n + 31]); }
;   DI bool farj(int j) const { return (j * 64 + 63 < q0) && (pqmin - posmax[j] >= 799); }
;   DI bool farj(int j) const { return (j * 64 + 63 < q0) && (pqmin - posmax[j] >= 799); }
;   DI int next(int t) const { for (int j = t + 1; j < 128; ++j) if (inu(j) && farj(j)) return j; return -1; }
;   DI float score(float s, int, float, int t) const { return mine(t) ? s * sc + bfar : NEG; }
; template <int DK, bool PV, class SF, class PH>
; DI void attn_tile(const bf16x8 (&qf)[DK / 16], f32x16 (&o)[4], float& m, float& l, const char* smem, SF sf, PH ph) {
;     ...
;   for (int kb = 0; kb < 2; ++kb) {
; #pragma unroll
;     for (int i = 0; i < 16; ++i) s[kb][i] = 0.f;
; #pragma unroll
;     for (int ks = 0; ks < DK / 16; ++ks) {
;       bf16x8 a = *(const bf16x8*)(Ks + (kb * 32 + r) * (DK + 8) + ks * 16 + h * 8);
;       s[kb] = MFMA32(a, qf[ks], s[kb]);
;     }
;   }
;   float mx = m;
; #pragma unroll
;   for (int kb = 0; kb < 2; ++kb)
; #pragma unroll
;     for (int i = 0; i < 16; ++i) {
;       int kl = kb * 32 + crow(i, h);
;       float v = sf(s[kb][i], kl, auxs[kl]);
;       s[kb][i] = v;
;       mx = fmaxf(mx, v);
;     }
;   DI bool inu(int j) const {
;     unsigned long long a = (ulo >> (j & 63)) & (j < 64 ? 1ull : 0ull);
;     unsigned long long b = (uhi >> (j & 63)) & (j >= 64 ? 1ull : 0ull);
;     return (a | b) != 0ull;
;   }
;   DI bool mine(int j) const {
;     unsigned long long a = (mlo >> (j & 63)) & (j < 64 ? 1ull : 0ull);
;     unsigned long long b = (mhi >> (j & 63)) & (j >= 64 ? 1ull : 0ull);
;     return (a | b) != 0ull;
;   }
;   DI int next(int t) const { for (int j = t + 1; j < 128; ++j) if (inu(j) && !farj(j)) return j; return -1; }
;   DI float aux(int key) const { return __int_as_float(pos[key]); }
;   DI float score(float s, int key, float ax, int t) const {
;     bool valid = mine(t) && key <= tq;
;     int d = posq - __float_as_int(ax);
;     d = d < 0 ? 0 : (d > 799 ? 799 : d);
;     return valid ? s * sc + lutr[d] : NEG;
;   }
.LBB0_679:
	s_cmp_lt_u32 s46, 64
	s_cselect_b64 s[12:13], -1, 0
	s_cmp_gt_u32 s46, 63
	v_lshrrev_b64 v[2:3], s46, v[144:145]
	v_cndmask_b32_e64 v0, 0, 1, s[12:13]
	s_cselect_b64 s[12:13], -1, 0
	v_lshrrev_b64 v[4:5], s46, v[146:147]
	v_cndmask_b32_e64 v3, 0, 1, s[12:13]
	v_and_b32_e32 v0, v0, v2
	v_and_b32_e32 v3, v3, v4
	v_or_b32_e32 v0, v3, v0
	v_cmp_ne_u64_e32 vcc, 0, v[0:1]
	s_cbranch_vccz .LBB0_665
	s_mov_b32 s12, 0
	v_and_b32_e32 v0, 1, v2
	v_add_u32_e32 v3, s12, v189
	v_and_b32_e32 v2, 31, v3
	v_lshrrev_b32_e32 v3, 5, v3
	v_and_b32_e32 v3, 1, v3
	v_lshlrev_b32_e32 v10, 4, v3
	v_mad_u32_u24 v9, v2, s73, v10
	v_and_b32_e32 v8, 1, v4
	ds_read_b128 v[4:7], v9
	ds_read_b128 v[12:15], v9 offset:32
	s_waitcnt lgkmcnt(1)
	v_mfma_f32_32x32x16_bf16 v[96:111], v[4:7], v[136:139], 0
	ds_read_b128 v[4:7], v9 offset:64
	s_cmp_lt_i32 s46, 64
	s_cselect_b64 vcc, -1, 0
	s_cmp_gt_i32 s46, 63
	v_cndmask_b32_e32 v0, 0, v0, vcc
	s_cselect_b64 vcc, -1, 0
	v_lshlrev_b32_e32 v3, 2, v3
	s_waitcnt lgkmcnt(1)
	v_mfma_f32_32x32x16_bf16 v[96:111], v[12:15], v[112:115], v[96:111]
	s_waitcnt lgkmcnt(0)
	v_mfma_f32_32x32x16_bf16 v[96:111], v[4:7], v[116:119], v[96:111]
	ds_read_b128 v[4:7], v9 offset:96
	s_waitcnt lgkmcnt(0)
	v_mfma_f32_32x32x16_bf16 v[96:111], v[4:7], v[120:123], v[96:111]
	ds_read_b128 v[4:7], v9 offset:128
	s_waitcnt lgkmcnt(0)
	v_mfma_f32_32x32x16_bf16 v[96:111], v[4:7], v[124:127], v[96:111]
	ds_read_b128 v[4:7], v9 offset:160
	s_waitcnt lgkmcnt(0)
	v_mfma_f32_32x32x16_bf16 v[96:111], v[4:7], v[128:131], v[96:111]
	ds_read_b128 v[4:7], v9 offset:192
	s_waitcnt lgkmcnt(0)
	v_mfma_f32_32x32x16_bf16 v[96:111], v[4:7], v[132:135], v[96:111]
	ds_read_b128 v[4:7], v9 offset:224
	s_waitcnt lgkmcnt(0)
	v_mfma_f32_32x32x16_bf16 v[96:111], v[4:7], v[140:143], v[96:111]
	ds_read_b128 v[4:7], v9 offset:8704
	s_waitcnt lgkmcnt(0)
	v_mfma_f32_32x32x16_bf16 v[80:95], v[4:7], v[136:139], 0
	ds_read_b128 v[4:7], v9 offset:8736
	s_waitcnt lgkmcnt(0)
	v_mfma_f32_32x32x16_bf16 v[80:95], v[4:7], v[112:115], v[80:95]
	ds_read_b128 v[4:7], v9 offset:8768
	s_waitcnt lgkmcnt(0)
	v_mfma_f32_32x32x16_bf16 v[80:95], v[4:7], v[116:119], v[80:95]
	ds_read_b128 v[4:7], v9 offset:8800
	s_waitcnt lgkmcnt(0)
	v_mfma_f32_32x32x16_bf16 v[80:95], v[4:7], v[120:123], v[80:95]
	ds_read_b128 v[4:7], v9 offset:8832
	s_waitcnt lgkmcnt(0)
	v_mfma_f32_32x32x16_bf16 v[80:95], v[4:7], v[124:127], v[80:95]
	ds_read_b128 v[4:7], v9 offset:8864
	s_waitcnt lgkmcnt(0)
	v_mfma_f32_32x32x16_bf16 v[80:95], v[4:7], v[128:131], v[80:95]
	ds_read_b128 v[4:7], v9 offset:8896
	s_waitcnt lgkmcnt(0)
	v_mfma_f32_32x32x16_bf16 v[80:95], v[4:7], v[132:135], v[80:95]
	ds_read_b128 v[4:7], v9 offset:8928
	s_waitcnt lgkmcnt(0)
	v_mfma_f32_32x32x16_bf16 v[80:95], v[4:7], v[140:143], v[80:95]
	v_cndmask_b32_e32 v4, 0, v8, vcc
	v_or_b32_e32 v0, v4, v0
	v_cmp_ne_u64_e32 vcc, 0, v[0:1]
	v_or_b32_e32 v0, s26, v3
	v_cmp_le_i32_e64 s[12:13], v0, v150
	s_and_b64 s[36:37], vcc, s[12:13]
	v_mov_b32_e32 v4, 0xf149f2ca
	v_mov_b32_e32 v5, 0xf149f2ca
	v_and_b32_e32 v226, 32, v189
	v_lshrrev_b32_e32 v226, 1, v226
	ds_read_b32 v213, v226 offset:43008
	ds_read_b32 v214, v226 offset:43012
	ds_read_b32 v215, v226 offset:43016
	ds_read_b32 v216, v226 offset:43020
	ds_read_b32 v217, v226 offset:43040
	ds_read_b32 v218, v226 offset:43044
	ds_read_b32 v224, v226 offset:43048
	ds_read_b32 v225, v226 offset:43052
	s_waitcnt lgkmcnt(0)
	v_sub_u32_e32 v213, v162, v213
	v_med3_i32 v213, v213, 0, v236
	v_lshl_add_u32 v213, v213, 2, v163
	ds_read_b32 v213, v213 offset:43264
	v_sub_u32_e32 v214, v162, v214
	v_med3_i32 v214, v214, 0, v236
	v_lshl_add_u32 v214, v214, 2, v163
	ds_read_b32 v214, v214 offset:43264
	v_sub_u32_e32 v215, v162, v215
	v_med3_i32 v215, v215, 0, v236
	v_lshl_add_u32 v215, v215, 2, v163
	ds_read_b32 v215, v215 offset:43264
	v_sub_u32_e32 v216, v162, v216
	v_med3_i32 v216, v216, 0, v236
	v_lshl_add_u32 v216, v216, 2, v163
	ds_read_b32 v216, v216 offset:43264
	v_sub_u32_e32 v217, v162, v217
	v_med3_i32 v217, v217, 0, v236
	v_lshl_add_u32 v217, v217, 2, v163
	ds_read_b32 v217, v217 offset:43264
	v_sub_u32_e32 v218, v162, v218
	v_med3_i32 v218, v218, 0, v236
	v_lshl_add_u32 v218, v218, 2, v163
	ds_read_b32 v218, v218 offset:43264
	v_sub_u32_e32 v224, v162, v224
	v_med3_i32 v224, v224, 0, v236
	v_lshl_add_u32 v224, v224, 2, v163
	ds_read_b32 v224, v224 offset:43264
	v_sub_u32_e32 v225, v162, v225
	v_med3_i32 v225, v225, 0, v236
	v_lshl_add_u32 v225, v225, 2, v163
	ds_read_b32 v225, v225 offset:43264
	s_waitcnt lgkmcnt(0)
	v_fmac_f32_e32 v213, 0x3e0293ee, v96
	v_cndmask_b32_e64 v5, v5, v213, s[36:37]
.LBB0_682:
	v_or3_b32 v0, v3, s26, 1
	v_cmp_le_i32_e64 s[12:13], v0, v150
	s_and_b64 s[36:37], vcc, s[12:13]
	v_fmac_f32_e32 v214, 0x3e0293ee, v97
	v_cndmask_b32_e64 v4, v4, v214, s[36:37]
.LBB0_684:
	v_or3_b32 v0, v3, s26, 2
	v_cmp_le_i32_e64 s[12:13], v0, v150
	s_and_b64 s[36:37], vcc, s[12:13]
	v_mov_b32_e32 v6, 0xf149f2ca
	v_mov_b32_e32 v7, 0xf149f2ca
	v_fmac_f32_e32 v215, 0x3e0293ee, v98
	v_cndmask_b32_e64 v7, v7, v215, s[36:37]
.LBB0_686:
	v_or3_b32 v0, v3, s26, 3
	v_cmp_le_i32_e64 s[12:13], v0, v150
	s_and_b64 s[36:37], vcc, s[12:13]
	v_fmac_f32_e32 v216, 0x3e0293ee, v99
	v_cndmask_b32_e64 v6, v6, v216, s[36:37]
.LBB0_688:
	v_or3_b32 v0, v3, s26, 8
	v_cmp_le_i32_e64 s[12:13], v0, v150
	s_and_b64 s[36:37], vcc, s[12:13]
	v_mov_b32_e32 v8, 0xf149f2ca
	v_mov_b32_e32 v9, 0xf149f2ca
	v_fmac_f32_e32 v217, 0x3e0293ee, v100
	v_cndmask_b32_e64 v9, v9, v217, s[36:37]
.LBB0_690:
	v_or3_b32 v0, v3, s26, 9
	v_cmp_le_i32_e64 s[12:13], v0, v150
	s_and_b64 s[36:37], vcc, s[12:13]
	v_fmac_f32_e32 v218, 0x3e0293ee, v101
	v_cndmask_b32_e64 v8, v8, v218, s[36:37]
; DI int crow(int i, int h) { return (i & 3) + 8 * (i >> 2) + 4 * h; }
;   DI float score(float s, int, float, int t) const { return mine(t) ? s * sc + bfar : NEG; }
; template <int DK, bool PV, class SF, class PH>
; DI void attn_tile(const bf16x8 (&qf)[DK / 16], f32x16 (&o)[4], float& m, float& l, const char* smem, SF sf, PH ph) {
;     ...
;   for (int kb = 0; kb < 2; ++kb)
; #pragma unroll
;     for (int i = 0; i < 16; ++i) {
;       int kl = kb * 32 + crow(i, h);
;       float v = sf(s[kb][i], kl, auxs[kl]);
;       s[kb][i] = v;
;       mx = fmaxf(mx, v);
;     }
;   DI float score(float s, int key, float ax, int t) const {
;     bool valid = mine(t) && key <= tq;
;     int d = posq - __float_as_int(ax);
;     d = d < 0 ? 0 : (d > 799 ? 799 : d);
;     return valid ? s * sc + lutr[d] : NEG;
;   }
.LBB0_692:
	v_or3_b32 v0, v3, s26, 10
	v_cmp_le_i32_e64 s[12:13], v0, v150
	s_and_b64 s[36:37], vcc, s[12:13]
	v_mov_b32_e32 v10, 0xf149f2ca
	v_lshlrev_b32_e32 v0, 2, v3
	v_mov_b32_e32 v11, 0xf149f2ca
	v_fmac_f32_e32 v224, 0x3e0293ee, v102
	v_cndmask_b32_e64 v11, v11, v224, s[36:37]
.LBB0_694:
	v_or3_b32 v12, v3, s26, 11
	v_cmp_le_i32_e64 s[12:13], v12, v150
	s_and_b64 s[36:37], vcc, s[12:13]
	v_fmac_f32_e32 v225, 0x3e0293ee, v103
	v_cndmask_b32_e64 v10, v10, v225, s[36:37]
.LBB0_696:
	v_or3_b32 v12, v3, s26, 16
	v_cmp_le_i32_e64 s[12:13], v12, v150
	s_and_b64 s[36:37], vcc, s[12:13]
	v_mov_b32_e32 v12, 0xf149f2ca
	v_mov_b32_e32 v13, 0xf149f2ca
	ds_read_b32 v213, v226 offset:43072
	ds_read_b32 v214, v226 offset:43076
	ds_read_b32 v215, v226 offset:43080
	ds_read_b32 v216, v226 offset:43084
	ds_read_b32 v217, v226 offset:43104
	ds_read_b32 v218, v226 offset:43108
	ds_read_b32 v224, v226 offset:43112
	ds_read_b32 v225, v226 offset:43116
	s_waitcnt lgkmcnt(0)
	v_sub_u32_e32 v213, v162, v213
	v_med3_i32 v213, v213, 0, v236
	v_lshl_add_u32 v213, v213, 2, v163
	ds_read_b32 v213, v213 offset:43264
	v_sub_u32_e32 v214, v162, v214
	v_med3_i32 v214, v214, 0, v236
	v_lshl_add_u32 v214, v214, 2, v163
	ds_read_b32 v214, v214 offset:43264
	v_sub_u32_e32 v215, v162, v215
	v_med3_i32 v215, v215, 0, v236
	v_lshl_add_u32 v215, v215, 2, v163
	ds_read_b32 v215, v215 offset:43264
	v_sub_u32_e32 v216, v162, v216
	v_med3_i32 v216, v216, 0, v236
	v_lshl_add_u32 v216, v216, 2, v163
	ds_read_b32 v216, v216 offset:43264
	v_sub_u32_e32 v217, v162, v217
	v_med3_i32 v217, v217, 0, v236
	v_lshl_add_u32 v217, v217, 2, v163
	ds_read_b32 v217, v217 offset:43264
	v_sub_u32_e32 v218, v162, v218
	v_med3_i32 v218, v218, 0, v236
	v_lshl_add_u32 v218, v218, 2, v163
	ds_read_b32 v218, v218 offset:43264
	v_sub_u32_e32 v224, v162, v224
	v_med3_i32 v224, v224, 0, v236
	v_lshl_add_u32 v224, v224, 2, v163
	ds_read_b32 v224, v224 offset:43264
	v_sub_u32_e32 v225, v162, v225
	v_med3_i32 v225, v225, 0, v236
	v_lshl_add_u32 v225, v225, 2, v163
	ds_read_b32 v225, v225 offset:43264
	s_waitcnt lgkmcnt(0)
	v_fmac_f32_e32 v213, 0x3e0293ee, v104
	v_cndmask_b32_e64 v13, v13, v213, s[36:37]
.LBB0_698:
	v_or3_b32 v14, v3, s26, 17
	v_cmp_le_i32_e64 s[12:13], v14, v150
	s_and_b64 s[36:37], vcc, s[12:13]
	v_fmac_f32_e32 v214, 0x3e0293ee, v105
	v_cndmask_b32_e64 v12, v12, v214, s[36:37]
.LBB0_700:
	v_or3_b32 v14, v3, s26, 18
	v_cmp_le_i32_e64 s[12:13], v14, v150
	s_and_b64 s[36:37], vcc, s[12:13]
	v_mov_b32_e32 v14, 0xf149f2ca
	v_mov_b32_e32 v15, 0xf149f2ca
	v_fmac_f32_e32 v215, 0x3e0293ee, v106
	v_cndmask_b32_e64 v15, v15, v215, s[36:37]
.LBB0_702:
	v_or3_b32 v96, v3, s26, 19
	v_cmp_le_i32_e64 s[12:13], v96, v150
	s_and_b64 s[36:37], vcc, s[12:13]
	v_fmac_f32_e32 v216, 0x3e0293ee, v107
	v_cndmask_b32_e64 v14, v14, v216, s[36:37]
.LBB0_704:
	v_or3_b32 v96, v3, s26, 24
	v_cmp_le_i32_e64 s[12:13], v96, v150
	s_and_b64 s[36:37], vcc, s[12:13]
	v_mov_b32_e32 v96, 0xf149f2ca
	v_mov_b32_e32 v97, 0xf149f2ca
	v_fmac_f32_e32 v217, 0x3e0293ee, v108
	v_cndmask_b32_e64 v97, v97, v217, s[36:37]
.LBB0_706:
	v_or3_b32 v98, v3, s26, 25
	v_cmp_le_i32_e64 s[12:13], v98, v150
	s_and_b64 s[36:37], vcc, s[12:13]
	v_fmac_f32_e32 v218, 0x3e0293ee, v109
	v_cndmask_b32_e64 v96, v96, v218, s[36:37]
.LBB0_708:
	v_or3_b32 v98, v3, s26, 26
	v_cmp_le_i32_e64 s[12:13], v98, v150
	s_and_b64 s[36:37], vcc, s[12:13]
	v_mov_b32_e32 v98, 0xf149f2ca
	v_mov_b32_e32 v99, 0xf149f2ca
	v_fmac_f32_e32 v224, 0x3e0293ee, v110
	v_cndmask_b32_e64 v99, v99, v224, s[36:37]
.LBB0_710:
	v_or3_b32 v100, v3, s26, 27
	v_cmp_le_i32_e64 s[12:13], v100, v150
	s_and_b64 s[36:37], vcc, s[12:13]
	v_fmac_f32_e32 v225, 0x3e0293ee, v111
	v_cndmask_b32_e64 v98, v98, v225, s[36:37]
.LBB0_712:
	v_or3_b32 v100, v3, s26, 32
	v_cmp_le_i32_e64 s[12:13], v100, v150
	s_and_b64 s[36:37], vcc, s[12:13]
	v_mov_b32_e32 v100, 0xf149f2ca
	v_mov_b32_e32 v101, 0xf149f2ca
	ds_read_b32 v213, v226 offset:43136
	ds_read_b32 v214, v226 offset:43140
	ds_read_b32 v215, v226 offset:43144
	ds_read_b32 v216, v226 offset:43148
	ds_read_b32 v217, v226 offset:43168
	ds_read_b32 v218, v226 offset:43172
	ds_read_b32 v224, v226 offset:43176
	ds_read_b32 v225, v226 offset:43180
	s_waitcnt lgkmcnt(0)
	v_sub_u32_e32 v213, v162, v213
	v_med3_i32 v213, v213, 0, v236
	v_lshl_add_u32 v213, v213, 2, v163
	ds_read_b32 v213, v213 offset:43264
	v_sub_u32_e32 v214, v162, v214
	v_med3_i32 v214, v214, 0, v236
	v_lshl_add_u32 v214, v214, 2, v163
	ds_read_b32 v214, v214 offset:43264
	v_sub_u32_e32 v215, v162, v215
	v_med3_i32 v215, v215, 0, v236
	v_lshl_add_u32 v215, v215, 2, v163
	ds_read_b32 v215, v215 offset:43264
	v_sub_u32_e32 v216, v162, v216
	v_med3_i32 v216, v216, 0, v236
	v_lshl_add_u32 v216, v216, 2, v163
	ds_read_b32 v216, v216 offset:43264
	v_sub_u32_e32 v217, v162, v217
	v_med3_i32 v217, v217, 0, v236
	v_lshl_add_u32 v217, v217, 2, v163
	ds_read_b32 v217, v217 offset:43264
	v_sub_u32_e32 v218, v162, v218
	v_med3_i32 v218, v218, 0, v236
	v_lshl_add_u32 v218, v218, 2, v163
	ds_read_b32 v218, v218 offset:43264
	v_sub_u32_e32 v224, v162, v224
	v_med3_i32 v224, v224, 0, v236
	v_lshl_add_u32 v224, v224, 2, v163
	ds_read_b32 v224, v224 offset:43264
	v_sub_u32_e32 v225, v162, v225
	v_med3_i32 v225, v225, 0, v236
	v_lshl_add_u32 v225, v225, 2, v163
	ds_read_b32 v225, v225 offset:43264
	s_waitcnt lgkmcnt(0)
	v_fmac_f32_e32 v213, 0x3e0293ee, v80
	v_cndmask_b32_e64 v101, v101, v213, s[36:37]
.LBB0_714:
	v_or3_b32 v80, v3, s26, 33
	v_cmp_le_i32_e64 s[12:13], v80, v150
	s_and_b64 s[36:37], vcc, s[12:13]
	v_fmac_f32_e32 v214, 0x3e0293ee, v81
	v_cndmask_b32_e64 v100, v100, v214, s[36:37]
; DI int crow(int i, int h) { return (i & 3) + 8 * (i >> 2) + 4 * h; }
;   DI float score(float s, int, float, int t) const { return mine(t) ? s * sc + bfar : NEG; }
; template <int DK, bool PV, class SF, class PH>
; DI void attn_tile(const bf16x8 (&qf)[DK / 16], f32x16 (&o)[4], float& m, float& l, const char* smem, SF sf, PH ph) {
;     ...
;   for (int kb = 0; kb < 2; ++kb)
; #pragma unroll
;     for (int i = 0; i < 16; ++i) {
;       int kl = kb * 32 + crow(i, h);
;       float v = sf(s[kb][i], kl, auxs[kl]);
;       s[kb][i] = v;
;       mx = fmaxf(mx, v);
;     }
;   DI float score(float s, int key, float ax, int t) const {
;     bool valid = mine(t) && key <= tq;
;     int d = posq - __float_as_int(ax);
;     d = d < 0 ? 0 : (d > 799 ? 799 : d);
;     return valid ? s * sc + lutr[d] : NEG;
;   }
.LBB0_716:
	v_or3_b32 v80, v3, s26, 34
	v_cmp_le_i32_e64 s[12:13], v80, v150
	s_and_b64 s[36:37], vcc, s[12:13]
	v_mov_b32_e32 v80, 0xf149f2ca
	v_mov_b32_e32 v81, 0xf149f2ca
	v_fmac_f32_e32 v215, 0x3e0293ee, v82
	v_cndmask_b32_e64 v81, v81, v215, s[36:37]
.LBB0_718:
	v_or3_b32 v82, v3, s26, 35
	v_cmp_le_i32_e64 s[12:13], v82, v150
	s_and_b64 s[36:37], vcc, s[12:13]
	v_fmac_f32_e32 v216, 0x3e0293ee, v83
	v_cndmask_b32_e64 v80, v80, v216, s[36:37]
.LBB0_720:
	v_or3_b32 v82, v3, s26, 40
	v_cmp_le_i32_e64 s[12:13], v82, v150
	s_and_b64 s[36:37], vcc, s[12:13]
	v_mov_b32_e32 v82, 0xf149f2ca
	v_mov_b32_e32 v83, 0xf149f2ca
	v_fmac_f32_e32 v217, 0x3e0293ee, v84
	v_cndmask_b32_e64 v83, v83, v217, s[36:37]
.LBB0_722:
	v_or3_b32 v84, v3, s26, 41
	v_cmp_le_i32_e64 s[12:13], v84, v150
	s_and_b64 s[36:37], vcc, s[12:13]
	v_fmac_f32_e32 v218, 0x3e0293ee, v85
	v_cndmask_b32_e64 v82, v82, v218, s[36:37]
.LBB0_724:
	v_or3_b32 v84, v3, s26, 42
	v_cmp_le_i32_e64 s[12:13], v84, v150
	s_and_b64 s[36:37], vcc, s[12:13]
	v_mov_b32_e32 v84, 0xf149f2ca
	v_mov_b32_e32 v102, 0xf149f2ca
	v_fmac_f32_e32 v224, 0x3e0293ee, v86
	v_cndmask_b32_e64 v102, v102, v224, s[36:37]
.LBB0_726:
	v_or3_b32 v85, v3, s26, 43
	v_cmp_le_i32_e64 s[12:13], v85, v150
	s_and_b64 s[36:37], vcc, s[12:13]
	v_fmac_f32_e32 v225, 0x3e0293ee, v87
	v_cndmask_b32_e64 v84, v84, v225, s[36:37]
.LBB0_728:
	v_or3_b32 v85, v3, s26, 48
	v_cmp_le_i32_e64 s[12:13], v85, v150
	s_and_b64 s[36:37], vcc, s[12:13]
	v_mov_b32_e32 v103, 0xf149f2ca
	v_mov_b32_e32 v104, 0xf149f2ca
	ds_read_b32 v213, v226 offset:43200
	ds_read_b32 v214, v226 offset:43204
	ds_read_b32 v215, v226 offset:43208
	ds_read_b32 v216, v226 offset:43212
	ds_read_b32 v217, v226 offset:43232
	ds_read_b32 v218, v226 offset:43236
	ds_read_b32 v224, v226 offset:43240
	ds_read_b32 v225, v226 offset:43244
	s_waitcnt lgkmcnt(0)
	v_sub_u32_e32 v213, v162, v213
	v_med3_i32 v213, v213, 0, v236
	v_lshl_add_u32 v213, v213, 2, v163
	ds_read_b32 v213, v213 offset:43264
	v_sub_u32_e32 v214, v162, v214
	v_med3_i32 v214, v214, 0, v236
	v_lshl_add_u32 v214, v214, 2, v163
	ds_read_b32 v214, v214 offset:43264
	v_sub_u32_e32 v215, v162, v215
	v_med3_i32 v215, v215, 0, v236
	v_lshl_add_u32 v215, v215, 2, v163
	ds_read_b32 v215, v215 offset:43264
	v_sub_u32_e32 v216, v162, v216
	v_med3_i32 v216, v216, 0, v236
	v_lshl_add_u32 v216, v216, 2, v163
	ds_read_b32 v216, v216 offset:43264
	v_sub_u32_e32 v217, v162, v217
	v_med3_i32 v217, v217, 0, v236
	v_lshl_add_u32 v217, v217, 2, v163
	ds_read_b32 v217, v217 offset:43264
	v_sub_u32_e32 v218, v162, v218
	v_med3_i32 v218, v218, 0, v236
	v_lshl_add_u32 v218, v218, 2, v163
	ds_read_b32 v218, v218 offset:43264
	v_sub_u32_e32 v224, v162, v224
	v_med3_i32 v224, v224, 0, v236
	v_lshl_add_u32 v224, v224, 2, v163
	ds_read_b32 v224, v224 offset:43264
	v_sub_u32_e32 v225, v162, v225
	v_med3_i32 v225, v225, 0, v236
	v_lshl_add_u32 v225, v225, 2, v163
	ds_read_b32 v225, v225 offset:43264
	s_waitcnt lgkmcnt(0)
	v_fmac_f32_e32 v213, 0x3e0293ee, v88
	v_cndmask_b32_e64 v104, v104, v213, s[36:37]
.LBB0_730:
	v_or3_b32 v85, v3, s26, 49
	v_cmp_le_i32_e64 s[12:13], v85, v150
	s_and_b64 s[36:37], vcc, s[12:13]
	v_fmac_f32_e32 v214, 0x3e0293ee, v89
	v_cndmask_b32_e64 v103, v103, v214, s[36:37]
.LBB0_732:
	v_or3_b32 v85, v3, s26, 50
	v_cmp_le_i32_e64 s[12:13], v85, v150
	s_and_b64 s[36:37], vcc, s[12:13]
	v_mov_b32_e32 v105, 0xf149f2ca
	v_mov_b32_e32 v106, 0xf149f2ca
	v_fmac_f32_e32 v215, 0x3e0293ee, v90
	v_cndmask_b32_e64 v106, v106, v215, s[36:37]
; DI int crow(int i, int h) { return (i & 3) + 8 * (i >> 2) + 4 * h; }
; DI float ex2(float x) { return __builtin_amdgcn_exp2f(x); }
;   DI float score(float s, int, float, int t) const { return mine(t) ? s * sc + bfar : NEG; }
; template <int DK, bool PV, class SF, class PH>
; DI void attn_tile(const bf16x8 (&qf)[DK / 16], f32x16 (&o)[4], float& m, float& l, const char* smem, SF sf, PH ph) {
;     ...
;   float mx = m;
; #pragma unroll
;   for (int kb = 0; kb < 2; ++kb)
; #pragma unroll
;     for (int i = 0; i < 16; ++i) {
;       int kl = kb * 32 + crow(i, h);
;       float v = sf(s[kb][i], kl, auxs[kl]);
;       s[kb][i] = v;
;       mx = fmaxf(mx, v);
;     }
;   mx = fmaxf(mx, __shfl_xor(mx, 32));
;   float alpha = ex2(m - mx);
;   m = mx;
;   float psum = 0.f;
; #pragma unroll
;   for (int kb = 0; kb < 2; ++kb)
; #pragma unroll
;     for (int i = 0; i < 16; ++i) {
;       float pv = ex2(s[kb][i] - mx);
;       s[kb][i] = pv;
;       psum += pv;
;     }
;   l = l * alpha + psum;
;   ph(0, s[0]);
;   ph(1, s[1]);
;   if (PV) {
;     if (__builtin_amdgcn_ballot_w64(alpha != 1.f) != 0ull) {
; #pragma unroll
;       for (int d = 0; d < 4; ++d)
; #pragma unroll
;         for (int i = 0; i < 16; ++i) o[d][i] *= alpha;
;   DI float score(float s, int key, float ax, int t) const {
;     bool valid = mine(t) && key <= tq;
;     int d = posq - __float_as_int(ax);
;     d = d < 0 ? 0 : (d > 799 ? 799 : d);
;     return valid ? s * sc + lutr[d] : NEG;
;   }
.LBB0_734:
	v_or3_b32 v85, v3, s26, 51
	v_cmp_le_i32_e64 s[12:13], v85, v150
	s_and_b64 s[36:37], vcc, s[12:13]
	v_fmac_f32_e32 v216, 0x3e0293ee, v91
	v_cndmask_b32_e64 v105, v105, v216, s[36:37]
.LBB0_736:
	v_or3_b32 v85, v3, s26, 56
	v_cmp_le_i32_e64 s[12:13], v85, v150
	s_and_b64 s[36:37], vcc, s[12:13]
	v_mov_b32_e32 v107, 0xf149f2ca
	v_mov_b32_e32 v108, 0xf149f2ca
	v_fmac_f32_e32 v217, 0x3e0293ee, v92
	v_cndmask_b32_e64 v108, v108, v217, s[36:37]
.LBB0_738:
	v_or3_b32 v85, v3, s26, 57
	v_cmp_le_i32_e64 s[12:13], v85, v150
	s_and_b64 s[36:37], vcc, s[12:13]
	v_fmac_f32_e32 v218, 0x3e0293ee, v93
	v_cndmask_b32_e64 v107, v107, v218, s[36:37]
.LBB0_740:
	v_or3_b32 v85, v3, s26, 58
	v_cmp_le_i32_e64 s[12:13], v85, v150
	s_and_b64 s[36:37], vcc, s[12:13]
	v_mov_b32_e32 v93, 0xf149f2ca
	v_mov_b32_e32 v109, 0xf149f2ca
	v_fmac_f32_e32 v224, 0x3e0293ee, v94
	v_cndmask_b32_e64 v109, v109, v224, s[36:37]
.LBB0_742:
	v_or3_b32 v85, v3, s26, 59
	v_cmp_le_i32_e64 s[12:13], v85, v150
	s_and_b64 s[36:37], vcc, s[12:13]
	v_fmac_f32_e32 v225, 0x3e0293ee, v95
	v_cndmask_b32_e64 v93, v93, v225, s[36:37]
.LBB0_744:
	v_max3_f32 v0, v177, v5, v4
	v_max3_f32 v0, v0, v7, v6
	v_max3_f32 v0, v0, v9, v8
	v_max3_f32 v0, v0, v11, v10
	v_max3_f32 v0, v0, v13, v12
	v_max3_f32 v0, v0, v15, v14
	v_max3_f32 v0, v0, v97, v96
	v_max3_f32 v0, v0, v99, v98
	v_max3_f32 v0, v0, v101, v100
	v_max3_f32 v0, v0, v81, v80
	v_max3_f32 v0, v0, v83, v82
	v_max3_f32 v0, v0, v102, v84
	v_max3_f32 v0, v0, v104, v103
	v_max3_f32 v0, v0, v106, v105
	v_max3_f32 v0, v0, v108, v107
	v_max3_f32 v0, v0, v109, v93
	ds_bpermute_b32 v85, v164, v0
	s_waitcnt lgkmcnt(0)
	v_max_f32_e32 v85, v85, v85
	v_max_f32_e32 v176, v0, v85
	v_sub_f32_e32 v0, v177, v176
	v_exp_f32_e32 v0, v0
	s_nop 0
	v_cmp_neq_f32_e32 vcc, 1.0, v0
	s_cbranch_vccz .LBB0_746
	v_pk_mul_f32 v[78:79], v[78:79], v[0:1] op_sel_hi:[1,0]
	v_pk_mul_f32 v[76:77], v[76:77], v[0:1] op_sel_hi:[1,0]
	v_pk_mul_f32 v[74:75], v[74:75], v[0:1] op_sel_hi:[1,0]
	v_pk_mul_f32 v[72:73], v[72:73], v[0:1] op_sel_hi:[1,0]
	v_pk_mul_f32 v[70:71], v[70:71], v[0:1] op_sel_hi:[1,0]
	v_pk_mul_f32 v[68:69], v[68:69], v[0:1] op_sel_hi:[1,0]
	v_pk_mul_f32 v[66:67], v[66:67], v[0:1] op_sel_hi:[1,0]
	v_pk_mul_f32 v[64:65], v[64:65], v[0:1] op_sel_hi:[1,0]
	v_pk_mul_f32 v[62:63], v[62:63], v[0:1] op_sel_hi:[1,0]
	v_pk_mul_f32 v[60:61], v[60:61], v[0:1] op_sel_hi:[1,0]
	v_pk_mul_f32 v[58:59], v[58:59], v[0:1] op_sel_hi:[1,0]
	v_pk_mul_f32 v[56:57], v[56:57], v[0:1] op_sel_hi:[1,0]
	v_pk_mul_f32 v[54:55], v[54:55], v[0:1] op_sel_hi:[1,0]
	v_pk_mul_f32 v[52:53], v[52:53], v[0:1] op_sel_hi:[1,0]
	v_pk_mul_f32 v[50:51], v[50:51], v[0:1] op_sel_hi:[1,0]
	v_pk_mul_f32 v[48:49], v[48:49], v[0:1] op_sel_hi:[1,0]
	v_pk_mul_f32 v[46:47], v[46:47], v[0:1] op_sel_hi:[1,0]
	v_pk_mul_f32 v[44:45], v[44:45], v[0:1] op_sel_hi:[1,0]
	v_pk_mul_f32 v[42:43], v[42:43], v[0:1] op_sel_hi:[1,0]
	v_pk_mul_f32 v[40:41], v[40:41], v[0:1] op_sel_hi:[1,0]
	v_pk_mul_f32 v[38:39], v[38:39], v[0:1] op_sel_hi:[1,0]
	v_pk_mul_f32 v[36:37], v[36:37], v[0:1] op_sel_hi:[1,0]
	v_pk_mul_f32 v[34:35], v[34:35], v[0:1] op_sel_hi:[1,0]
	v_pk_mul_f32 v[32:33], v[32:33], v[0:1] op_sel_hi:[1,0]
	v_pk_mul_f32 v[30:31], v[30:31], v[0:1] op_sel_hi:[1,0]
	v_pk_mul_f32 v[28:29], v[28:29], v[0:1] op_sel_hi:[1,0]
	v_pk_mul_f32 v[26:27], v[26:27], v[0:1] op_sel_hi:[1,0]
	v_pk_mul_f32 v[24:25], v[24:25], v[0:1] op_sel_hi:[1,0]
	v_pk_mul_f32 v[22:23], v[22:23], v[0:1] op_sel_hi:[1,0]
	v_pk_mul_f32 v[20:21], v[20:21], v[0:1] op_sel_hi:[1,0]
	v_pk_mul_f32 v[18:19], v[18:19], v[0:1] op_sel_hi:[1,0]
	v_pk_mul_f32 v[16:17], v[16:17], v[0:1] op_sel_hi:[1,0]

; #define MFMA32(a, b, c) __builtin_amdgcn_mfma_f32_32x32x16_bf16((a), (b), (c), 0, 0, 0)
; DI int crow(int i, int h) { return (i & 3) + 8 * (i >> 2) + 4 * h; }
;   DI float score(float s, int, float, int t) const { return mine(t) ? s * sc + bfar : NEG; }
; template <int DK, bool PV, class SF, class PH>
; DI void attn_tile(const bf16x8 (&qf)[DK / 16], f32x16 (&o)[4], float& m, float& l, const char* smem, SF sf, PH ph) {
;     ...
;   for (int kb = 0; kb < 2; ++kb) {
; #pragma unroll
;     for (int i = 0; i < 16; ++i) s[kb][i] = 0.f;
; #pragma unroll
;     for (int ks = 0; ks < DK / 16; ++ks) {
;       bf16x8 a = *(const bf16x8*)(Ks + (kb * 32 + r) * (DK + 8) + ks * 16 + h * 8);
;       s[kb] = MFMA32(a, qf[ks], s[kb]);
;     }
;   }
;   float mx = m;
; #pragma unroll
;   for (int kb = 0; kb < 2; ++kb)
; #pragma unroll
;     for (int i = 0; i < 16; ++i) {
;       int kl = kb * 32 + crow(i, h);
;       float v = sf(s[kb][i], kl, auxs[kl]);
;       s[kb][i] = v;
;       mx = fmaxf(mx, v);
;     }
;   DI float score(float s, int key, float ax, int) const {
;     bool valid = key <= tq && (tq - key) < 512;
;     int d = posq - __float_as_int(ax);
;     d = d < 0 ? 0 : (d > 799 ? 799 : d);
;     return valid ? s * sc + lutr[d] : NEG;
;   }
.LBB0_779:
	s_or_b64 exec, exec, s[6:7]
	s_waitcnt vmcnt(7)
	ds_write_b128 v147, v[2:5]
	s_waitcnt vmcnt(6)
	ds_write_b128 v151, v[6:9]
	s_waitcnt vmcnt(5)
	ds_write_b128 v160, v[10:13]
	s_waitcnt vmcnt(4)
	ds_write_b128 v161, v[80:83]
	s_waitcnt vmcnt(3)
	ds_write2_b64 v165, v[84:85], v[86:87] offset1:1
	s_waitcnt vmcnt(2)
	ds_write2_b64 v166, v[88:89], v[90:91] offset1:1
	s_waitcnt vmcnt(1)
	ds_write2_b64 v167, v[92:93], v[94:95] offset1:1
	s_waitcnt vmcnt(0)
	ds_write2_b64 v168, v[96:97], v[98:99] offset1:1
	s_and_saveexec_b64 s[6:7], s[10:11]
	ds_write_b32 v145, v0 offset:43008
	s_or_b64 exec, exec, s[6:7]
	s_waitcnt lgkmcnt(0)
	s_barrier
	s_mov_b32 s6, 0
	s_nop 0
	v_add_u32_e32 v0, s6, v189
	v_and_b32_e32 v2, 31, v0
	v_lshrrev_b32_e32 v0, 5, v0
	v_and_b32_e32 v0, 1, v0
	v_lshlrev_b32_e32 v11, 4, v0
	v_mad_u32_u24 v3, v2, s73, v11
	ds_read_b128 v[4:7], v3
	ds_read_b128 v[12:15], v3 offset:32
	s_waitcnt lgkmcnt(1)
	v_mfma_f32_32x32x16_bf16 v[96:111], v[4:7], v[136:139], 0
	ds_read_b128 v[4:7], v3 offset:64
	s_waitcnt lgkmcnt(1)
	v_mfma_f32_32x32x16_bf16 v[96:111], v[12:15], v[112:115], v[96:111]
	s_waitcnt lgkmcnt(0)
	v_mfma_f32_32x32x16_bf16 v[96:111], v[4:7], v[116:119], v[96:111]
	ds_read_b128 v[4:7], v3 offset:96
	s_waitcnt lgkmcnt(0)
	v_mfma_f32_32x32x16_bf16 v[96:111], v[4:7], v[120:123], v[96:111]
	ds_read_b128 v[4:7], v3 offset:128
	s_waitcnt lgkmcnt(0)
	v_mfma_f32_32x32x16_bf16 v[96:111], v[4:7], v[124:127], v[96:111]
	ds_read_b128 v[4:7], v3 offset:160
	s_waitcnt lgkmcnt(0)
	v_mfma_f32_32x32x16_bf16 v[96:111], v[4:7], v[128:131], v[96:111]
	ds_read_b128 v[4:7], v3 offset:192
	s_waitcnt lgkmcnt(0)
	v_mfma_f32_32x32x16_bf16 v[96:111], v[4:7], v[132:135], v[96:111]
	ds_read_b128 v[4:7], v3 offset:224
	s_waitcnt lgkmcnt(0)
	v_mfma_f32_32x32x16_bf16 v[96:111], v[4:7], v[140:143], v[96:111]
	ds_read_b128 v[4:7], v3 offset:8704
	s_waitcnt lgkmcnt(0)
	v_mfma_f32_32x32x16_bf16 v[80:95], v[4:7], v[136:139], 0
	ds_read_b128 v[4:7], v3 offset:8736
	s_waitcnt lgkmcnt(0)
	v_mfma_f32_32x32x16_bf16 v[80:95], v[4:7], v[112:115], v[80:95]
	ds_read_b128 v[4:7], v3 offset:8768
	s_waitcnt lgkmcnt(0)
	v_mfma_f32_32x32x16_bf16 v[80:95], v[4:7], v[116:119], v[80:95]
	ds_read_b128 v[4:7], v3 offset:8800
	s_waitcnt lgkmcnt(0)
	v_mfma_f32_32x32x16_bf16 v[80:95], v[4:7], v[120:123], v[80:95]
	ds_read_b128 v[4:7], v3 offset:8832
	s_waitcnt lgkmcnt(0)
	v_mfma_f32_32x32x16_bf16 v[80:95], v[4:7], v[124:127], v[80:95]
	ds_read_b128 v[4:7], v3 offset:8864
	s_waitcnt lgkmcnt(0)
	v_mfma_f32_32x32x16_bf16 v[80:95], v[4:7], v[128:131], v[80:95]
	ds_read_b128 v[4:7], v3 offset:8896
	s_waitcnt lgkmcnt(0)
	v_mfma_f32_32x32x16_bf16 v[80:95], v[4:7], v[132:135], v[80:95]
	ds_read_b128 v[4:7], v3 offset:8928
	s_waitcnt lgkmcnt(0)
	v_mfma_f32_32x32x16_bf16 v[80:95], v[4:7], v[140:143], v[80:95]
	v_lshlrev_b32_e32 v4, 2, v0
	v_add_u32_e32 v0, s26, v4
	v_subrev_u32_e32 v3, 59, v0
	v_sub_u32_e32 v5, v146, v4
	v_cmp_le_i32_e32 vcc, v3, v150
	v_add_u32_e32 v3, 59, v5
	v_cmp_gt_i32_e64 s[12:13], s3, v3
	s_and_b64 s[12:13], vcc, s[12:13]
	v_mov_b32_e32 v3, 0xf149f2ca
	v_mov_b32_e32 v6, 0xf149f2ca
	v_and_b32_e32 v226, 32, v189
	v_lshrrev_b32_e32 v226, 1, v226
	ds_read_b32 v213, v226 offset:43008
	ds_read_b32 v214, v226 offset:43012
	ds_read_b32 v215, v226 offset:43016
	ds_read_b32 v216, v226 offset:43020
	ds_read_b32 v217, v226 offset:43040
	ds_read_b32 v218, v226 offset:43044
	ds_read_b32 v224, v226 offset:43048
	ds_read_b32 v225, v226 offset:43052
	s_waitcnt lgkmcnt(0)
	v_sub_u32_e32 v213, v162, v213
	v_med3_i32 v213, v213, 0, v236
	v_lshl_add_u32 v213, v213, 2, v163
	ds_read_b32 v213, v213 offset:43264
	v_sub_u32_e32 v214, v162, v214
	v_med3_i32 v214, v214, 0, v236
	v_lshl_add_u32 v214, v214, 2, v163
	ds_read_b32 v214, v214 offset:43264
	v_sub_u32_e32 v215, v162, v215
	v_med3_i32 v215, v215, 0, v236
	v_lshl_add_u32 v215, v215, 2, v163
	ds_read_b32 v215, v215 offset:43264
	v_sub_u32_e32 v216, v162, v216
	v_med3_i32 v216, v216, 0, v236
	v_lshl_add_u32 v216, v216, 2, v163
	ds_read_b32 v216, v216 offset:43264
	v_sub_u32_e32 v217, v162, v217
	v_med3_i32 v217, v217, 0, v236
	v_lshl_add_u32 v217, v217, 2, v163
	ds_read_b32 v217, v217 offset:43264
	v_sub_u32_e32 v218, v162, v218
	v_med3_i32 v218, v218, 0, v236
	v_lshl_add_u32 v218, v218, 2, v163
	ds_read_b32 v218, v218 offset:43264
	v_sub_u32_e32 v224, v162, v224
	v_med3_i32 v224, v224, 0, v236
	v_lshl_add_u32 v224, v224, 2, v163
	ds_read_b32 v224, v224 offset:43264
	v_sub_u32_e32 v225, v162, v225
	v_med3_i32 v225, v225, 0, v236
	v_lshl_add_u32 v225, v225, 2, v163
	ds_read_b32 v225, v225 offset:43264
	s_waitcnt lgkmcnt(0)
	v_fmac_f32_e32 v213, 0x3e0293ee, v96
	v_cndmask_b32_e64 v6, v6, v213, s[12:13]
.LBB0_783:
	v_subrev_u32_e32 v7, 58, v0
	v_cmp_le_i32_e32 vcc, v7, v150
	v_add_u32_e32 v7, 58, v5
	v_cmp_gt_i32_e64 s[12:13], s3, v7
	s_and_b64 s[12:13], vcc, s[12:13]
	v_fmac_f32_e32 v214, 0x3e0293ee, v97
	v_cndmask_b32_e64 v3, v3, v214, s[12:13]
.LBB0_785:
	v_subrev_u32_e32 v7, 57, v0
	v_cmp_le_i32_e32 vcc, v7, v150
	v_add_u32_e32 v7, 57, v5
	v_cmp_gt_i32_e64 s[12:13], s3, v7
	s_and_b64 s[12:13], vcc, s[12:13]
	v_mov_b32_e32 v7, 0xf149f2ca
	v_mov_b32_e32 v8, 0xf149f2ca
	v_fmac_f32_e32 v215, 0x3e0293ee, v98
	v_cndmask_b32_e64 v8, v8, v215, s[12:13]
.LBB0_787:
	v_subrev_u32_e32 v9, 56, v0
	v_cmp_le_i32_e32 vcc, v9, v150
	v_add_u32_e32 v9, 56, v5
	v_cmp_gt_i32_e64 s[12:13], s3, v9
	s_and_b64 s[12:13], vcc, s[12:13]
	v_fmac_f32_e32 v216, 0x3e0293ee, v99
	v_cndmask_b32_e64 v7, v7, v216, s[12:13]
; DI int crow(int i, int h) { return (i & 3) + 8 * (i >> 2) + 4 * h; }
;   DI float score(float s, int, float, int t) const { return mine(t) ? s * sc + bfar : NEG; }
; template <int DK, bool PV, class SF, class PH>
; DI void attn_tile(const bf16x8 (&qf)[DK / 16], f32x16 (&o)[4], float& m, float& l, const char* smem, SF sf, PH ph) {
;     ...
;   for (int kb = 0; kb < 2; ++kb)
; #pragma unroll
;     for (int i = 0; i < 16; ++i) {
;       int kl = kb * 32 + crow(i, h);
;       float v = sf(s[kb][i], kl, auxs[kl]);
;       s[kb][i] = v;
;       mx = fmaxf(mx, v);
;     }
;   DI float score(float s, int key, float ax, int) const {
;     bool valid = key <= tq && (tq - key) < 512;
;     int d = posq - __float_as_int(ax);
;     d = d < 0 ? 0 : (d > 799 ? 799 : d);
;     return valid ? s * sc + lutr[d] : NEG;
;   }
.LBB0_789:
	v_subrev_u32_e32 v9, 51, v0
	v_cmp_le_i32_e32 vcc, v9, v150
	v_add_u32_e32 v9, 51, v5
	v_cmp_gt_i32_e64 s[12:13], s3, v9
	s_and_b64 s[12:13], vcc, s[12:13]
	v_mov_b32_e32 v9, 0xf149f2ca
	v_mov_b32_e32 v10, 0xf149f2ca
	v_fmac_f32_e32 v217, 0x3e0293ee, v100
	v_cndmask_b32_e64 v10, v10, v217, s[12:13]
.LBB0_791:
	v_subrev_u32_e32 v12, 50, v0
	v_cmp_le_i32_e32 vcc, v12, v150
	v_add_u32_e32 v12, 50, v5
	v_cmp_gt_i32_e64 s[12:13], s3, v12
	s_and_b64 s[12:13], vcc, s[12:13]
	v_fmac_f32_e32 v218, 0x3e0293ee, v101
	v_cndmask_b32_e64 v9, v9, v218, s[12:13]
.LBB0_793:
	v_subrev_u32_e32 v11, 49, v0
	v_cmp_le_i32_e32 vcc, v11, v150
	v_add_u32_e32 v11, 49, v5
	v_cmp_gt_i32_e64 s[12:13], s3, v11
	s_and_b64 s[12:13], vcc, s[12:13]
	v_mov_b32_e32 v11, 0xf149f2ca
	v_lshlrev_b32_e32 v171, 2, v4
	v_mov_b32_e32 v12, 0xf149f2ca
	v_fmac_f32_e32 v224, 0x3e0293ee, v102
	v_cndmask_b32_e64 v12, v12, v224, s[12:13]
.LBB0_795:
	v_subrev_u32_e32 v13, 48, v0
	v_cmp_le_i32_e32 vcc, v13, v150
	v_add_u32_e32 v13, 48, v5
	v_cmp_gt_i32_e64 s[12:13], s3, v13
	s_and_b64 s[12:13], vcc, s[12:13]
	v_fmac_f32_e32 v225, 0x3e0293ee, v103
	v_cndmask_b32_e64 v11, v11, v225, s[12:13]
.LBB0_797:
	v_subrev_u32_e32 v13, 43, v0
	v_cmp_le_i32_e32 vcc, v13, v150
	v_add_u32_e32 v13, 43, v5
	v_cmp_gt_i32_e64 s[12:13], s3, v13
	s_and_b64 s[12:13], vcc, s[12:13]
	v_mov_b32_e32 v13, 0xf149f2ca
	v_mov_b32_e32 v14, 0xf149f2ca
	ds_read_b32 v213, v226 offset:43072
	ds_read_b32 v214, v226 offset:43076
	ds_read_b32 v215, v226 offset:43080
	ds_read_b32 v216, v226 offset:43084
	ds_read_b32 v217, v226 offset:43104
	ds_read_b32 v218, v226 offset:43108
	ds_read_b32 v224, v226 offset:43112
	ds_read_b32 v225, v226 offset:43116
	s_waitcnt lgkmcnt(0)
	v_sub_u32_e32 v213, v162, v213
	v_med3_i32 v213, v213, 0, v236
	v_lshl_add_u32 v213, v213, 2, v163
	ds_read_b32 v213, v213 offset:43264
	v_sub_u32_e32 v214, v162, v214
	v_med3_i32 v214, v214, 0, v236
	v_lshl_add_u32 v214, v214, 2, v163
	ds_read_b32 v214, v214 offset:43264
	v_sub_u32_e32 v215, v162, v215
	v_med3_i32 v215, v215, 0, v236
	v_lshl_add_u32 v215, v215, 2, v163
	ds_read_b32 v215, v215 offset:43264
	v_sub_u32_e32 v216, v162, v216
	v_med3_i32 v216, v216, 0, v236
	v_lshl_add_u32 v216, v216, 2, v163
	ds_read_b32 v216, v216 offset:43264
	v_sub_u32_e32 v217, v162, v217
	v_med3_i32 v217, v217, 0, v236
	v_lshl_add_u32 v217, v217, 2, v163
	ds_read_b32 v217, v217 offset:43264
	v_sub_u32_e32 v218, v162, v218
	v_med3_i32 v218, v218, 0, v236
	v_lshl_add_u32 v218, v218, 2, v163
	ds_read_b32 v218, v218 offset:43264
	v_sub_u32_e32 v224, v162, v224
	v_med3_i32 v224, v224, 0, v236
	v_lshl_add_u32 v224, v224, 2, v163
	ds_read_b32 v224, v224 offset:43264
	v_sub_u32_e32 v225, v162, v225
	v_med3_i32 v225, v225, 0, v236
	v_lshl_add_u32 v225, v225, 2, v163
	ds_read_b32 v225, v225 offset:43264
	s_waitcnt lgkmcnt(0)
	v_fmac_f32_e32 v213, 0x3e0293ee, v104
	v_cndmask_b32_e64 v14, v14, v213, s[12:13]
.LBB0_799:
	v_subrev_u32_e32 v15, 42, v0
	v_cmp_le_i32_e32 vcc, v15, v150
	v_add_u32_e32 v15, 42, v5
	v_cmp_gt_i32_e64 s[12:13], s3, v15
	s_and_b64 s[12:13], vcc, s[12:13]
	v_fmac_f32_e32 v214, 0x3e0293ee, v105
	v_cndmask_b32_e64 v13, v13, v214, s[12:13]
.LBB0_801:
	v_subrev_u32_e32 v15, 41, v0
	v_cmp_le_i32_e32 vcc, v15, v150
	v_add_u32_e32 v15, 41, v5
	v_cmp_gt_i32_e64 s[12:13], s3, v15
	s_and_b64 s[12:13], vcc, s[12:13]
	v_mov_b32_e32 v15, 0xf149f2ca
	v_mov_b32_e32 v96, 0xf149f2ca
	v_fmac_f32_e32 v215, 0x3e0293ee, v106
	v_cndmask_b32_e64 v96, v96, v215, s[12:13]
.LBB0_803:
	v_subrev_u32_e32 v97, 40, v0
	v_cmp_le_i32_e32 vcc, v97, v150
	v_add_u32_e32 v97, 40, v5
	v_cmp_gt_i32_e64 s[12:13], s3, v97
	s_and_b64 s[12:13], vcc, s[12:13]
	v_fmac_f32_e32 v216, 0x3e0293ee, v107
	v_cndmask_b32_e64 v15, v15, v216, s[12:13]
.LBB0_805:
	v_subrev_u32_e32 v97, 35, v0
	v_cmp_le_i32_e32 vcc, v97, v150
	v_add_u32_e32 v97, 35, v5
	v_cmp_gt_i32_e64 s[12:13], s3, v97
	s_and_b64 s[12:13], vcc, s[12:13]
	v_mov_b32_e32 v97, 0xf149f2ca
	v_mov_b32_e32 v98, 0xf149f2ca
	v_fmac_f32_e32 v217, 0x3e0293ee, v108
	v_cndmask_b32_e64 v98, v98, v217, s[12:13]
.LBB0_807:
	v_subrev_u32_e32 v99, 34, v0
	v_cmp_le_i32_e32 vcc, v99, v150
	v_add_u32_e32 v99, 34, v5
	v_cmp_gt_i32_e64 s[12:13], s3, v99
	s_and_b64 s[12:13], vcc, s[12:13]
	v_fmac_f32_e32 v218, 0x3e0293ee, v109
	v_cndmask_b32_e64 v97, v97, v218, s[12:13]
.LBB0_809:
	v_subrev_u32_e32 v99, 33, v0
	v_cmp_le_i32_e32 vcc, v99, v150
	v_add_u32_e32 v99, 33, v5
	v_cmp_gt_i32_e64 s[12:13], s3, v99
	s_and_b64 s[12:13], vcc, s[12:13]
	v_mov_b32_e32 v99, 0xf149f2ca
	v_mov_b32_e32 v100, 0xf149f2ca
	v_fmac_f32_e32 v224, 0x3e0293ee, v110
	v_cndmask_b32_e64 v100, v100, v224, s[12:13]
.LBB0_811:
	v_subrev_u32_e32 v101, 32, v0
	v_cmp_le_i32_e32 vcc, v101, v150
	v_add_u32_e32 v101, 32, v5
	v_cmp_gt_i32_e64 s[12:13], s3, v101
	s_and_b64 s[12:13], vcc, s[12:13]
	v_fmac_f32_e32 v225, 0x3e0293ee, v111
	v_cndmask_b32_e64 v99, v99, v225, s[12:13]
; DI int crow(int i, int h) { return (i & 3) + 8 * (i >> 2) + 4 * h; }
;   DI float score(float s, int, float, int t) const { return mine(t) ? s * sc + bfar : NEG; }
; template <int DK, bool PV, class SF, class PH>
; DI void attn_tile(const bf16x8 (&qf)[DK / 16], f32x16 (&o)[4], float& m, float& l, const char* smem, SF sf, PH ph) {
;     ...
;   for (int kb = 0; kb < 2; ++kb)
; #pragma unroll
;     for (int i = 0; i < 16; ++i) {
;       int kl = kb * 32 + crow(i, h);
;       float v = sf(s[kb][i], kl, auxs[kl]);
;       s[kb][i] = v;
;       mx = fmaxf(mx, v);
;     }
;   DI float score(float s, int key, float ax, int) const {
;     bool valid = key <= tq && (tq - key) < 512;
;     int d = posq - __float_as_int(ax);
;     d = d < 0 ? 0 : (d > 799 ? 799 : d);
;     return valid ? s * sc + lutr[d] : NEG;
;   }
.LBB0_813:
	v_subrev_u32_e32 v101, 27, v0
	v_cmp_le_i32_e32 vcc, v101, v150
	v_add_u32_e32 v101, 27, v5
	v_cmp_gt_i32_e64 s[12:13], s3, v101
	s_and_b64 s[12:13], vcc, s[12:13]
	v_mov_b32_e32 v101, 0xf149f2ca
	v_mov_b32_e32 v102, 0xf149f2ca
	ds_read_b32 v213, v226 offset:43136
	ds_read_b32 v214, v226 offset:43140
	ds_read_b32 v215, v226 offset:43144
	ds_read_b32 v216, v226 offset:43148
	ds_read_b32 v217, v226 offset:43168
	ds_read_b32 v218, v226 offset:43172
	ds_read_b32 v224, v226 offset:43176
	ds_read_b32 v225, v226 offset:43180
	s_waitcnt lgkmcnt(0)
	v_sub_u32_e32 v213, v162, v213
	v_med3_i32 v213, v213, 0, v236
	v_lshl_add_u32 v213, v213, 2, v163
	ds_read_b32 v213, v213 offset:43264
	v_sub_u32_e32 v214, v162, v214
	v_med3_i32 v214, v214, 0, v236
	v_lshl_add_u32 v214, v214, 2, v163
	ds_read_b32 v214, v214 offset:43264
	v_sub_u32_e32 v215, v162, v215
	v_med3_i32 v215, v215, 0, v236
	v_lshl_add_u32 v215, v215, 2, v163
	ds_read_b32 v215, v215 offset:43264
	v_sub_u32_e32 v216, v162, v216
	v_med3_i32 v216, v216, 0, v236
	v_lshl_add_u32 v216, v216, 2, v163
	ds_read_b32 v216, v216 offset:43264
	v_sub_u32_e32 v217, v162, v217
	v_med3_i32 v217, v217, 0, v236
	v_lshl_add_u32 v217, v217, 2, v163
	ds_read_b32 v217, v217 offset:43264
	v_sub_u32_e32 v218, v162, v218
	v_med3_i32 v218, v218, 0, v236
	v_lshl_add_u32 v218, v218, 2, v163
	ds_read_b32 v218, v218 offset:43264
	v_sub_u32_e32 v224, v162, v224
	v_med3_i32 v224, v224, 0, v236
	v_lshl_add_u32 v224, v224, 2, v163
	ds_read_b32 v224, v224 offset:43264
	v_sub_u32_e32 v225, v162, v225
	v_med3_i32 v225, v225, 0, v236
	v_lshl_add_u32 v225, v225, 2, v163
	ds_read_b32 v225, v225 offset:43264
	s_waitcnt lgkmcnt(0)
	v_fmac_f32_e32 v213, 0x3e0293ee, v80
	v_cndmask_b32_e64 v102, v102, v213, s[12:13]
.LBB0_815:
	v_subrev_u32_e32 v80, 26, v0
	v_cmp_le_i32_e32 vcc, v80, v150
	v_add_u32_e32 v80, 26, v5
	v_cmp_gt_i32_e64 s[12:13], s3, v80
	s_and_b64 s[12:13], vcc, s[12:13]
	v_fmac_f32_e32 v214, 0x3e0293ee, v81
	v_cndmask_b32_e64 v101, v101, v214, s[12:13]
.LBB0_817:
	v_subrev_u32_e32 v80, 25, v0
	v_cmp_le_i32_e32 vcc, v80, v150
	v_add_u32_e32 v80, 25, v5
	v_cmp_gt_i32_e64 s[12:13], s3, v80
	s_and_b64 s[12:13], vcc, s[12:13]
	v_mov_b32_e32 v81, 0xf149f2ca
	v_mov_b32_e32 v80, 0xf149f2ca
	v_fmac_f32_e32 v215, 0x3e0293ee, v82
	v_cndmask_b32_e64 v80, v80, v215, s[12:13]
.LBB0_819:
	v_subrev_u32_e32 v82, 24, v0
	v_cmp_le_i32_e32 vcc, v82, v150
	v_add_u32_e32 v82, 24, v5
	v_cmp_gt_i32_e64 s[12:13], s3, v82
	s_and_b64 s[12:13], vcc, s[12:13]
	v_fmac_f32_e32 v216, 0x3e0293ee, v83
	v_cndmask_b32_e64 v81, v81, v216, s[12:13]
.LBB0_821:
	v_subrev_u32_e32 v82, 19, v0
	v_cmp_le_i32_e32 vcc, v82, v150
	v_add_u32_e32 v82, 19, v5
	v_cmp_gt_i32_e64 s[12:13], s3, v82
	s_and_b64 s[12:13], vcc, s[12:13]
	v_mov_b32_e32 v83, 0xf149f2ca
	v_mov_b32_e32 v82, 0xf149f2ca
	v_fmac_f32_e32 v217, 0x3e0293ee, v84
	v_cndmask_b32_e64 v82, v82, v217, s[12:13]
.LBB0_823:
	v_subrev_u32_e32 v84, 18, v0
	v_cmp_le_i32_e32 vcc, v84, v150
	v_add_u32_e32 v84, 18, v5
	v_cmp_gt_i32_e64 s[12:13], s3, v84
	s_and_b64 s[12:13], vcc, s[12:13]
	v_fmac_f32_e32 v218, 0x3e0293ee, v85
	v_cndmask_b32_e64 v83, v83, v218, s[12:13]
.LBB0_825:
	v_subrev_u32_e32 v84, 17, v0
	v_cmp_le_i32_e32 vcc, v84, v150
	v_add_u32_e32 v84, 17, v5
	v_cmp_gt_i32_e64 s[12:13], s3, v84
	s_and_b64 s[12:13], vcc, s[12:13]
	v_mov_b32_e32 v85, 0xf149f2ca
	v_mov_b32_e32 v84, 0xf149f2ca
	v_fmac_f32_e32 v224, 0x3e0293ee, v86
	v_cndmask_b32_e64 v84, v84, v224, s[12:13]
.LBB0_827:
	v_add_u32_e32 v86, -16, v0
	v_cmp_le_i32_e32 vcc, v86, v150
	v_add_u32_e32 v86, 16, v5
	v_cmp_gt_i32_e64 s[12:13], s3, v86
	s_and_b64 s[12:13], vcc, s[12:13]
	v_fmac_f32_e32 v225, 0x3e0293ee, v87
	v_cndmask_b32_e64 v85, v85, v225, s[12:13]
.LBB0_829:
	v_add_u32_e32 v86, -11, v0
	v_cmp_le_i32_e32 vcc, v86, v150
	v_add_u32_e32 v86, 11, v5
	v_cmp_gt_i32_e64 s[12:13], s3, v86
	s_and_b64 s[12:13], vcc, s[12:13]
	v_mov_b32_e32 v103, 0xf149f2ca
	v_mov_b32_e32 v104, 0xf149f2ca
	ds_read_b32 v213, v226 offset:43200
	ds_read_b32 v214, v226 offset:43204
	ds_read_b32 v215, v226 offset:43208
	ds_read_b32 v216, v226 offset:43212
	ds_read_b32 v217, v226 offset:43232
	ds_read_b32 v218, v226 offset:43236
	ds_read_b32 v224, v226 offset:43240
	ds_read_b32 v225, v226 offset:43244
	s_waitcnt lgkmcnt(0)
	v_sub_u32_e32 v213, v162, v213
	v_med3_i32 v213, v213, 0, v236
	v_lshl_add_u32 v213, v213, 2, v163
	ds_read_b32 v213, v213 offset:43264
	v_sub_u32_e32 v214, v162, v214
	v_med3_i32 v214, v214, 0, v236
	v_lshl_add_u32 v214, v214, 2, v163
	ds_read_b32 v214, v214 offset:43264
	v_sub_u32_e32 v215, v162, v215
	v_med3_i32 v215, v215, 0, v236
	v_lshl_add_u32 v215, v215, 2, v163
	ds_read_b32 v215, v215 offset:43264
	v_sub_u32_e32 v216, v162, v216
	v_med3_i32 v216, v216, 0, v236
	v_lshl_add_u32 v216, v216, 2, v163
	ds_read_b32 v216, v216 offset:43264
	v_sub_u32_e32 v217, v162, v217
	v_med3_i32 v217, v217, 0, v236
	v_lshl_add_u32 v217, v217, 2, v163
	ds_read_b32 v217, v217 offset:43264
	v_sub_u32_e32 v218, v162, v218
	v_med3_i32 v218, v218, 0, v236
	v_lshl_add_u32 v218, v218, 2, v163
	ds_read_b32 v218, v218 offset:43264
	v_sub_u32_e32 v224, v162, v224
	v_med3_i32 v224, v224, 0, v236
	v_lshl_add_u32 v224, v224, 2, v163
	ds_read_b32 v224, v224 offset:43264
	v_sub_u32_e32 v225, v162, v225
	v_med3_i32 v225, v225, 0, v236
	v_lshl_add_u32 v225, v225, 2, v163
	ds_read_b32 v225, v225 offset:43264
	s_waitcnt lgkmcnt(0)
	v_fmac_f32_e32 v213, 0x3e0293ee, v88
	v_cndmask_b32_e64 v104, v104, v213, s[12:13]
; DI int crow(int i, int h) { return (i & 3) + 8 * (i >> 2) + 4 * h; }
; DI float ex2(float x) { return __builtin_amdgcn_exp2f(x); }
;   DI float score(float s, int, float, int t) const { return mine(t) ? s * sc + bfar : NEG; }
; template <int DK, bool PV, class SF, class PH>
; DI void attn_tile(const bf16x8 (&qf)[DK / 16], f32x16 (&o)[4], float& m, float& l, const char* smem, SF sf, PH ph) {
;     ...
;   float mx = m;
; #pragma unroll
;   for (int kb = 0; kb < 2; ++kb)
; #pragma unroll
;     for (int i = 0; i < 16; ++i) {
;       int kl = kb * 32 + crow(i, h);
;       float v = sf(s[kb][i], kl, auxs[kl]);
;       s[kb][i] = v;
;       mx = fmaxf(mx, v);
;     }
;   mx = fmaxf(mx, __shfl_xor(mx, 32));
;   float alpha = ex2(m - mx);
;   m = mx;
;   float psum = 0.f;
; #pragma unroll
;   for (int kb = 0; kb < 2; ++kb)
; #pragma unroll
;     for (int i = 0; i < 16; ++i) {
;       float pv = ex2(s[kb][i] - mx);
;       s[kb][i] = pv;
;       psum += pv;
;     }
;   l = l * alpha + psum;
;   ph(0, s[0]);
;   ph(1, s[1]);
;   if (PV) {
;     if (__builtin_amdgcn_ballot_w64(alpha != 1.f) != 0ull) {
; #pragma unroll
;       for (int d = 0; d < 4; ++d)
; #pragma unroll
;         for (int i = 0; i < 16; ++i) o[d][i] *= alpha;
;   DI float score(float s, int key, float ax, int) const {
;     bool valid = key <= tq && (tq - key) < 512;
;     int d = posq - __float_as_int(ax);
;     d = d < 0 ? 0 : (d > 799 ? 799 : d);
;     return valid ? s * sc + lutr[d] : NEG;
;   }
.LBB0_831:
	v_add_u32_e32 v86, -10, v0
	v_cmp_le_i32_e32 vcc, v86, v150
	v_add_u32_e32 v86, 10, v5
	v_cmp_gt_i32_e64 s[12:13], s3, v86
	s_and_b64 s[12:13], vcc, s[12:13]
	v_fmac_f32_e32 v214, 0x3e0293ee, v89
	v_cndmask_b32_e64 v103, v103, v214, s[12:13]
.LBB0_833:
	v_add_u32_e32 v86, -9, v0
	v_cmp_le_i32_e32 vcc, v86, v150
	v_add_u32_e32 v86, 9, v5
	v_cmp_gt_i32_e64 s[12:13], s3, v86
	s_and_b64 s[12:13], vcc, s[12:13]
	v_mov_b32_e32 v105, 0xf149f2ca
	v_mov_b32_e32 v106, 0xf149f2ca
	v_fmac_f32_e32 v215, 0x3e0293ee, v90
	v_cndmask_b32_e64 v106, v106, v215, s[12:13]
.LBB0_835:
	v_add_u32_e32 v86, -8, v0
	v_cmp_le_i32_e32 vcc, v86, v150
	v_add_u32_e32 v86, 8, v5
	v_cmp_gt_i32_e64 s[12:13], s3, v86
	s_and_b64 s[12:13], vcc, s[12:13]
	v_fmac_f32_e32 v216, 0x3e0293ee, v91
	v_cndmask_b32_e64 v105, v105, v216, s[12:13]
.LBB0_837:
	v_add_u32_e32 v86, -3, v0
	v_cmp_le_i32_e32 vcc, v86, v150
	v_add_u32_e32 v86, 3, v5
	v_cmp_gt_i32_e64 s[12:13], s3, v86
	s_and_b64 s[12:13], vcc, s[12:13]
	v_mov_b32_e32 v107, 0xf149f2ca
	v_mov_b32_e32 v108, 0xf149f2ca
	v_fmac_f32_e32 v217, 0x3e0293ee, v92
	v_cndmask_b32_e64 v108, v108, v217, s[12:13]
.LBB0_839:
	v_add_u32_e32 v86, -2, v0
	v_cmp_le_i32_e32 vcc, v86, v150
	v_add_u32_e32 v86, 2, v5
	v_cmp_gt_i32_e64 s[12:13], s3, v86
	s_and_b64 s[12:13], vcc, s[12:13]
	v_fmac_f32_e32 v218, 0x3e0293ee, v93
	v_cndmask_b32_e64 v107, v107, v218, s[12:13]
.LBB0_841:
	v_add_u32_e32 v86, -1, v0
	v_cmp_le_i32_e32 vcc, v86, v150
	v_add_u32_e32 v86, 1, v5
	v_cmp_gt_i32_e64 s[12:13], s3, v86
	s_and_b64 s[12:13], vcc, s[12:13]
	v_mov_b32_e32 v109, 0xf149f2ca
	v_mov_b32_e32 v110, 0xf149f2ca
	v_fmac_f32_e32 v224, 0x3e0293ee, v94
	v_cndmask_b32_e64 v110, v110, v224, s[12:13]
.LBB0_843:
	v_cmp_le_i32_e32 vcc, v0, v150
	v_cmp_gt_i32_e64 s[12:13], s3, v5
	s_and_b64 s[12:13], vcc, s[12:13]
	v_fmac_f32_e32 v225, 0x3e0293ee, v95
	v_cndmask_b32_e64 v109, v109, v225, s[12:13]
.LBB0_845:
	v_max3_f32 v0, v170, v6, v3
	v_max3_f32 v0, v0, v8, v7
	v_max3_f32 v0, v0, v10, v9
	v_max3_f32 v0, v0, v12, v11
	v_max3_f32 v0, v0, v14, v13
	v_max3_f32 v0, v0, v96, v15
	v_max3_f32 v0, v0, v98, v97
	v_max3_f32 v0, v0, v100, v99
	v_max3_f32 v0, v0, v102, v101
	v_max3_f32 v0, v0, v80, v81
	v_max3_f32 v0, v0, v82, v83
	v_max3_f32 v0, v0, v84, v85
	v_max3_f32 v0, v0, v104, v103
	v_max3_f32 v0, v0, v106, v105
	v_max3_f32 v0, v0, v108, v107
	v_max3_f32 v0, v0, v110, v109
	ds_bpermute_b32 v5, v164, v0
	s_waitcnt lgkmcnt(0)
	v_max_f32_e32 v5, v5, v5
	v_max_f32_e32 v5, v0, v5
	v_sub_f32_e32 v0, v170, v5
	v_exp_f32_e32 v0, v0
	s_nop 0
	v_cmp_neq_f32_e32 vcc, 1.0, v0
	s_cbranch_vccz .LBB0_847
	v_pk_mul_f32 v[78:79], v[78:79], v[0:1] op_sel_hi:[1,0]
	v_pk_mul_f32 v[76:77], v[76:77], v[0:1] op_sel_hi:[1,0]
	v_pk_mul_f32 v[74:75], v[74:75], v[0:1] op_sel_hi:[1,0]
	v_pk_mul_f32 v[72:73], v[72:73], v[0:1] op_sel_hi:[1,0]
	v_pk_mul_f32 v[70:71], v[70:71], v[0:1] op_sel_hi:[1,0]
	v_pk_mul_f32 v[68:69], v[68:69], v[0:1] op_sel_hi:[1,0]
	v_pk_mul_f32 v[66:67], v[66:67], v[0:1] op_sel_hi:[1,0]
	v_pk_mul_f32 v[64:65], v[64:65], v[0:1] op_sel_hi:[1,0]
	v_pk_mul_f32 v[62:63], v[62:63], v[0:1] op_sel_hi:[1,0]
	v_pk_mul_f32 v[60:61], v[60:61], v[0:1] op_sel_hi:[1,0]
	v_pk_mul_f32 v[58:59], v[58:59], v[0:1] op_sel_hi:[1,0]
	v_pk_mul_f32 v[56:57], v[56:57], v[0:1] op_sel_hi:[1,0]
	v_pk_mul_f32 v[54:55], v[54:55], v[0:1] op_sel_hi:[1,0]
	v_pk_mul_f32 v[52:53], v[52:53], v[0:1] op_sel_hi:[1,0]
	v_pk_mul_f32 v[50:51], v[50:51], v[0:1] op_sel_hi:[1,0]
	v_pk_mul_f32 v[48:49], v[48:49], v[0:1] op_sel_hi:[1,0]
	v_pk_mul_f32 v[46:47], v[46:47], v[0:1] op_sel_hi:[1,0]
	v_pk_mul_f32 v[44:45], v[44:45], v[0:1] op_sel_hi:[1,0]
	v_pk_mul_f32 v[42:43], v[42:43], v[0:1] op_sel_hi:[1,0]
	v_pk_mul_f32 v[40:41], v[40:41], v[0:1] op_sel_hi:[1,0]
	v_pk_mul_f32 v[38:39], v[38:39], v[0:1] op_sel_hi:[1,0]
	v_pk_mul_f32 v[36:37], v[36:37], v[0:1] op_sel_hi:[1,0]
	v_pk_mul_f32 v[34:35], v[34:35], v[0:1] op_sel_hi:[1,0]
	v_pk_mul_f32 v[32:33], v[32:33], v[0:1] op_sel_hi:[1,0]
	v_pk_mul_f32 v[30:31], v[30:31], v[0:1] op_sel_hi:[1,0]
	v_pk_mul_f32 v[28:29], v[28:29], v[0:1] op_sel_hi:[1,0]
	v_pk_mul_f32 v[26:27], v[26:27], v[0:1] op_sel_hi:[1,0]
	v_pk_mul_f32 v[24:25], v[24:25], v[0:1] op_sel_hi:[1,0]
	v_pk_mul_f32 v[22:23], v[22:23], v[0:1] op_sel_hi:[1,0]
	v_pk_mul_f32 v[20:21], v[20:21], v[0:1] op_sel_hi:[1,0]
	v_pk_mul_f32 v[18:19], v[18:19], v[0:1] op_sel_hi:[1,0]
	v_pk_mul_f32 v[16:17], v[16:17], v[0:1] op_sel_hi:[1,0]
